# adds GEMM mainloops: priority raise moved in front of the leading barrier, priority drop behind the closing barrier, redundant lgkmcnt(0) behind the leading barrier dropped (shorter hand-off between t
# speedup vs baseline: 1.0154x; 1.0032x over previous
; #define PG8_STAGE(bufoff, gbase, voff) do { _Pragma("unroll") for (int _i = 0; _i < 2; ++_i) \
;         __builtin_amdgcn_global_load_lds((const unsigned*)((const char*)(gbase) + (voff)[_i]), (PG8_LAS unsigned*)(lds + (bufoff) + ldsw + _i * 8192), 16, 0, 0); } while (0)
; #define PG8_LDA(dst, b, h) do { _Pragma("unroll") for (int m = 0; m < 4; ++m) _Pragma("unroll") for (int k = 0; k < 2; ++k) dst[m][k] = *(const PG8_LAS bf16x8*)(lds + PG8_SA(b, h) + aoff + m * 2048 + k * 1024); } while (0)
; #define PG8_LDB(dst, b, h) do { _Pragma("unroll") for (int n = 0; n < 2; ++n) _Pragma("unroll") for (int k = 0; k < 2; ++k) dst[n][k] = *(const PG8_LAS bf16x8*)(lds + PG8_SB(b, h) + boff + n * 2048 + k * 1024); } while (0)
; #define PG8_MMA(ai, bj, At, Bt) do { __builtin_amdgcn_s_setprio(1); _Pragma("unroll") for (int m = 0; m < 4; ++m) _Pragma("unroll") for (int n = 0; n < 2; ++n) _Pragma("unroll") for (int k = 0; k < 2; ++k) \
;         acc[ai][bj][m][n] = __builtin_amdgcn_mfma_f32_16x16x32_bf16(Bt[n][k], At[m][k], acc[ai][bj][m][n], 0, 0, 0); __builtin_amdgcn_s_setprio(0); } while (0)
; #define PG8_WAIT_V(n) asm volatile("s_waitcnt vmcnt(" #n ")" ::: "memory")
; template <class Epi, class Sched, bool ALIGN_EPI = false, bool SP2 = false>
; __device__ __forceinline__ void gemm_phase(PG8_LAS unsigned char* lds, const Gemm g, const Sched& S, const Epi& E) {
;     ...
;             PG8_LDB(B0, 0, 0); PG8_LDB(B1, 0, 1); PG8_SCHED; PG8_LDA(At, 0, 0); PG8_STAGE(PG8_SA(1, 1), a1 + hstepA, voffA);
;             PG8_WAIT_V(8); PG8_WAIT_L(0); PG8_BAR; PG8_MMA(0, 0, At, B0); PG8_MMA(0, 1, At, B1); PG8_BAR; PG8_SCHED;
;             PG8_LDA(At, 0, 1); PG8_STAGE(PG8_SB(0, 0), b2, voffB); PG8_STAGE(PG8_SB(0, 1), b2 + hstepB, voffB); PG8_STAGE(PG8_SA(0, 0), a2, voffA);
;             PG8_WAIT_V(8); PG8_WAIT_L(0); PG8_BAR; PG8_MMA(1, 0, At, B0); PG8_MMA(1, 1, At, B1); PG8_BAR; PG8_SCHED;
;             PG8_LDB(B0, 1, 0); PG8_LDB(B1, 1, 1); PG8_SCHED; PG8_LDA(At, 1, 0); PG8_STAGE(PG8_SA(0, 1), a2 + hstepA, voffA);
;             PG8_WAIT_V(8); PG8_WAIT_L(0); PG8_BAR; PG8_MMA(0, 0, At, B0); PG8_MMA(0, 1, At, B1); PG8_BAR; PG8_SCHED;
;             PG8_LDA(At, 1, 1); PG8_STAGE(PG8_SB(1, 0), b3, voffB); PG8_STAGE(PG8_SB(1, 1), b3 + hstepB, voffB); PG8_STAGE(PG8_SA(1, 0), a3, voffA);
;             PG8_WAIT_V(8); PG8_WAIT_L(0); PG8_BAR; PG8_MMA(1, 0, At, B0); PG8_MMA(1, 1, At, B1); PG8_BAR; PG8_SCHED;
.LBB0_300:
	ds_read_b128 v[156:159], v152
	ds_read_b128 v[160:163], v152 offset:1024
	ds_read_b128 v[164:167], v152 offset:2048
	ds_read_b128 v[168:171], v152 offset:3072
	ds_read_b128 v[172:175], v153
	ds_read_b128 v[176:179], v153 offset:1024
	ds_read_b128 v[180:183], v153 offset:2048
	ds_read_b128 v[186:189], v153 offset:3072
	s_add_u32 s56, s50, 0xfff80080
	s_addc_u32 s57, s51, -1
	s_cmp_eq_u32 s61, 28
	s_cselect_b32 s59, s4, s57
	s_cselect_b32 s58, s5, s56
	s_cselect_b32 s57, s12, s43
	s_cselect_b32 s56, s13, s41
	v_lshl_add_u64 v[222:223], s[50:51], 0, v[142:143]
	s_add_i32 m0, s6, 0xc000
	ds_read_b128 v[190:193], v154
	ds_read_b128 v[194:197], v154 offset:1024
	ds_read_b128 v[198:201], v154 offset:2048
	ds_read_b128 v[202:205], v154 offset:3072
	ds_read_b128 v[206:209], v154 offset:4096
	ds_read_b128 v[210:213], v154 offset:5120
	ds_read_b128 v[214:217], v154 offset:6144
	ds_read_b128 v[218:221], v154 offset:7168
	global_load_lds_dwordx4 v[222:223], off
	v_lshl_add_u64 v[222:223], s[50:51], 0, v[144:145]
	s_add_i32 m0, s6, 0xe000
	s_nop 0
	global_load_lds_dwordx4 v[222:223], off
	s_waitcnt vmcnt(8)
	s_waitcnt lgkmcnt(0)
	s_setprio 1
	s_barrier
	v_mfma_f32_16x16x32_bf16 v[124:127], v[156:159], v[190:193], v[124:127]
	v_mfma_f32_16x16x32_bf16 v[120:123], v[164:167], v[190:193], v[120:123]
	v_mfma_f32_16x16x32_bf16 v[108:111], v[156:159], v[198:201], v[108:111]
	v_mfma_f32_16x16x32_bf16 v[104:107], v[164:167], v[198:201], v[104:107]
	v_mfma_f32_16x16x32_bf16 v[92:95], v[156:159], v[206:209], v[92:95]
	v_mfma_f32_16x16x32_bf16 v[88:91], v[164:167], v[206:209], v[88:91]
	v_mfma_f32_16x16x32_bf16 v[76:79], v[156:159], v[214:217], v[76:79]
	v_mfma_f32_16x16x32_bf16 v[72:75], v[164:167], v[214:217], v[72:75]
	v_mfma_f32_16x16x32_bf16 v[124:127], v[160:163], v[194:197], v[124:127]
	v_mfma_f32_16x16x32_bf16 v[120:123], v[168:171], v[194:197], v[120:123]
	v_mfma_f32_16x16x32_bf16 v[108:111], v[160:163], v[202:205], v[108:111]
	v_mfma_f32_16x16x32_bf16 v[104:107], v[168:171], v[202:205], v[104:107]
	v_mfma_f32_16x16x32_bf16 v[92:95], v[160:163], v[210:213], v[92:95]
	v_mfma_f32_16x16x32_bf16 v[88:91], v[168:171], v[210:213], v[88:91]
	v_mfma_f32_16x16x32_bf16 v[76:79], v[160:163], v[218:221], v[76:79]
	v_mfma_f32_16x16x32_bf16 v[72:75], v[168:171], v[218:221], v[72:75]
	s_setprio 0
	s_setprio 1
	v_mfma_f32_16x16x32_bf16 v[116:119], v[172:175], v[190:193], v[116:119]
	v_mfma_f32_16x16x32_bf16 v[112:115], v[180:183], v[190:193], v[112:115]
	v_mfma_f32_16x16x32_bf16 v[100:103], v[172:175], v[198:201], v[100:103]
	v_mfma_f32_16x16x32_bf16 v[96:99], v[180:183], v[198:201], v[96:99]
	v_mfma_f32_16x16x32_bf16 v[84:87], v[172:175], v[206:209], v[84:87]
	v_mfma_f32_16x16x32_bf16 v[80:83], v[180:183], v[206:209], v[80:83]
	v_mfma_f32_16x16x32_bf16 v[68:71], v[172:175], v[214:217], v[68:71]
	v_mfma_f32_16x16x32_bf16 v[64:67], v[180:183], v[214:217], v[64:67]
	v_mfma_f32_16x16x32_bf16 v[116:119], v[176:179], v[194:197], v[116:119]
	v_mfma_f32_16x16x32_bf16 v[112:115], v[186:189], v[194:197], v[112:115]
	v_mfma_f32_16x16x32_bf16 v[100:103], v[176:179], v[202:205], v[100:103]
	v_mfma_f32_16x16x32_bf16 v[96:99], v[186:189], v[202:205], v[96:99]
	v_mfma_f32_16x16x32_bf16 v[84:87], v[176:179], v[210:213], v[84:87]
	v_mfma_f32_16x16x32_bf16 v[80:83], v[186:189], v[210:213], v[80:83]
	v_mfma_f32_16x16x32_bf16 v[68:71], v[176:179], v[218:221], v[68:71]
	v_mfma_f32_16x16x32_bf16 v[64:67], v[186:189], v[218:221], v[64:67]
	s_barrier
	s_setprio 0
	s_add_i32 s62, s53, s3
	v_lshl_add_u64 v[222:223], s[56:57], 0, v[130:131]
	s_mov_b32 m0, s62
	ds_read_b128 v[190:193], v154 offset:16384
	ds_read_b128 v[194:197], v154 offset:17408
	ds_read_b128 v[198:201], v154 offset:18432
	ds_read_b128 v[202:205], v154 offset:19456
	ds_read_b128 v[206:209], v154 offset:20480
	ds_read_b128 v[210:213], v154 offset:21504
	ds_read_b128 v[214:217], v154 offset:22528
	ds_read_b128 v[218:221], v154 offset:23552
	global_load_lds_dwordx4 v[222:223], off
	s_add_i32 m0, s62, 0x2000
	s_add_u32 s62, s56, 0x80000
	v_lshl_add_u64 v[224:225], s[56:57], 0, v[134:135]
	s_addc_u32 s63, s57, 0
	s_add_i32 s64, s55, s3
	global_load_lds_dwordx4 v[224:225], off
	v_lshl_add_u64 v[226:227], s[62:63], 0, v[130:131]
	s_mov_b32 m0, s64
	v_lshl_add_u64 v[228:229], s[58:59], 0, v[132:133]
	global_load_lds_dwordx4 v[226:227], off
	v_lshl_add_u64 v[226:227], s[62:63], 0, v[134:135]
	s_add_i32 m0, s64, 0x2000
	s_nop 0
	global_load_lds_dwordx4 v[226:227], off
	v_lshl_add_u64 v[226:227], s[58:59], 0, v[128:129]
	s_mov_b32 m0, s6
	s_nop 0
	global_load_lds_dwordx4 v[226:227], off
	s_mov_b32 m0, s7
	s_nop 0
	global_load_lds_dwordx4 v[228:229], off
	s_waitcnt vmcnt(8)
	s_waitcnt lgkmcnt(0)
	s_setprio 1
	s_barrier
; #define PG8_STAGE(bufoff, gbase, voff) do { _Pragma("unroll") for (int _i = 0; _i < 2; ++_i) \
;         __builtin_amdgcn_global_load_lds((const unsigned*)((const char*)(gbase) + (voff)[_i]), (PG8_LAS unsigned*)(lds + (bufoff) + ldsw + _i * 8192), 16, 0, 0); } while (0)
; #define PG8_LDA(dst, b, h) do { _Pragma("unroll") for (int m = 0; m < 4; ++m) _Pragma("unroll") for (int k = 0; k < 2; ++k) dst[m][k] = *(const PG8_LAS bf16x8*)(lds + PG8_SA(b, h) + aoff + m * 2048 + k * 1024); } while (0)
; #define PG8_LDB(dst, b, h) do { _Pragma("unroll") for (int n = 0; n < 2; ++n) _Pragma("unroll") for (int k = 0; k < 2; ++k) dst[n][k] = *(const PG8_LAS bf16x8*)(lds + PG8_SB(b, h) + boff + n * 2048 + k * 1024); } while (0)
; #define PG8_MMA(ai, bj, At, Bt) do { __builtin_amdgcn_s_setprio(1); _Pragma("unroll") for (int m = 0; m < 4; ++m) _Pragma("unroll") for (int n = 0; n < 2; ++n) _Pragma("unroll") for (int k = 0; k < 2; ++k) \
;         acc[ai][bj][m][n] = __builtin_amdgcn_mfma_f32_16x16x32_bf16(Bt[n][k], At[m][k], acc[ai][bj][m][n], 0, 0, 0); __builtin_amdgcn_s_setprio(0); } while (0)
; #define PG8_WAIT_V(n) asm volatile("s_waitcnt vmcnt(" #n ")" ::: "memory")
; template <class Epi, class Sched, bool ALIGN_EPI = false, bool SP2 = false>
; __device__ __forceinline__ void gemm_phase(PG8_LAS unsigned char* lds, const Gemm g, const Sched& S, const Epi& E) {
;     ...
;             PG8_LDB(B0, 0, 0); PG8_LDB(B1, 0, 1); PG8_SCHED; PG8_LDA(At, 0, 0); PG8_STAGE(PG8_SA(1, 1), a1 + hstepA, voffA);
;             PG8_WAIT_V(8); PG8_WAIT_L(0); PG8_BAR; PG8_MMA(0, 0, At, B0); PG8_MMA(0, 1, At, B1); PG8_BAR; PG8_SCHED;
;             PG8_LDA(At, 0, 1); PG8_STAGE(PG8_SB(0, 0), b2, voffB); PG8_STAGE(PG8_SB(0, 1), b2 + hstepB, voffB); PG8_STAGE(PG8_SA(0, 0), a2, voffA);
;             PG8_WAIT_V(8); PG8_WAIT_L(0); PG8_BAR; PG8_MMA(1, 0, At, B0); PG8_MMA(1, 1, At, B1); PG8_BAR; PG8_SCHED;
;             PG8_LDB(B0, 1, 0); PG8_LDB(B1, 1, 1); PG8_SCHED; PG8_LDA(At, 1, 0); PG8_STAGE(PG8_SA(0, 1), a2 + hstepA, voffA);
;             PG8_WAIT_V(8); PG8_WAIT_L(0); PG8_BAR; PG8_MMA(0, 0, At, B0); PG8_MMA(0, 1, At, B1); PG8_BAR; PG8_SCHED;
;             PG8_LDA(At, 1, 1); PG8_STAGE(PG8_SB(1, 0), b3, voffB); PG8_STAGE(PG8_SB(1, 1), b3 + hstepB, voffB); PG8_STAGE(PG8_SA(1, 0), a3, voffA);
;             PG8_WAIT_V(8); PG8_WAIT_L(0); PG8_BAR; PG8_MMA(1, 0, At, B0); PG8_MMA(1, 1, At, B1); PG8_BAR; PG8_SCHED;
	v_mfma_f32_16x16x32_bf16 v[60:63], v[156:159], v[190:193], v[60:63]
	v_mfma_f32_16x16x32_bf16 v[56:59], v[164:167], v[190:193], v[56:59]
	v_mfma_f32_16x16x32_bf16 v[44:47], v[156:159], v[198:201], v[44:47]
	v_mfma_f32_16x16x32_bf16 v[40:43], v[164:167], v[198:201], v[40:43]
	v_mfma_f32_16x16x32_bf16 v[28:31], v[156:159], v[206:209], v[28:31]
	v_mfma_f32_16x16x32_bf16 v[24:27], v[164:167], v[206:209], v[24:27]
	v_mfma_f32_16x16x32_bf16 v[12:15], v[156:159], v[214:217], v[12:15]
	v_mfma_f32_16x16x32_bf16 v[8:11], v[164:167], v[214:217], v[8:11]
	v_mfma_f32_16x16x32_bf16 v[60:63], v[160:163], v[194:197], v[60:63]
	v_mfma_f32_16x16x32_bf16 v[56:59], v[168:171], v[194:197], v[56:59]
	v_mfma_f32_16x16x32_bf16 v[44:47], v[160:163], v[202:205], v[44:47]
	v_mfma_f32_16x16x32_bf16 v[40:43], v[168:171], v[202:205], v[40:43]
	v_mfma_f32_16x16x32_bf16 v[28:31], v[160:163], v[210:213], v[28:31]
	v_mfma_f32_16x16x32_bf16 v[24:27], v[168:171], v[210:213], v[24:27]
	v_mfma_f32_16x16x32_bf16 v[12:15], v[160:163], v[218:221], v[12:15]
	v_mfma_f32_16x16x32_bf16 v[8:11], v[168:171], v[218:221], v[8:11]
	s_setprio 0
	s_setprio 1
	v_mfma_f32_16x16x32_bf16 v[52:55], v[172:175], v[190:193], v[52:55]
	v_mfma_f32_16x16x32_bf16 v[48:51], v[180:183], v[190:193], v[48:51]
	v_mfma_f32_16x16x32_bf16 v[36:39], v[172:175], v[198:201], v[36:39]
	v_mfma_f32_16x16x32_bf16 v[32:35], v[180:183], v[198:201], v[32:35]
	v_mfma_f32_16x16x32_bf16 v[20:23], v[172:175], v[206:209], v[20:23]
	v_mfma_f32_16x16x32_bf16 v[16:19], v[180:183], v[206:209], v[16:19]
	v_mfma_f32_16x16x32_bf16 v[4:7], v[172:175], v[214:217], v[4:7]
	v_mfma_f32_16x16x32_bf16 v[0:3], v[180:183], v[214:217], v[0:3]
	v_mfma_f32_16x16x32_bf16 v[52:55], v[176:179], v[194:197], v[52:55]
	v_mfma_f32_16x16x32_bf16 v[48:51], v[186:189], v[194:197], v[48:51]
	v_mfma_f32_16x16x32_bf16 v[36:39], v[176:179], v[202:205], v[36:39]
	v_mfma_f32_16x16x32_bf16 v[32:35], v[186:189], v[202:205], v[32:35]
	v_mfma_f32_16x16x32_bf16 v[20:23], v[176:179], v[210:213], v[20:23]
	v_mfma_f32_16x16x32_bf16 v[16:19], v[186:189], v[210:213], v[16:19]
	v_mfma_f32_16x16x32_bf16 v[4:7], v[176:179], v[218:221], v[4:7]
	v_mfma_f32_16x16x32_bf16 v[0:3], v[186:189], v[218:221], v[0:3]
	s_barrier
	s_setprio 0
	s_add_i32 s62, 0, 0x18000
	v_add_u32_e32 v155, s62, v150
	s_add_i32 s63, 0, 0x1c000
	ds_read_b128 v[156:159], v155
	ds_read_b128 v[160:163], v155 offset:1024
	ds_read_b128 v[164:167], v155 offset:2048
	ds_read_b128 v[168:171], v155 offset:3072
	v_add_u32_e32 v155, s63, v150
	ds_read_b128 v[172:175], v155
	ds_read_b128 v[176:179], v155 offset:1024
	ds_read_b128 v[180:183], v155 offset:2048
	ds_read_b128 v[186:189], v155 offset:3072
	s_add_u32 s58, s58, 0x80000
	s_addc_u32 s59, s59, 0
	s_mov_b32 m0, s8
	v_lshl_add_u64 v[230:231], s[58:59], 0, v[128:129]
	ds_read_b128 v[190:193], v154 offset:32768
	ds_read_b128 v[194:197], v154 offset:33792
	ds_read_b128 v[198:201], v154 offset:34816
	ds_read_b128 v[202:205], v154 offset:35840
	ds_read_b128 v[206:209], v154 offset:36864
	ds_read_b128 v[210:213], v154 offset:37888
	ds_read_b128 v[214:217], v154 offset:38912
	ds_read_b128 v[218:221], v154 offset:39936
	global_load_lds_dwordx4 v[230:231], off
	v_lshl_add_u64 v[230:231], s[58:59], 0, v[132:133]
	s_mov_b32 m0, s9
	s_nop 0
	global_load_lds_dwordx4 v[230:231], off
	s_waitcnt vmcnt(8)
	s_waitcnt lgkmcnt(0)
	s_setprio 1
	s_barrier
	v_mfma_f32_16x16x32_bf16 v[124:127], v[156:159], v[190:193], v[124:127]
	v_mfma_f32_16x16x32_bf16 v[120:123], v[164:167], v[190:193], v[120:123]
	v_mfma_f32_16x16x32_bf16 v[108:111], v[156:159], v[198:201], v[108:111]
	v_mfma_f32_16x16x32_bf16 v[104:107], v[164:167], v[198:201], v[104:107]
	v_mfma_f32_16x16x32_bf16 v[92:95], v[156:159], v[206:209], v[92:95]
	v_mfma_f32_16x16x32_bf16 v[88:91], v[164:167], v[206:209], v[88:91]
	v_mfma_f32_16x16x32_bf16 v[76:79], v[156:159], v[214:217], v[76:79]
	v_mfma_f32_16x16x32_bf16 v[72:75], v[164:167], v[214:217], v[72:75]
	v_mfma_f32_16x16x32_bf16 v[124:127], v[160:163], v[194:197], v[124:127]
	v_mfma_f32_16x16x32_bf16 v[120:123], v[168:171], v[194:197], v[120:123]
	v_mfma_f32_16x16x32_bf16 v[108:111], v[160:163], v[202:205], v[108:111]
	v_mfma_f32_16x16x32_bf16 v[104:107], v[168:171], v[202:205], v[104:107]
	v_mfma_f32_16x16x32_bf16 v[92:95], v[160:163], v[210:213], v[92:95]
	v_mfma_f32_16x16x32_bf16 v[88:91], v[168:171], v[210:213], v[88:91]
	v_mfma_f32_16x16x32_bf16 v[76:79], v[160:163], v[218:221], v[76:79]
	v_mfma_f32_16x16x32_bf16 v[72:75], v[168:171], v[218:221], v[72:75]
	s_setprio 0
	s_setprio 1
	v_mfma_f32_16x16x32_bf16 v[116:119], v[172:175], v[190:193], v[116:119]
	v_mfma_f32_16x16x32_bf16 v[112:115], v[180:183], v[190:193], v[112:115]
	v_mfma_f32_16x16x32_bf16 v[100:103], v[172:175], v[198:201], v[100:103]
	v_mfma_f32_16x16x32_bf16 v[96:99], v[180:183], v[198:201], v[96:99]
	v_mfma_f32_16x16x32_bf16 v[84:87], v[172:175], v[206:209], v[84:87]
	v_mfma_f32_16x16x32_bf16 v[80:83], v[180:183], v[206:209], v[80:83]
	v_mfma_f32_16x16x32_bf16 v[68:71], v[172:175], v[214:217], v[68:71]
	v_mfma_f32_16x16x32_bf16 v[64:67], v[180:183], v[214:217], v[64:67]
	v_mfma_f32_16x16x32_bf16 v[116:119], v[176:179], v[194:197], v[116:119]
	v_mfma_f32_16x16x32_bf16 v[112:115], v[186:189], v[194:197], v[112:115]
	v_mfma_f32_16x16x32_bf16 v[100:103], v[176:179], v[202:205], v[100:103]
	v_mfma_f32_16x16x32_bf16 v[96:99], v[186:189], v[202:205], v[96:99]
	v_mfma_f32_16x16x32_bf16 v[84:87], v[176:179], v[210:213], v[84:87]
	v_mfma_f32_16x16x32_bf16 v[80:83], v[186:189], v[210:213], v[80:83]
	v_mfma_f32_16x16x32_bf16 v[68:71], v[176:179], v[218:221], v[68:71]
	v_mfma_f32_16x16x32_bf16 v[64:67], v[186:189], v[218:221], v[64:67]
	s_barrier
; #define PG8_STAGE(bufoff, gbase, voff) do { _Pragma("unroll") for (int _i = 0; _i < 2; ++_i) \
;         __builtin_amdgcn_global_load_lds((const unsigned*)((const char*)(gbase) + (voff)[_i]), (PG8_LAS unsigned*)(lds + (bufoff) + ldsw + _i * 8192), 16, 0, 0); } while (0)
; #define PG8_LDA(dst, b, h) do { _Pragma("unroll") for (int m = 0; m < 4; ++m) _Pragma("unroll") for (int k = 0; k < 2; ++k) dst[m][k] = *(const PG8_LAS bf16x8*)(lds + PG8_SA(b, h) + aoff + m * 2048 + k * 1024); } while (0)
; #define PG8_LDB(dst, b, h) do { _Pragma("unroll") for (int n = 0; n < 2; ++n) _Pragma("unroll") for (int k = 0; k < 2; ++k) dst[n][k] = *(const PG8_LAS bf16x8*)(lds + PG8_SB(b, h) + boff + n * 2048 + k * 1024); } while (0)
; template <class Epi, class Sched, bool ALIGN_EPI = false, bool SP2 = false>
; __device__ __forceinline__ void gemm_phase(PG8_LAS unsigned char* lds, const Gemm g, const Sched& S, const Epi& E) {
;     ...
;         for (int t = 0; t < nt; t += 2) {
;             const bool last = (t == nt - 2);
;             const char* a1 = cA + (size_t)(t + 1) * kstA;
;             const char* a2 = last ? nA : cA + (size_t)(t + 2) * kstA; const char* b2 = last ? nB : cB + (size_t)(t + 2) * kstep;
;             const char* a3 = a2 + kstA; const char* b3 = b2 + kstep;
;             if (last && has_next) S.a_ready(nxt);
;             if constexpr (SP2) {
;             PG8_LDB(B0, 0, 0); PG8_LDB(B1, 0, 1); PG8_SCHED; PG8_LDA(At, 0, 0); PG8_STAGE(PG8_SA(1, 1), a1 + hstepA, voffA);
;             PG8_WAIT_V(8); PG8_WAIT_L(0); PG8_BAR; PG8_MMA(0, 0, At, B0); PG8_MMA(0, 1, At, B1); PG8_BAR; PG8_SCHED;
;             PG8_LDA(At, 0, 1); PG8_STAGE(PG8_SB(0, 0), b2, voffB); PG8_STAGE(PG8_SB(0, 1), b2 + hstepB, voffB); PG8_STAGE(PG8_SA(0, 0), a2, voffA);
;             PG8_WAIT_V(8); PG8_WAIT_L(0); PG8_BAR; PG8_MMA(1, 0, At, B0); PG8_MMA(1, 1, At, B1); PG8_BAR; PG8_SCHED;
;             PG8_LDB(B0, 1, 0); PG8_LDB(B1, 1, 1); PG8_SCHED; PG8_LDA(At, 1, 0); PG8_STAGE(PG8_SA(0, 1), a2 + hstepA, voffA);
;             PG8_WAIT_V(8); PG8_WAIT_L(0); PG8_BAR; PG8_MMA(0, 0, At, B0); PG8_MMA(0, 1, At, B1); PG8_BAR; PG8_SCHED;
;             PG8_LDA(At, 1, 1); PG8_STAGE(PG8_SB(1, 0), b3, voffB); PG8_STAGE(PG8_SB(1, 1), b3 + hstepB, voffB); PG8_STAGE(PG8_SA(1, 0), a3, voffA);
;             PG8_WAIT_V(8); PG8_WAIT_L(0); PG8_BAR; PG8_MMA(1, 0, At, B0); PG8_MMA(1, 1, At, B1); PG8_BAR; PG8_SCHED;
	s_setprio 0
	s_add_i32 s58, s62, s3
	v_lshl_add_u64 v[222:223], v[222:223], 0, s[36:37]
	s_mov_b32 m0, s58
	ds_read_b128 v[190:193], v154 offset:49152
	ds_read_b128 v[194:197], v154 offset:50176
	ds_read_b128 v[198:201], v154 offset:51200
	ds_read_b128 v[202:205], v154 offset:52224
	ds_read_b128 v[206:209], v154 offset:53248
	ds_read_b128 v[210:213], v154 offset:54272
	ds_read_b128 v[214:217], v154 offset:55296
	ds_read_b128 v[218:221], v154 offset:56320
	global_load_lds_dwordx4 v[222:223], off
	s_add_i32 m0, s58, 0x2000
	s_add_u32 s56, s56, 0x80080
	v_lshl_add_u64 v[222:223], v[224:225], 0, s[36:37]
	s_addc_u32 s57, s57, 0
	s_add_i32 s58, s63, s3
	global_load_lds_dwordx4 v[222:223], off
	v_lshl_add_u64 v[222:223], s[56:57], 0, v[130:131]
	s_mov_b32 m0, s58
	s_nop 0
	global_load_lds_dwordx4 v[222:223], off
	v_lshl_add_u64 v[222:223], s[56:57], 0, v[134:135]
	s_add_i32 m0, s58, 0x2000
	s_nop 0
	global_load_lds_dwordx4 v[222:223], off
	v_lshl_add_u64 v[222:223], v[226:227], 0, s[36:37]
	s_mov_b32 m0, s44
	s_nop 0
	global_load_lds_dwordx4 v[222:223], off
	v_lshl_add_u64 v[222:223], v[228:229], 0, s[36:37]
	s_mov_b32 m0, s45
	s_nop 0
	global_load_lds_dwordx4 v[222:223], off
	s_waitcnt vmcnt(8)
	s_waitcnt lgkmcnt(0)
	s_setprio 1
	s_barrier
	v_mfma_f32_16x16x32_bf16 v[60:63], v[156:159], v[190:193], v[60:63]
	v_mfma_f32_16x16x32_bf16 v[56:59], v[164:167], v[190:193], v[56:59]
	v_mfma_f32_16x16x32_bf16 v[44:47], v[156:159], v[198:201], v[44:47]
	v_mfma_f32_16x16x32_bf16 v[40:43], v[164:167], v[198:201], v[40:43]
	v_mfma_f32_16x16x32_bf16 v[28:31], v[156:159], v[206:209], v[28:31]
	v_mfma_f32_16x16x32_bf16 v[24:27], v[164:167], v[206:209], v[24:27]
	v_mfma_f32_16x16x32_bf16 v[12:15], v[156:159], v[214:217], v[12:15]
	v_mfma_f32_16x16x32_bf16 v[8:11], v[164:167], v[214:217], v[8:11]
	v_mfma_f32_16x16x32_bf16 v[60:63], v[160:163], v[194:197], v[60:63]
	v_mfma_f32_16x16x32_bf16 v[56:59], v[168:171], v[194:197], v[56:59]
	v_mfma_f32_16x16x32_bf16 v[44:47], v[160:163], v[202:205], v[44:47]
	v_mfma_f32_16x16x32_bf16 v[40:43], v[168:171], v[202:205], v[40:43]
	v_mfma_f32_16x16x32_bf16 v[28:31], v[160:163], v[210:213], v[28:31]
	v_mfma_f32_16x16x32_bf16 v[24:27], v[168:171], v[210:213], v[24:27]
	v_mfma_f32_16x16x32_bf16 v[12:15], v[160:163], v[218:221], v[12:15]
	v_mfma_f32_16x16x32_bf16 v[8:11], v[168:171], v[218:221], v[8:11]
	s_setprio 0
	s_setprio 1
	v_mfma_f32_16x16x32_bf16 v[52:55], v[172:175], v[190:193], v[52:55]
	v_mfma_f32_16x16x32_bf16 v[48:51], v[180:183], v[190:193], v[48:51]
	v_mfma_f32_16x16x32_bf16 v[36:39], v[172:175], v[198:201], v[36:39]
	v_mfma_f32_16x16x32_bf16 v[32:35], v[180:183], v[198:201], v[32:35]
	v_mfma_f32_16x16x32_bf16 v[20:23], v[172:175], v[206:209], v[20:23]
	v_mfma_f32_16x16x32_bf16 v[16:19], v[180:183], v[206:209], v[16:19]
	v_mfma_f32_16x16x32_bf16 v[4:7], v[172:175], v[214:217], v[4:7]
	v_mfma_f32_16x16x32_bf16 v[0:3], v[180:183], v[214:217], v[0:3]
	v_mfma_f32_16x16x32_bf16 v[52:55], v[176:179], v[194:197], v[52:55]
	v_mfma_f32_16x16x32_bf16 v[48:51], v[186:189], v[194:197], v[48:51]
	v_mfma_f32_16x16x32_bf16 v[36:39], v[176:179], v[202:205], v[36:39]
	v_mfma_f32_16x16x32_bf16 v[32:35], v[186:189], v[202:205], v[32:35]
	v_mfma_f32_16x16x32_bf16 v[20:23], v[176:179], v[210:213], v[20:23]
	v_mfma_f32_16x16x32_bf16 v[16:19], v[186:189], v[210:213], v[16:19]
	v_mfma_f32_16x16x32_bf16 v[4:7], v[176:179], v[218:221], v[4:7]
	v_mfma_f32_16x16x32_bf16 v[0:3], v[186:189], v[218:221], v[0:3]
	s_barrier
	s_setprio 0
	s_add_i32 s61, s61, 2
	s_add_u32 s50, s50, 0x100
	s_addc_u32 s51, s51, 0
	s_add_u32 s41, s41, 0x100
	s_addc_u32 s43, s43, 0
	s_cmp_gt_u32 s61, 29
	s_cbranch_scc0 .LBB0_300
	s_and_b64 vcc, exec, s[38:39]
	s_cbranch_vccz .LBB0_303
	s_barrier

; #define PG8_STAGE(bufoff, gbase, voff) do { _Pragma("unroll") for (int _i = 0; _i < 2; ++_i) \
;         __builtin_amdgcn_global_load_lds((const unsigned*)((const char*)(gbase) + (voff)[_i]), (PG8_LAS unsigned*)(lds + (bufoff) + ldsw + _i * 8192), 16, 0, 0); } while (0)
; #define PG8_WAIT_V(n) asm volatile("s_waitcnt vmcnt(" #n ")" ::: "memory")
; #define PG8_WAIT_L(n) asm volatile("s_waitcnt lgkmcnt(" #n ")" ::: "memory")
; template <class Epi, class Sched, bool ALIGN_EPI = false, bool SP2 = false>
; __device__ __forceinline__ void gemm_phase(PG8_LAS unsigned char* lds, const Gemm g, const Sched& S, const Epi& E) {
;     ...
;         const char* nA = has_next ? (const char*)g.A + (size_t)nxt.pm * tstepA + (size_t)nxt.z * g.azs + (size_t)(nxt.k0 >> 6) * kstA : cA; const char* nB = has_next ? (const char*)g.Bt + (size_t)nxt.pn * tstepB + (size_t)nxt.z * g.bzs + (size_t)nxt.k0 * 2 : cB;
;         const int nt = cur.nt;
;         for (int t = 0; t < nt; t += 2) {
;             const bool last = (t == nt - 2);
;             const char* a1 = cA + (size_t)(t + 1) * kstA;
;             const char* a2 = last ? nA : cA + (size_t)(t + 2) * kstA; const char* b2 = last ? nB : cB + (size_t)(t + 2) * kstep;
;             const char* a3 = a2 + kstA; const char* b3 = b2 + kstep;
;             if (last && has_next) S.a_ready(nxt);
;             if constexpr (SP2) {
;             PG8_LDB(B0, 0, 0); PG8_LDB(B1, 0, 1); PG8_SCHED; PG8_LDA(At, 0, 0); PG8_STAGE(PG8_SA(1, 1), a1 + hstepA, voffA);
;             PG8_WAIT_V(8); PG8_WAIT_L(0); PG8_BAR; PG8_MMA(0, 0, At, B0); PG8_MMA(0, 1, At, B1); PG8_BAR; PG8_SCHED;
;             PG8_LDA(At, 0, 1); PG8_STAGE(PG8_SB(0, 0), b2, voffB); PG8_STAGE(PG8_SB(0, 1), b2 + hstepB, voffB); PG8_STAGE(PG8_SA(0, 0), a2, voffA);
;             PG8_WAIT_V(8); PG8_WAIT_L(0); PG8_BAR; PG8_MMA(1, 0, At, B0); PG8_MMA(1, 1, At, B1); PG8_BAR; PG8_SCHED;
;             PG8_LDB(B0, 1, 0); PG8_LDB(B1, 1, 1); PG8_SCHED; PG8_LDA(At, 1, 0); PG8_STAGE(PG8_SA(0, 1), a2 + hstepA, voffA);
;             PG8_WAIT_V(8); PG8_WAIT_L(0); PG8_BAR; PG8_MMA(0, 0, At, B0); PG8_MMA(0, 1, At, B1); PG8_BAR; PG8_SCHED;
;             PG8_LDA(At, 1, 1); PG8_STAGE(PG8_SB(1, 0), b3, voffB); PG8_STAGE(PG8_SB(1, 1), b3 + hstepB, voffB); PG8_STAGE(PG8_SA(1, 0), a3, voffA);
;             PG8_WAIT_V(8); PG8_WAIT_L(0); PG8_BAR; PG8_MMA(1, 0, At, B0); PG8_MMA(1, 1, At, B1); PG8_BAR; PG8_SCHED;
.LBB0_397:
	s_or_b32 s42, s74, 1
	s_add_i32 s74, s74, 2
	s_mov_b32 s75, s43
	s_lshl_b64 s[4:5], s[42:43], 15
	s_lshl_b64 s[12:13], s[74:75], 15
	s_add_u32 s42, s38, s12
	v_add_u32_e32 v170, s10, v177
	v_add_u32_e32 v174, s11, v177
	s_addc_u32 s46, s39, s13
	ds_read_b128 v[158:161], v170
	ds_read_b128 v[162:165], v170 offset:1024
	ds_read_b128 v[166:169], v170 offset:2048
	ds_read_b128 v[170:173], v170 offset:3072
	ds_read_b128 v[180:183], v174
	ds_read_b128 v[186:189], v174 offset:1024
	ds_read_b128 v[190:193], v174 offset:2048
	ds_read_b128 v[194:197], v174 offset:3072
	s_and_b64 s[12:13], s[50:51], exec
	s_cselect_b32 s59, s46, s61
	s_cselect_b32 s58, s42, s60
	s_lshl_b64 s[12:13], s[74:75], 7
	s_add_u32 s42, s40, s12
	s_addc_u32 s46, s41, s13
	s_and_b64 s[12:13], s[50:51], exec
	s_cselect_b32 s53, s46, s63
	s_cselect_b32 s52, s42, s62
	s_add_u32 s50, s58, 0x8000
	s_addc_u32 s51, s59, 0
	s_add_u32 s4, s35, s4
	s_addc_u32 s5, s65, s5
	v_lshl_add_u64 v[174:175], s[4:5], 0, v[128:129]
	s_add_i32 m0, s66, 0xc000
	ds_read_b128 v[198:201], v179
	ds_read_b128 v[202:205], v179 offset:1024
	ds_read_b128 v[206:209], v179 offset:2048
	ds_read_b128 v[210:213], v179 offset:3072
	ds_read_b128 v[214:217], v179 offset:4096
	ds_read_b128 v[218:221], v179 offset:5120
	ds_read_b128 v[222:225], v179 offset:6144
	ds_read_b128 v[226:229], v179 offset:7168
	global_load_lds_dwordx4 v[174:175], off
	v_lshl_add_u64 v[174:175], s[4:5], 0, v[132:133]
	s_add_i32 m0, s66, 0xe000
	s_nop 0
	global_load_lds_dwordx4 v[174:175], off
	s_waitcnt vmcnt(8)
	s_waitcnt lgkmcnt(0)
	s_setprio 1
	s_barrier
	v_mfma_f32_16x16x32_bf16 v[124:127], v[158:161], v[198:201], v[124:127]
	v_mfma_f32_16x16x32_bf16 v[120:123], v[166:169], v[198:201], v[120:123]
	v_mfma_f32_16x16x32_bf16 v[116:119], v[158:161], v[206:209], v[116:119]
	v_mfma_f32_16x16x32_bf16 v[112:115], v[166:169], v[206:209], v[112:115]
	v_mfma_f32_16x16x32_bf16 v[108:111], v[158:161], v[214:217], v[108:111]
	v_mfma_f32_16x16x32_bf16 v[104:107], v[166:169], v[214:217], v[104:107]
	v_mfma_f32_16x16x32_bf16 v[100:103], v[158:161], v[222:225], v[100:103]
	v_mfma_f32_16x16x32_bf16 v[96:99], v[166:169], v[222:225], v[96:99]
	v_mfma_f32_16x16x32_bf16 v[124:127], v[162:165], v[202:205], v[124:127]
	v_mfma_f32_16x16x32_bf16 v[120:123], v[170:173], v[202:205], v[120:123]
	v_mfma_f32_16x16x32_bf16 v[116:119], v[162:165], v[210:213], v[116:119]
	v_mfma_f32_16x16x32_bf16 v[112:115], v[170:173], v[210:213], v[112:115]
	v_mfma_f32_16x16x32_bf16 v[108:111], v[162:165], v[218:221], v[108:111]
	v_mfma_f32_16x16x32_bf16 v[104:107], v[170:173], v[218:221], v[104:107]
	v_mfma_f32_16x16x32_bf16 v[100:103], v[162:165], v[226:229], v[100:103]
	v_mfma_f32_16x16x32_bf16 v[96:99], v[170:173], v[226:229], v[96:99]
	s_setprio 0
	s_setprio 1
	v_mfma_f32_16x16x32_bf16 v[92:95], v[180:183], v[198:201], v[92:95]
	v_mfma_f32_16x16x32_bf16 v[88:91], v[190:193], v[198:201], v[88:91]
	v_mfma_f32_16x16x32_bf16 v[84:87], v[180:183], v[206:209], v[84:87]
	v_mfma_f32_16x16x32_bf16 v[80:83], v[190:193], v[206:209], v[80:83]
	v_mfma_f32_16x16x32_bf16 v[76:79], v[180:183], v[214:217], v[76:79]
	v_mfma_f32_16x16x32_bf16 v[72:75], v[190:193], v[214:217], v[72:75]
	v_mfma_f32_16x16x32_bf16 v[68:71], v[180:183], v[222:225], v[68:71]
	v_mfma_f32_16x16x32_bf16 v[64:67], v[190:193], v[222:225], v[64:67]
	v_mfma_f32_16x16x32_bf16 v[92:95], v[186:189], v[202:205], v[92:95]
	v_mfma_f32_16x16x32_bf16 v[88:91], v[194:197], v[202:205], v[88:91]
	v_mfma_f32_16x16x32_bf16 v[84:87], v[186:189], v[210:213], v[84:87]
	v_mfma_f32_16x16x32_bf16 v[80:83], v[194:197], v[210:213], v[80:83]
	v_mfma_f32_16x16x32_bf16 v[76:79], v[186:189], v[218:221], v[76:79]
	v_mfma_f32_16x16x32_bf16 v[72:75], v[194:197], v[218:221], v[72:75]
	v_mfma_f32_16x16x32_bf16 v[68:71], v[186:189], v[226:229], v[68:71]
	v_mfma_f32_16x16x32_bf16 v[64:67], v[194:197], v[226:229], v[64:67]
	s_barrier
	s_setprio 0
	s_add_i32 s4, s10, s9
	v_lshl_add_u64 v[174:175], s[52:53], 0, v[130:131]
	s_mov_b32 m0, s4
	ds_read_b128 v[198:201], v179 offset:16384
	ds_read_b128 v[202:205], v179 offset:17408
	ds_read_b128 v[206:209], v179 offset:18432
	ds_read_b128 v[210:213], v179 offset:19456
	ds_read_b128 v[214:217], v179 offset:20480
	ds_read_b128 v[218:221], v179 offset:21504
	ds_read_b128 v[222:225], v179 offset:22528
	ds_read_b128 v[226:229], v179 offset:23552
	global_load_lds_dwordx4 v[174:175], off
	s_add_i32 m0, s4, 0x2000
	s_add_u32 s4, s52, 0x160000
	v_lshl_add_u64 v[230:231], s[52:53], 0, v[134:135]
	s_addc_u32 s5, s53, 0
	s_add_i32 s12, s11, s9
	global_load_lds_dwordx4 v[230:231], off
	v_lshl_add_u64 v[232:233], s[4:5], 0, v[130:131]
	s_mov_b32 m0, s12
	s_nop 0
	global_load_lds_dwordx4 v[232:233], off
	v_lshl_add_u64 v[232:233], s[4:5], 0, v[134:135]
	s_add_i32 m0, s12, 0x2000
	s_nop 0
	global_load_lds_dwordx4 v[232:233], off
	v_lshl_add_u64 v[232:233], s[58:59], 0, v[128:129]
	s_mov_b32 m0, s66
	s_nop 0
	global_load_lds_dwordx4 v[232:233], off
	v_lshl_add_u64 v[232:233], s[58:59], 0, v[132:133]
	s_mov_b32 m0, s67
	s_nop 0
	global_load_lds_dwordx4 v[232:233], off
	s_waitcnt vmcnt(8)
	s_waitcnt lgkmcnt(0)
	s_setprio 1
	s_barrier
; #define PG8_STAGE(bufoff, gbase, voff) do { _Pragma("unroll") for (int _i = 0; _i < 2; ++_i) \
;         __builtin_amdgcn_global_load_lds((const unsigned*)((const char*)(gbase) + (voff)[_i]), (PG8_LAS unsigned*)(lds + (bufoff) + ldsw + _i * 8192), 16, 0, 0); } while (0)
; #define PG8_LDA(dst, b, h) do { _Pragma("unroll") for (int m = 0; m < 4; ++m) _Pragma("unroll") for (int k = 0; k < 2; ++k) dst[m][k] = *(const PG8_LAS bf16x8*)(lds + PG8_SA(b, h) + aoff + m * 2048 + k * 1024); } while (0)
; #define PG8_LDB(dst, b, h) do { _Pragma("unroll") for (int n = 0; n < 2; ++n) _Pragma("unroll") for (int k = 0; k < 2; ++k) dst[n][k] = *(const PG8_LAS bf16x8*)(lds + PG8_SB(b, h) + boff + n * 2048 + k * 1024); } while (0)
; #define PG8_MMA(ai, bj, At, Bt) do { __builtin_amdgcn_s_setprio(1); _Pragma("unroll") for (int m = 0; m < 4; ++m) _Pragma("unroll") for (int n = 0; n < 2; ++n) _Pragma("unroll") for (int k = 0; k < 2; ++k) \
;         acc[ai][bj][m][n] = __builtin_amdgcn_mfma_f32_16x16x32_bf16(Bt[n][k], At[m][k], acc[ai][bj][m][n], 0, 0, 0); __builtin_amdgcn_s_setprio(0); } while (0)
; #define PG8_WAIT_V(n) asm volatile("s_waitcnt vmcnt(" #n ")" ::: "memory")
; template <class Epi, class Sched, bool ALIGN_EPI = false, bool SP2 = false>
; __device__ __forceinline__ void gemm_phase(PG8_LAS unsigned char* lds, const Gemm g, const Sched& S, const Epi& E) {
;     ...
;             PG8_LDB(B0, 0, 0); PG8_LDB(B1, 0, 1); PG8_SCHED; PG8_LDA(At, 0, 0); PG8_STAGE(PG8_SA(1, 1), a1 + hstepA, voffA);
;             PG8_WAIT_V(8); PG8_WAIT_L(0); PG8_BAR; PG8_MMA(0, 0, At, B0); PG8_MMA(0, 1, At, B1); PG8_BAR; PG8_SCHED;
;             PG8_LDA(At, 0, 1); PG8_STAGE(PG8_SB(0, 0), b2, voffB); PG8_STAGE(PG8_SB(0, 1), b2 + hstepB, voffB); PG8_STAGE(PG8_SA(0, 0), a2, voffA);
;             PG8_WAIT_V(8); PG8_WAIT_L(0); PG8_BAR; PG8_MMA(1, 0, At, B0); PG8_MMA(1, 1, At, B1); PG8_BAR; PG8_SCHED;
;             PG8_LDB(B0, 1, 0); PG8_LDB(B1, 1, 1); PG8_SCHED; PG8_LDA(At, 1, 0); PG8_STAGE(PG8_SA(0, 1), a2 + hstepA, voffA);
;             PG8_WAIT_V(8); PG8_WAIT_L(0); PG8_BAR; PG8_MMA(0, 0, At, B0); PG8_MMA(0, 1, At, B1); PG8_BAR; PG8_SCHED;
;             PG8_LDA(At, 1, 1); PG8_STAGE(PG8_SB(1, 0), b3, voffB); PG8_STAGE(PG8_SB(1, 1), b3 + hstepB, voffB); PG8_STAGE(PG8_SA(1, 0), a3, voffA);
;             PG8_WAIT_V(8); PG8_WAIT_L(0); PG8_BAR; PG8_MMA(1, 0, At, B0); PG8_MMA(1, 1, At, B1); PG8_BAR; PG8_SCHED;
	v_mfma_f32_16x16x32_bf16 v[60:63], v[158:161], v[198:201], v[60:63]
	v_mfma_f32_16x16x32_bf16 v[56:59], v[166:169], v[198:201], v[56:59]
	v_mfma_f32_16x16x32_bf16 v[52:55], v[158:161], v[206:209], v[52:55]
	v_mfma_f32_16x16x32_bf16 v[48:51], v[166:169], v[206:209], v[48:51]
	v_mfma_f32_16x16x32_bf16 v[44:47], v[158:161], v[214:217], v[44:47]
	v_mfma_f32_16x16x32_bf16 v[40:43], v[166:169], v[214:217], v[40:43]
	v_mfma_f32_16x16x32_bf16 v[36:39], v[158:161], v[222:225], v[36:39]
	v_mfma_f32_16x16x32_bf16 v[32:35], v[166:169], v[222:225], v[32:35]
	v_mfma_f32_16x16x32_bf16 v[60:63], v[162:165], v[202:205], v[60:63]
	v_mfma_f32_16x16x32_bf16 v[56:59], v[170:173], v[202:205], v[56:59]
	v_mfma_f32_16x16x32_bf16 v[52:55], v[162:165], v[210:213], v[52:55]
	v_mfma_f32_16x16x32_bf16 v[48:51], v[170:173], v[210:213], v[48:51]
	v_mfma_f32_16x16x32_bf16 v[44:47], v[162:165], v[218:221], v[44:47]
	v_mfma_f32_16x16x32_bf16 v[40:43], v[170:173], v[218:221], v[40:43]
	v_mfma_f32_16x16x32_bf16 v[36:39], v[162:165], v[226:229], v[36:39]
	v_mfma_f32_16x16x32_bf16 v[32:35], v[170:173], v[226:229], v[32:35]
	s_setprio 0
	s_setprio 1
	v_mfma_f32_16x16x32_bf16 v[28:31], v[180:183], v[198:201], v[28:31]
	v_mfma_f32_16x16x32_bf16 v[24:27], v[190:193], v[198:201], v[24:27]
	v_mfma_f32_16x16x32_bf16 v[20:23], v[180:183], v[206:209], v[20:23]
	v_mfma_f32_16x16x32_bf16 v[16:19], v[190:193], v[206:209], v[16:19]
	v_mfma_f32_16x16x32_bf16 v[12:15], v[180:183], v[214:217], v[12:15]
	v_mfma_f32_16x16x32_bf16 v[8:11], v[190:193], v[214:217], v[8:11]
	v_mfma_f32_16x16x32_bf16 v[4:7], v[180:183], v[222:225], v[4:7]
	v_mfma_f32_16x16x32_bf16 v[0:3], v[190:193], v[222:225], v[0:3]
	v_mfma_f32_16x16x32_bf16 v[28:31], v[186:189], v[202:205], v[28:31]
	v_mfma_f32_16x16x32_bf16 v[24:27], v[194:197], v[202:205], v[24:27]
	v_mfma_f32_16x16x32_bf16 v[20:23], v[186:189], v[210:213], v[20:23]
	v_mfma_f32_16x16x32_bf16 v[16:19], v[194:197], v[210:213], v[16:19]
	v_mfma_f32_16x16x32_bf16 v[12:15], v[186:189], v[218:221], v[12:15]
	v_mfma_f32_16x16x32_bf16 v[8:11], v[194:197], v[218:221], v[8:11]
	v_mfma_f32_16x16x32_bf16 v[4:7], v[186:189], v[226:229], v[4:7]
	v_mfma_f32_16x16x32_bf16 v[0:3], v[194:197], v[226:229], v[0:3]
	s_barrier
	s_setprio 0
	s_add_i32 s12, 0, 0x18000
	s_add_i32 s13, 0, 0x1c000
	v_add_u32_e32 v170, s12, v177
	v_add_u32_e32 v185, s13, v177
	ds_read_b128 v[158:161], v170
	ds_read_b128 v[162:165], v170 offset:1024
	ds_read_b128 v[166:169], v170 offset:2048
	ds_read_b128 v[170:173], v170 offset:3072
	ds_read_b128 v[180:183], v185
	ds_read_b128 v[186:189], v185 offset:1024
	ds_read_b128 v[190:193], v185 offset:2048
	ds_read_b128 v[194:197], v185 offset:3072
	s_add_u32 s4, s58, 0x4000
	s_addc_u32 s5, s59, 0
	s_mov_b32 m0, s76
	v_lshl_add_u64 v[232:233], s[4:5], 0, v[128:129]
	ds_read_b128 v[198:201], v179 offset:32768
	ds_read_b128 v[202:205], v179 offset:33792
	ds_read_b128 v[206:209], v179 offset:34816
	ds_read_b128 v[210:213], v179 offset:35840
	ds_read_b128 v[214:217], v179 offset:36864
	ds_read_b128 v[218:221], v179 offset:37888
	ds_read_b128 v[222:225], v179 offset:38912
	ds_read_b128 v[226:229], v179 offset:39936
	global_load_lds_dwordx4 v[232:233], off
	v_lshl_add_u64 v[232:233], s[4:5], 0, v[132:133]
	s_mov_b32 m0, s77
	s_nop 0
	global_load_lds_dwordx4 v[232:233], off
	s_waitcnt vmcnt(8)
	s_waitcnt lgkmcnt(0)
	s_setprio 1
	s_barrier
	v_mfma_f32_16x16x32_bf16 v[124:127], v[158:161], v[198:201], v[124:127]
	v_mfma_f32_16x16x32_bf16 v[120:123], v[166:169], v[198:201], v[120:123]
	v_mfma_f32_16x16x32_bf16 v[116:119], v[158:161], v[206:209], v[116:119]
	v_mfma_f32_16x16x32_bf16 v[112:115], v[166:169], v[206:209], v[112:115]
	v_mfma_f32_16x16x32_bf16 v[108:111], v[158:161], v[214:217], v[108:111]
	v_mfma_f32_16x16x32_bf16 v[104:107], v[166:169], v[214:217], v[104:107]
	v_mfma_f32_16x16x32_bf16 v[100:103], v[158:161], v[222:225], v[100:103]
	v_mfma_f32_16x16x32_bf16 v[96:99], v[166:169], v[222:225], v[96:99]
	v_mfma_f32_16x16x32_bf16 v[124:127], v[162:165], v[202:205], v[124:127]
	v_mfma_f32_16x16x32_bf16 v[120:123], v[170:173], v[202:205], v[120:123]
	v_mfma_f32_16x16x32_bf16 v[116:119], v[162:165], v[210:213], v[116:119]
	v_mfma_f32_16x16x32_bf16 v[112:115], v[170:173], v[210:213], v[112:115]
	v_mfma_f32_16x16x32_bf16 v[108:111], v[162:165], v[218:221], v[108:111]
	v_mfma_f32_16x16x32_bf16 v[104:107], v[170:173], v[218:221], v[104:107]
	v_mfma_f32_16x16x32_bf16 v[100:103], v[162:165], v[226:229], v[100:103]
	v_mfma_f32_16x16x32_bf16 v[96:99], v[170:173], v[226:229], v[96:99]
	s_setprio 0
	s_setprio 1
	v_mfma_f32_16x16x32_bf16 v[92:95], v[180:183], v[198:201], v[92:95]
	v_mfma_f32_16x16x32_bf16 v[88:91], v[190:193], v[198:201], v[88:91]
	v_mfma_f32_16x16x32_bf16 v[84:87], v[180:183], v[206:209], v[84:87]
	v_mfma_f32_16x16x32_bf16 v[80:83], v[190:193], v[206:209], v[80:83]
	v_mfma_f32_16x16x32_bf16 v[76:79], v[180:183], v[214:217], v[76:79]
	v_mfma_f32_16x16x32_bf16 v[72:75], v[190:193], v[214:217], v[72:75]
	v_mfma_f32_16x16x32_bf16 v[68:71], v[180:183], v[222:225], v[68:71]
	v_mfma_f32_16x16x32_bf16 v[64:67], v[190:193], v[222:225], v[64:67]
	v_mfma_f32_16x16x32_bf16 v[92:95], v[186:189], v[202:205], v[92:95]
	v_mfma_f32_16x16x32_bf16 v[88:91], v[194:197], v[202:205], v[88:91]
	v_mfma_f32_16x16x32_bf16 v[84:87], v[186:189], v[210:213], v[84:87]
	v_mfma_f32_16x16x32_bf16 v[80:83], v[194:197], v[210:213], v[80:83]
	v_mfma_f32_16x16x32_bf16 v[76:79], v[186:189], v[218:221], v[76:79]
	v_mfma_f32_16x16x32_bf16 v[72:75], v[194:197], v[218:221], v[72:75]
	v_mfma_f32_16x16x32_bf16 v[68:71], v[186:189], v[226:229], v[68:71]
	v_mfma_f32_16x16x32_bf16 v[64:67], v[194:197], v[226:229], v[64:67]
	s_barrier
; #define PG8_STAGE(bufoff, gbase, voff) do { _Pragma("unroll") for (int _i = 0; _i < 2; ++_i) \
;         __builtin_amdgcn_global_load_lds((const unsigned*)((const char*)(gbase) + (voff)[_i]), (PG8_LAS unsigned*)(lds + (bufoff) + ldsw + _i * 8192), 16, 0, 0); } while (0)
; #define PG8_LDA(dst, b, h) do { _Pragma("unroll") for (int m = 0; m < 4; ++m) _Pragma("unroll") for (int k = 0; k < 2; ++k) dst[m][k] = *(const PG8_LAS bf16x8*)(lds + PG8_SA(b, h) + aoff + m * 2048 + k * 1024); } while (0)
; #define PG8_LDB(dst, b, h) do { _Pragma("unroll") for (int n = 0; n < 2; ++n) _Pragma("unroll") for (int k = 0; k < 2; ++k) dst[n][k] = *(const PG8_LAS bf16x8*)(lds + PG8_SB(b, h) + boff + n * 2048 + k * 1024); } while (0)
; #define PG8_MMA(ai, bj, At, Bt) do { __builtin_amdgcn_s_setprio(1); _Pragma("unroll") for (int m = 0; m < 4; ++m) _Pragma("unroll") for (int n = 0; n < 2; ++n) _Pragma("unroll") for (int k = 0; k < 2; ++k) \
;         acc[ai][bj][m][n] = __builtin_amdgcn_mfma_f32_16x16x32_bf16(Bt[n][k], At[m][k], acc[ai][bj][m][n], 0, 0, 0); __builtin_amdgcn_s_setprio(0); } while (0)
; template <class Epi, class Sched, bool ALIGN_EPI = false, bool SP2 = false>
; __device__ __forceinline__ void gemm_phase(PG8_LAS unsigned char* lds, const Gemm g, const Sched& S, const Epi& E) {
;     ...
;         for (int t = 0; t < nt; t += 2) {
;     ...
;             PG8_LDB(B0, 0, 0); PG8_LDB(B1, 0, 1); PG8_SCHED; PG8_LDA(At, 0, 0); PG8_STAGE(PG8_SA(1, 1), a1 + hstepA, voffA);
;             PG8_WAIT_V(8); PG8_WAIT_L(0); PG8_BAR; PG8_MMA(0, 0, At, B0); PG8_MMA(0, 1, At, B1); PG8_BAR; PG8_SCHED;
;             PG8_LDA(At, 0, 1); PG8_STAGE(PG8_SB(0, 0), b2, voffB); PG8_STAGE(PG8_SB(0, 1), b2 + hstepB, voffB); PG8_STAGE(PG8_SA(0, 0), a2, voffA);
;             PG8_WAIT_V(8); PG8_WAIT_L(0); PG8_BAR; PG8_MMA(1, 0, At, B0); PG8_MMA(1, 1, At, B1); PG8_BAR; PG8_SCHED;
;             PG8_LDB(B0, 1, 0); PG8_LDB(B1, 1, 1); PG8_SCHED; PG8_LDA(At, 1, 0); PG8_STAGE(PG8_SA(0, 1), a2 + hstepA, voffA);
;             PG8_WAIT_V(8); PG8_WAIT_L(0); PG8_BAR; PG8_MMA(0, 0, At, B0); PG8_MMA(0, 1, At, B1); PG8_BAR; PG8_SCHED;
;             PG8_LDA(At, 1, 1); PG8_STAGE(PG8_SB(1, 0), b3, voffB); PG8_STAGE(PG8_SB(1, 1), b3 + hstepB, voffB); PG8_STAGE(PG8_SA(1, 0), a3, voffA);
;             PG8_WAIT_V(8); PG8_WAIT_L(0); PG8_BAR; PG8_MMA(1, 0, At, B0); PG8_MMA(1, 1, At, B1); PG8_BAR; PG8_SCHED;
	s_setprio 0
	s_add_i32 s4, s12, s9
	v_lshl_add_u64 v[174:175], v[174:175], 0, s[54:55]
	s_mov_b32 m0, s4
	ds_read_b128 v[198:201], v179 offset:49152
	ds_read_b128 v[202:205], v179 offset:50176
	ds_read_b128 v[206:209], v179 offset:51200
	ds_read_b128 v[210:213], v179 offset:52224
	ds_read_b128 v[214:217], v179 offset:53248
	ds_read_b128 v[218:221], v179 offset:54272
	ds_read_b128 v[222:225], v179 offset:55296
	ds_read_b128 v[226:229], v179 offset:56320
	global_load_lds_dwordx4 v[174:175], off
	s_add_i32 m0, s4, 0x2000
	s_add_u32 s4, s52, 0x160080
	v_lshl_add_u64 v[174:175], v[230:231], 0, s[54:55]
	s_addc_u32 s5, s53, 0
	s_add_i32 s12, s13, s9
	global_load_lds_dwordx4 v[174:175], off
	v_lshl_add_u64 v[174:175], s[4:5], 0, v[130:131]
	s_mov_b32 m0, s12
	s_nop 0
	global_load_lds_dwordx4 v[174:175], off
	v_lshl_add_u64 v[174:175], s[4:5], 0, v[134:135]
	s_add_i32 m0, s12, 0x2000
	s_nop 0
	global_load_lds_dwordx4 v[174:175], off
	v_lshl_add_u64 v[174:175], s[50:51], 0, v[128:129]
	s_mov_b32 m0, s45
	s_nop 0
	global_load_lds_dwordx4 v[174:175], off
	v_lshl_add_u64 v[174:175], s[50:51], 0, v[132:133]
	s_mov_b32 m0, s56
	s_nop 0
	global_load_lds_dwordx4 v[174:175], off
	s_waitcnt vmcnt(8)
	s_waitcnt lgkmcnt(0)
	s_setprio 1
	s_barrier
	v_mfma_f32_16x16x32_bf16 v[60:63], v[158:161], v[198:201], v[60:63]
	v_mfma_f32_16x16x32_bf16 v[56:59], v[166:169], v[198:201], v[56:59]
	v_mfma_f32_16x16x32_bf16 v[52:55], v[158:161], v[206:209], v[52:55]
	v_mfma_f32_16x16x32_bf16 v[48:51], v[166:169], v[206:209], v[48:51]
	v_mfma_f32_16x16x32_bf16 v[44:47], v[158:161], v[214:217], v[44:47]
	v_mfma_f32_16x16x32_bf16 v[40:43], v[166:169], v[214:217], v[40:43]
	v_mfma_f32_16x16x32_bf16 v[36:39], v[158:161], v[222:225], v[36:39]
	v_mfma_f32_16x16x32_bf16 v[32:35], v[166:169], v[222:225], v[32:35]
	v_mfma_f32_16x16x32_bf16 v[60:63], v[162:165], v[202:205], v[60:63]
	v_mfma_f32_16x16x32_bf16 v[56:59], v[170:173], v[202:205], v[56:59]
	v_mfma_f32_16x16x32_bf16 v[52:55], v[162:165], v[210:213], v[52:55]
	v_mfma_f32_16x16x32_bf16 v[48:51], v[170:173], v[210:213], v[48:51]
	v_mfma_f32_16x16x32_bf16 v[44:47], v[162:165], v[218:221], v[44:47]
	v_mfma_f32_16x16x32_bf16 v[40:43], v[170:173], v[218:221], v[40:43]
	v_mfma_f32_16x16x32_bf16 v[36:39], v[162:165], v[226:229], v[36:39]
	v_mfma_f32_16x16x32_bf16 v[32:35], v[170:173], v[226:229], v[32:35]
	s_setprio 0
	s_setprio 1
	v_mfma_f32_16x16x32_bf16 v[28:31], v[180:183], v[198:201], v[28:31]
	v_mfma_f32_16x16x32_bf16 v[24:27], v[190:193], v[198:201], v[24:27]
	v_mfma_f32_16x16x32_bf16 v[20:23], v[180:183], v[206:209], v[20:23]
	v_mfma_f32_16x16x32_bf16 v[16:19], v[190:193], v[206:209], v[16:19]
	v_mfma_f32_16x16x32_bf16 v[12:15], v[180:183], v[214:217], v[12:15]
	v_mfma_f32_16x16x32_bf16 v[8:11], v[190:193], v[214:217], v[8:11]
	v_mfma_f32_16x16x32_bf16 v[4:7], v[180:183], v[222:225], v[4:7]
	v_mfma_f32_16x16x32_bf16 v[0:3], v[190:193], v[222:225], v[0:3]
	v_mfma_f32_16x16x32_bf16 v[28:31], v[186:189], v[202:205], v[28:31]
	v_mfma_f32_16x16x32_bf16 v[24:27], v[194:197], v[202:205], v[24:27]
	v_mfma_f32_16x16x32_bf16 v[20:23], v[186:189], v[210:213], v[20:23]
	v_mfma_f32_16x16x32_bf16 v[16:19], v[194:197], v[210:213], v[16:19]
	v_mfma_f32_16x16x32_bf16 v[12:15], v[186:189], v[218:221], v[12:15]
	v_mfma_f32_16x16x32_bf16 v[8:11], v[194:197], v[218:221], v[8:11]
	v_mfma_f32_16x16x32_bf16 v[4:7], v[186:189], v[226:229], v[4:7]
	v_mfma_f32_16x16x32_bf16 v[0:3], v[194:197], v[226:229], v[0:3]
	s_barrier
	s_setprio 0
	s_cmp_ge_i32 s74, s57
	s_cbranch_scc1 .LBB0_409

; #define PG8_STAGE(bufoff, gbase, voff) do { _Pragma("unroll") for (int _i = 0; _i < 2; ++_i) \
;         __builtin_amdgcn_global_load_lds((const unsigned*)((const char*)(gbase) + (voff)[_i]), (PG8_LAS unsigned*)(lds + (bufoff) + ldsw + _i * 8192), 16, 0, 0); } while (0)
; #define PG8_WAIT_V(n) asm volatile("s_waitcnt vmcnt(" #n ")" ::: "memory")
; #define PG8_WAIT_L(n) asm volatile("s_waitcnt lgkmcnt(" #n ")" ::: "memory")
; template <class Epi, class Sched, bool ALIGN_EPI = false, bool SP2 = false>
; __device__ __forceinline__ void gemm_phase(PG8_LAS unsigned char* lds, const Gemm g, const Sched& S, const Epi& E) {
;     ...
;         const char* nA = has_next ? (const char*)g.A + (size_t)nxt.pm * tstepA + (size_t)nxt.z * g.azs + (size_t)(nxt.k0 >> 6) * kstA : cA; const char* nB = has_next ? (const char*)g.Bt + (size_t)nxt.pn * tstepB + (size_t)nxt.z * g.bzs + (size_t)nxt.k0 * 2 : cB;
;         const int nt = cur.nt;
;         for (int t = 0; t < nt; t += 2) {
;             const bool last = (t == nt - 2);
;             const char* a1 = cA + (size_t)(t + 1) * kstA;
;             const char* a2 = last ? nA : cA + (size_t)(t + 2) * kstA; const char* b2 = last ? nB : cB + (size_t)(t + 2) * kstep;
;             const char* a3 = a2 + kstA; const char* b3 = b2 + kstep;
;             if (last && has_next) S.a_ready(nxt);
;             if constexpr (SP2) {
;             PG8_LDB(B0, 0, 0); PG8_LDB(B1, 0, 1); PG8_SCHED; PG8_LDA(At, 0, 0); PG8_STAGE(PG8_SA(1, 1), a1 + hstepA, voffA);
;             PG8_WAIT_V(8); PG8_WAIT_L(0); PG8_BAR; PG8_MMA(0, 0, At, B0); PG8_MMA(0, 1, At, B1); PG8_BAR; PG8_SCHED;
;             PG8_LDA(At, 0, 1); PG8_STAGE(PG8_SB(0, 0), b2, voffB); PG8_STAGE(PG8_SB(0, 1), b2 + hstepB, voffB); PG8_STAGE(PG8_SA(0, 0), a2, voffA);
;             PG8_WAIT_V(8); PG8_WAIT_L(0); PG8_BAR; PG8_MMA(1, 0, At, B0); PG8_MMA(1, 1, At, B1); PG8_BAR; PG8_SCHED;
;             PG8_LDB(B0, 1, 0); PG8_LDB(B1, 1, 1); PG8_SCHED; PG8_LDA(At, 1, 0); PG8_STAGE(PG8_SA(0, 1), a2 + hstepA, voffA);
;             PG8_WAIT_V(8); PG8_WAIT_L(0); PG8_BAR; PG8_MMA(0, 0, At, B0); PG8_MMA(0, 1, At, B1); PG8_BAR; PG8_SCHED;
;             PG8_LDA(At, 1, 1); PG8_STAGE(PG8_SB(1, 0), b3, voffB); PG8_STAGE(PG8_SB(1, 1), b3 + hstepB, voffB); PG8_STAGE(PG8_SA(1, 0), a3, voffA);
;             PG8_WAIT_V(8); PG8_WAIT_L(0); PG8_BAR; PG8_MMA(1, 0, At, B0); PG8_MMA(1, 1, At, B1); PG8_BAR; PG8_SCHED;
.LBB0_656:
	ds_read_b128 v[166:169], v163
	ds_read_b128 v[170:173], v163 offset:1024
	ds_read_b128 v[174:177], v163 offset:2048
	ds_read_b128 v[178:181], v163 offset:3072
	ds_read_b128 v[186:189], v164
	ds_read_b128 v[190:193], v164 offset:1024
	ds_read_b128 v[194:197], v164 offset:2048
	ds_read_b128 v[198:201], v164 offset:3072
	s_add_u32 s47, s50, 0xfff80080
	s_addc_u32 s52, s51, -1
	s_cmp_eq_u32 s46, 28
	s_cselect_b32 s59, s63, s52
	s_cselect_b32 s58, s62, s47
	s_cselect_b32 s53, s65, s5
	s_cselect_b32 s52, s64, s4
	v_lshl_add_u64 v[158:159], s[50:51], 0, v[152:153]
	s_add_i32 m0, s9, 0xc000
	ds_read_b128 v[202:205], v165
	ds_read_b128 v[206:209], v165 offset:1024
	ds_read_b128 v[210:213], v165 offset:2048
	ds_read_b128 v[214:217], v165 offset:3072
	ds_read_b128 v[218:221], v165 offset:4096
	ds_read_b128 v[222:225], v165 offset:5120
	ds_read_b128 v[226:229], v165 offset:6144
	ds_read_b128 v[230:233], v165 offset:7168
	global_load_lds_dwordx4 v[158:159], off
	v_lshl_add_u64 v[158:159], s[50:51], 0, v[154:155]
	s_add_i32 m0, s9, 0xe000
	s_nop 0
	global_load_lds_dwordx4 v[158:159], off
	s_waitcnt vmcnt(8)
	s_waitcnt lgkmcnt(0)
	s_setprio 1
	s_barrier
	v_mfma_f32_16x16x32_bf16 v[124:127], v[166:169], v[202:205], v[124:127]
	v_mfma_f32_16x16x32_bf16 v[120:123], v[174:177], v[202:205], v[120:123]
	v_mfma_f32_16x16x32_bf16 v[112:115], v[166:169], v[210:213], v[112:115]
	v_mfma_f32_16x16x32_bf16 v[104:107], v[174:177], v[210:213], v[104:107]
	v_mfma_f32_16x16x32_bf16 v[96:99], v[166:169], v[218:221], v[96:99]
	v_mfma_f32_16x16x32_bf16 v[88:91], v[174:177], v[218:221], v[88:91]
	v_mfma_f32_16x16x32_bf16 v[80:83], v[166:169], v[226:229], v[80:83]
	v_mfma_f32_16x16x32_bf16 v[72:75], v[174:177], v[226:229], v[72:75]
	v_mfma_f32_16x16x32_bf16 v[124:127], v[170:173], v[206:209], v[124:127]
	v_mfma_f32_16x16x32_bf16 v[120:123], v[178:181], v[206:209], v[120:123]
	v_mfma_f32_16x16x32_bf16 v[112:115], v[170:173], v[214:217], v[112:115]
	v_mfma_f32_16x16x32_bf16 v[104:107], v[178:181], v[214:217], v[104:107]
	v_mfma_f32_16x16x32_bf16 v[96:99], v[170:173], v[222:225], v[96:99]
	v_mfma_f32_16x16x32_bf16 v[88:91], v[178:181], v[222:225], v[88:91]
	v_mfma_f32_16x16x32_bf16 v[80:83], v[170:173], v[230:233], v[80:83]
	v_mfma_f32_16x16x32_bf16 v[72:75], v[178:181], v[230:233], v[72:75]
	s_setprio 0
	s_setprio 1
	v_mfma_f32_16x16x32_bf16 v[116:119], v[186:189], v[202:205], v[116:119]
	v_mfma_f32_16x16x32_bf16 v[108:111], v[194:197], v[202:205], v[108:111]
	v_mfma_f32_16x16x32_bf16 v[100:103], v[186:189], v[210:213], v[100:103]
	v_mfma_f32_16x16x32_bf16 v[92:95], v[194:197], v[210:213], v[92:95]
	v_mfma_f32_16x16x32_bf16 v[84:87], v[186:189], v[218:221], v[84:87]
	v_mfma_f32_16x16x32_bf16 v[76:79], v[194:197], v[218:221], v[76:79]
	v_mfma_f32_16x16x32_bf16 v[68:71], v[186:189], v[226:229], v[68:71]
	v_mfma_f32_16x16x32_bf16 v[64:67], v[194:197], v[226:229], v[64:67]
	v_mfma_f32_16x16x32_bf16 v[116:119], v[190:193], v[206:209], v[116:119]
	v_mfma_f32_16x16x32_bf16 v[108:111], v[198:201], v[206:209], v[108:111]
	v_mfma_f32_16x16x32_bf16 v[100:103], v[190:193], v[214:217], v[100:103]
	v_mfma_f32_16x16x32_bf16 v[92:95], v[198:201], v[214:217], v[92:95]
	v_mfma_f32_16x16x32_bf16 v[84:87], v[190:193], v[222:225], v[84:87]
	v_mfma_f32_16x16x32_bf16 v[76:79], v[198:201], v[222:225], v[76:79]
	v_mfma_f32_16x16x32_bf16 v[68:71], v[190:193], v[230:233], v[68:71]
	v_mfma_f32_16x16x32_bf16 v[64:67], v[198:201], v[230:233], v[64:67]
	s_barrier
	s_setprio 0
	s_add_i32 s47, s44, s8
	v_lshl_add_u64 v[158:159], s[52:53], 0, v[130:131]
	s_mov_b32 m0, s47
	ds_read_b128 v[202:205], v165 offset:16384
	ds_read_b128 v[206:209], v165 offset:17408
	ds_read_b128 v[210:213], v165 offset:18432
	ds_read_b128 v[214:217], v165 offset:19456
	ds_read_b128 v[218:221], v165 offset:20480
	ds_read_b128 v[222:225], v165 offset:21504
	ds_read_b128 v[226:229], v165 offset:22528
	ds_read_b128 v[230:233], v165 offset:23552
	global_load_lds_dwordx4 v[158:159], off
	s_add_i32 m0, s47, 0x2000
	s_add_u32 s66, s52, 0x80000
	v_lshl_add_u64 v[182:183], s[52:53], 0, v[134:135]
	s_addc_u32 s67, s53, 0
	s_add_i32 s47, s45, s8
	global_load_lds_dwordx4 v[182:183], off
	v_lshl_add_u64 v[234:235], s[66:67], 0, v[130:131]
	s_mov_b32 m0, s47
	v_lshl_add_u64 v[236:237], s[58:59], 0, v[132:133]
	global_load_lds_dwordx4 v[234:235], off
	v_lshl_add_u64 v[234:235], s[66:67], 0, v[134:135]
	s_add_i32 m0, s47, 0x2000
	s_nop 0
	global_load_lds_dwordx4 v[234:235], off
	v_lshl_add_u64 v[234:235], s[58:59], 0, v[128:129]
	s_mov_b32 m0, s9
	s_nop 0
	global_load_lds_dwordx4 v[234:235], off
	s_mov_b32 m0, s10
	s_nop 0
	global_load_lds_dwordx4 v[236:237], off
	s_waitcnt vmcnt(8)
	s_waitcnt lgkmcnt(0)
	s_setprio 1
	s_barrier
; #define PG8_STAGE(bufoff, gbase, voff) do { _Pragma("unroll") for (int _i = 0; _i < 2; ++_i) \
;         __builtin_amdgcn_global_load_lds((const unsigned*)((const char*)(gbase) + (voff)[_i]), (PG8_LAS unsigned*)(lds + (bufoff) + ldsw + _i * 8192), 16, 0, 0); } while (0)
; #define PG8_LDA(dst, b, h) do { _Pragma("unroll") for (int m = 0; m < 4; ++m) _Pragma("unroll") for (int k = 0; k < 2; ++k) dst[m][k] = *(const PG8_LAS bf16x8*)(lds + PG8_SA(b, h) + aoff + m * 2048 + k * 1024); } while (0)
; #define PG8_LDB(dst, b, h) do { _Pragma("unroll") for (int n = 0; n < 2; ++n) _Pragma("unroll") for (int k = 0; k < 2; ++k) dst[n][k] = *(const PG8_LAS bf16x8*)(lds + PG8_SB(b, h) + boff + n * 2048 + k * 1024); } while (0)
; #define PG8_MMA(ai, bj, At, Bt) do { __builtin_amdgcn_s_setprio(1); _Pragma("unroll") for (int m = 0; m < 4; ++m) _Pragma("unroll") for (int n = 0; n < 2; ++n) _Pragma("unroll") for (int k = 0; k < 2; ++k) \
;         acc[ai][bj][m][n] = __builtin_amdgcn_mfma_f32_16x16x32_bf16(Bt[n][k], At[m][k], acc[ai][bj][m][n], 0, 0, 0); __builtin_amdgcn_s_setprio(0); } while (0)
; #define PG8_WAIT_V(n) asm volatile("s_waitcnt vmcnt(" #n ")" ::: "memory")
; template <class Epi, class Sched, bool ALIGN_EPI = false, bool SP2 = false>
; __device__ __forceinline__ void gemm_phase(PG8_LAS unsigned char* lds, const Gemm g, const Sched& S, const Epi& E) {
;     ...
;             PG8_LDB(B0, 0, 0); PG8_LDB(B1, 0, 1); PG8_SCHED; PG8_LDA(At, 0, 0); PG8_STAGE(PG8_SA(1, 1), a1 + hstepA, voffA);
;             PG8_WAIT_V(8); PG8_WAIT_L(0); PG8_BAR; PG8_MMA(0, 0, At, B0); PG8_MMA(0, 1, At, B1); PG8_BAR; PG8_SCHED;
;             PG8_LDA(At, 0, 1); PG8_STAGE(PG8_SB(0, 0), b2, voffB); PG8_STAGE(PG8_SB(0, 1), b2 + hstepB, voffB); PG8_STAGE(PG8_SA(0, 0), a2, voffA);
;             PG8_WAIT_V(8); PG8_WAIT_L(0); PG8_BAR; PG8_MMA(1, 0, At, B0); PG8_MMA(1, 1, At, B1); PG8_BAR; PG8_SCHED;
;             PG8_LDB(B0, 1, 0); PG8_LDB(B1, 1, 1); PG8_SCHED; PG8_LDA(At, 1, 0); PG8_STAGE(PG8_SA(0, 1), a2 + hstepA, voffA);
;             PG8_WAIT_V(8); PG8_WAIT_L(0); PG8_BAR; PG8_MMA(0, 0, At, B0); PG8_MMA(0, 1, At, B1); PG8_BAR; PG8_SCHED;
;             PG8_LDA(At, 1, 1); PG8_STAGE(PG8_SB(1, 0), b3, voffB); PG8_STAGE(PG8_SB(1, 1), b3 + hstepB, voffB); PG8_STAGE(PG8_SA(1, 0), a3, voffA);
;             PG8_WAIT_V(8); PG8_WAIT_L(0); PG8_BAR; PG8_MMA(1, 0, At, B0); PG8_MMA(1, 1, At, B1); PG8_BAR; PG8_SCHED;
	v_mfma_f32_16x16x32_bf16 v[60:63], v[166:169], v[202:205], v[60:63]
	v_mfma_f32_16x16x32_bf16 v[56:59], v[174:177], v[202:205], v[56:59]
	v_mfma_f32_16x16x32_bf16 v[48:51], v[166:169], v[210:213], v[48:51]
	v_mfma_f32_16x16x32_bf16 v[40:43], v[174:177], v[210:213], v[40:43]
	v_mfma_f32_16x16x32_bf16 v[32:35], v[166:169], v[218:221], v[32:35]
	v_mfma_f32_16x16x32_bf16 v[24:27], v[174:177], v[218:221], v[24:27]
	v_mfma_f32_16x16x32_bf16 v[16:19], v[166:169], v[226:229], v[16:19]
	v_mfma_f32_16x16x32_bf16 v[8:11], v[174:177], v[226:229], v[8:11]
	v_mfma_f32_16x16x32_bf16 v[60:63], v[170:173], v[206:209], v[60:63]
	v_mfma_f32_16x16x32_bf16 v[56:59], v[178:181], v[206:209], v[56:59]
	v_mfma_f32_16x16x32_bf16 v[48:51], v[170:173], v[214:217], v[48:51]
	v_mfma_f32_16x16x32_bf16 v[40:43], v[178:181], v[214:217], v[40:43]
	v_mfma_f32_16x16x32_bf16 v[32:35], v[170:173], v[222:225], v[32:35]
	v_mfma_f32_16x16x32_bf16 v[24:27], v[178:181], v[222:225], v[24:27]
	v_mfma_f32_16x16x32_bf16 v[16:19], v[170:173], v[230:233], v[16:19]
	v_mfma_f32_16x16x32_bf16 v[8:11], v[178:181], v[230:233], v[8:11]
	s_setprio 0
	s_setprio 1
	v_mfma_f32_16x16x32_bf16 v[52:55], v[186:189], v[202:205], v[52:55]
	v_mfma_f32_16x16x32_bf16 v[44:47], v[194:197], v[202:205], v[44:47]
	v_mfma_f32_16x16x32_bf16 v[36:39], v[186:189], v[210:213], v[36:39]
	v_mfma_f32_16x16x32_bf16 v[28:31], v[194:197], v[210:213], v[28:31]
	v_mfma_f32_16x16x32_bf16 v[20:23], v[186:189], v[218:221], v[20:23]
	v_mfma_f32_16x16x32_bf16 v[12:15], v[194:197], v[218:221], v[12:15]
	v_mfma_f32_16x16x32_bf16 v[4:7], v[186:189], v[226:229], v[4:7]
	v_mfma_f32_16x16x32_bf16 v[0:3], v[194:197], v[226:229], v[0:3]
	v_mfma_f32_16x16x32_bf16 v[52:55], v[190:193], v[206:209], v[52:55]
	v_mfma_f32_16x16x32_bf16 v[44:47], v[198:201], v[206:209], v[44:47]
	v_mfma_f32_16x16x32_bf16 v[36:39], v[190:193], v[214:217], v[36:39]
	v_mfma_f32_16x16x32_bf16 v[28:31], v[198:201], v[214:217], v[28:31]
	v_mfma_f32_16x16x32_bf16 v[20:23], v[190:193], v[222:225], v[20:23]
	v_mfma_f32_16x16x32_bf16 v[12:15], v[198:201], v[222:225], v[12:15]
	v_mfma_f32_16x16x32_bf16 v[4:7], v[190:193], v[230:233], v[4:7]
	v_mfma_f32_16x16x32_bf16 v[0:3], v[198:201], v[230:233], v[0:3]
	s_barrier
	s_setprio 0
	s_add_i32 s47, 0, 0x18000
	s_add_i32 s55, 0, 0x1c000
	v_add_u32_e32 v178, s47, v160
	v_add_u32_e32 v185, s55, v160
	ds_read_b128 v[166:169], v178
	ds_read_b128 v[170:173], v178 offset:1024
	ds_read_b128 v[174:177], v178 offset:2048
	ds_read_b128 v[178:181], v178 offset:3072
	ds_read_b128 v[186:189], v185
	ds_read_b128 v[190:193], v185 offset:1024
	ds_read_b128 v[194:197], v185 offset:2048
	ds_read_b128 v[198:201], v185 offset:3072
	s_add_u32 s58, s58, 0x80000
	s_addc_u32 s59, s59, 0
	s_mov_b32 m0, s11
	v_lshl_add_u64 v[238:239], s[58:59], 0, v[128:129]
	ds_read_b128 v[202:205], v165 offset:32768
	ds_read_b128 v[206:209], v165 offset:33792
	ds_read_b128 v[210:213], v165 offset:34816
	ds_read_b128 v[214:217], v165 offset:35840
	ds_read_b128 v[218:221], v165 offset:36864
	ds_read_b128 v[222:225], v165 offset:37888
	ds_read_b128 v[226:229], v165 offset:38912
	ds_read_b128 v[230:233], v165 offset:39936
	global_load_lds_dwordx4 v[238:239], off
	v_lshl_add_u64 v[238:239], s[58:59], 0, v[132:133]
	s_mov_b32 m0, s12
	s_nop 0
	global_load_lds_dwordx4 v[238:239], off
	s_waitcnt vmcnt(8)
	s_waitcnt lgkmcnt(0)
	s_setprio 1
	s_barrier
	v_mfma_f32_16x16x32_bf16 v[124:127], v[166:169], v[202:205], v[124:127]
	v_mfma_f32_16x16x32_bf16 v[120:123], v[174:177], v[202:205], v[120:123]
	v_mfma_f32_16x16x32_bf16 v[112:115], v[166:169], v[210:213], v[112:115]
	v_mfma_f32_16x16x32_bf16 v[104:107], v[174:177], v[210:213], v[104:107]
	v_mfma_f32_16x16x32_bf16 v[96:99], v[166:169], v[218:221], v[96:99]
	v_mfma_f32_16x16x32_bf16 v[88:91], v[174:177], v[218:221], v[88:91]
	v_mfma_f32_16x16x32_bf16 v[80:83], v[166:169], v[226:229], v[80:83]
	v_mfma_f32_16x16x32_bf16 v[72:75], v[174:177], v[226:229], v[72:75]
	v_mfma_f32_16x16x32_bf16 v[124:127], v[170:173], v[206:209], v[124:127]
	v_mfma_f32_16x16x32_bf16 v[120:123], v[178:181], v[206:209], v[120:123]
	v_mfma_f32_16x16x32_bf16 v[112:115], v[170:173], v[214:217], v[112:115]
	v_mfma_f32_16x16x32_bf16 v[104:107], v[178:181], v[214:217], v[104:107]
	v_mfma_f32_16x16x32_bf16 v[96:99], v[170:173], v[222:225], v[96:99]
	v_mfma_f32_16x16x32_bf16 v[88:91], v[178:181], v[222:225], v[88:91]
	v_mfma_f32_16x16x32_bf16 v[80:83], v[170:173], v[230:233], v[80:83]
	v_mfma_f32_16x16x32_bf16 v[72:75], v[178:181], v[230:233], v[72:75]
	s_setprio 0
	s_setprio 1
	v_mfma_f32_16x16x32_bf16 v[116:119], v[186:189], v[202:205], v[116:119]
	v_mfma_f32_16x16x32_bf16 v[108:111], v[194:197], v[202:205], v[108:111]
	v_mfma_f32_16x16x32_bf16 v[100:103], v[186:189], v[210:213], v[100:103]
	v_mfma_f32_16x16x32_bf16 v[92:95], v[194:197], v[210:213], v[92:95]
	v_mfma_f32_16x16x32_bf16 v[84:87], v[186:189], v[218:221], v[84:87]
	v_mfma_f32_16x16x32_bf16 v[76:79], v[194:197], v[218:221], v[76:79]
	v_mfma_f32_16x16x32_bf16 v[68:71], v[186:189], v[226:229], v[68:71]
	v_mfma_f32_16x16x32_bf16 v[64:67], v[194:197], v[226:229], v[64:67]
	v_mfma_f32_16x16x32_bf16 v[116:119], v[190:193], v[206:209], v[116:119]
	v_mfma_f32_16x16x32_bf16 v[108:111], v[198:201], v[206:209], v[108:111]
	v_mfma_f32_16x16x32_bf16 v[100:103], v[190:193], v[214:217], v[100:103]
	v_mfma_f32_16x16x32_bf16 v[92:95], v[198:201], v[214:217], v[92:95]
	v_mfma_f32_16x16x32_bf16 v[84:87], v[190:193], v[222:225], v[84:87]
	v_mfma_f32_16x16x32_bf16 v[76:79], v[198:201], v[222:225], v[76:79]
	v_mfma_f32_16x16x32_bf16 v[68:71], v[190:193], v[230:233], v[68:71]
	v_mfma_f32_16x16x32_bf16 v[64:67], v[198:201], v[230:233], v[64:67]
	s_barrier
; #define PG8_STAGE(bufoff, gbase, voff) do { _Pragma("unroll") for (int _i = 0; _i < 2; ++_i) \
;         __builtin_amdgcn_global_load_lds((const unsigned*)((const char*)(gbase) + (voff)[_i]), (PG8_LAS unsigned*)(lds + (bufoff) + ldsw + _i * 8192), 16, 0, 0); } while (0)
; #define PG8_LDA(dst, b, h) do { _Pragma("unroll") for (int m = 0; m < 4; ++m) _Pragma("unroll") for (int k = 0; k < 2; ++k) dst[m][k] = *(const PG8_LAS bf16x8*)(lds + PG8_SA(b, h) + aoff + m * 2048 + k * 1024); } while (0)
; #define PG8_LDB(dst, b, h) do { _Pragma("unroll") for (int n = 0; n < 2; ++n) _Pragma("unroll") for (int k = 0; k < 2; ++k) dst[n][k] = *(const PG8_LAS bf16x8*)(lds + PG8_SB(b, h) + boff + n * 2048 + k * 1024); } while (0)
; template <class Epi, class Sched, bool ALIGN_EPI = false, bool SP2 = false>
; __device__ __forceinline__ void gemm_phase(PG8_LAS unsigned char* lds, const Gemm g, const Sched& S, const Epi& E) {
;     ...
;         for (int t = 0; t < nt; t += 2) {
;             const bool last = (t == nt - 2);
;             const char* a1 = cA + (size_t)(t + 1) * kstA;
;             const char* a2 = last ? nA : cA + (size_t)(t + 2) * kstA; const char* b2 = last ? nB : cB + (size_t)(t + 2) * kstep;
;             const char* a3 = a2 + kstA; const char* b3 = b2 + kstep;
;             if (last && has_next) S.a_ready(nxt);
;             if constexpr (SP2) {
;             PG8_LDB(B0, 0, 0); PG8_LDB(B1, 0, 1); PG8_SCHED; PG8_LDA(At, 0, 0); PG8_STAGE(PG8_SA(1, 1), a1 + hstepA, voffA);
;             PG8_WAIT_V(8); PG8_WAIT_L(0); PG8_BAR; PG8_MMA(0, 0, At, B0); PG8_MMA(0, 1, At, B1); PG8_BAR; PG8_SCHED;
;             PG8_LDA(At, 0, 1); PG8_STAGE(PG8_SB(0, 0), b2, voffB); PG8_STAGE(PG8_SB(0, 1), b2 + hstepB, voffB); PG8_STAGE(PG8_SA(0, 0), a2, voffA);
;             PG8_WAIT_V(8); PG8_WAIT_L(0); PG8_BAR; PG8_MMA(1, 0, At, B0); PG8_MMA(1, 1, At, B1); PG8_BAR; PG8_SCHED;
;             PG8_LDB(B0, 1, 0); PG8_LDB(B1, 1, 1); PG8_SCHED; PG8_LDA(At, 1, 0); PG8_STAGE(PG8_SA(0, 1), a2 + hstepA, voffA);
;             PG8_WAIT_V(8); PG8_WAIT_L(0); PG8_BAR; PG8_MMA(0, 0, At, B0); PG8_MMA(0, 1, At, B1); PG8_BAR; PG8_SCHED;
;             PG8_LDA(At, 1, 1); PG8_STAGE(PG8_SB(1, 0), b3, voffB); PG8_STAGE(PG8_SB(1, 1), b3 + hstepB, voffB); PG8_STAGE(PG8_SA(1, 0), a3, voffA);
;             PG8_WAIT_V(8); PG8_WAIT_L(0); PG8_BAR; PG8_MMA(1, 0, At, B0); PG8_MMA(1, 1, At, B1); PG8_BAR; PG8_SCHED;
	s_setprio 0
	s_add_i32 s47, s47, s8
	v_lshl_add_u64 v[158:159], v[158:159], 0, s[38:39]
	s_mov_b32 m0, s47
	ds_read_b128 v[202:205], v165 offset:49152
	ds_read_b128 v[206:209], v165 offset:50176
	ds_read_b128 v[210:213], v165 offset:51200
	ds_read_b128 v[214:217], v165 offset:52224
	ds_read_b128 v[218:221], v165 offset:53248
	ds_read_b128 v[222:225], v165 offset:54272
	ds_read_b128 v[226:229], v165 offset:55296
	ds_read_b128 v[230:233], v165 offset:56320
	global_load_lds_dwordx4 v[158:159], off
	s_add_i32 m0, s47, 0x2000
	s_add_u32 s52, s52, 0x80080
	v_lshl_add_u64 v[158:159], v[182:183], 0, s[38:39]
	s_addc_u32 s53, s53, 0
	s_add_i32 s47, s55, s8
	global_load_lds_dwordx4 v[158:159], off
	v_lshl_add_u64 v[158:159], s[52:53], 0, v[130:131]
	s_mov_b32 m0, s47
	s_nop 0
	global_load_lds_dwordx4 v[158:159], off
	v_lshl_add_u64 v[158:159], s[52:53], 0, v[134:135]
	s_add_i32 m0, s47, 0x2000
	s_nop 0
	global_load_lds_dwordx4 v[158:159], off
	v_lshl_add_u64 v[158:159], v[234:235], 0, s[38:39]
	s_mov_b32 m0, s13
	s_nop 0
	global_load_lds_dwordx4 v[158:159], off
	v_lshl_add_u64 v[158:159], v[236:237], 0, s[38:39]
	s_mov_b32 m0, s33
	s_nop 0
	global_load_lds_dwordx4 v[158:159], off
	s_waitcnt vmcnt(8)
	s_waitcnt lgkmcnt(0)
	s_setprio 1
	s_barrier
	v_mfma_f32_16x16x32_bf16 v[60:63], v[166:169], v[202:205], v[60:63]
	v_mfma_f32_16x16x32_bf16 v[56:59], v[174:177], v[202:205], v[56:59]
	v_mfma_f32_16x16x32_bf16 v[48:51], v[166:169], v[210:213], v[48:51]
	v_mfma_f32_16x16x32_bf16 v[40:43], v[174:177], v[210:213], v[40:43]
	v_mfma_f32_16x16x32_bf16 v[32:35], v[166:169], v[218:221], v[32:35]
	v_mfma_f32_16x16x32_bf16 v[24:27], v[174:177], v[218:221], v[24:27]
	v_mfma_f32_16x16x32_bf16 v[16:19], v[166:169], v[226:229], v[16:19]
	v_mfma_f32_16x16x32_bf16 v[8:11], v[174:177], v[226:229], v[8:11]
	v_mfma_f32_16x16x32_bf16 v[60:63], v[170:173], v[206:209], v[60:63]
	v_mfma_f32_16x16x32_bf16 v[56:59], v[178:181], v[206:209], v[56:59]
	v_mfma_f32_16x16x32_bf16 v[48:51], v[170:173], v[214:217], v[48:51]
	v_mfma_f32_16x16x32_bf16 v[40:43], v[178:181], v[214:217], v[40:43]
	v_mfma_f32_16x16x32_bf16 v[32:35], v[170:173], v[222:225], v[32:35]
	v_mfma_f32_16x16x32_bf16 v[24:27], v[178:181], v[222:225], v[24:27]
	v_mfma_f32_16x16x32_bf16 v[16:19], v[170:173], v[230:233], v[16:19]
	v_mfma_f32_16x16x32_bf16 v[8:11], v[178:181], v[230:233], v[8:11]
	s_setprio 0
	s_setprio 1
	v_mfma_f32_16x16x32_bf16 v[52:55], v[186:189], v[202:205], v[52:55]
	v_mfma_f32_16x16x32_bf16 v[44:47], v[194:197], v[202:205], v[44:47]
	v_mfma_f32_16x16x32_bf16 v[36:39], v[186:189], v[210:213], v[36:39]
	v_mfma_f32_16x16x32_bf16 v[28:31], v[194:197], v[210:213], v[28:31]
	v_mfma_f32_16x16x32_bf16 v[20:23], v[186:189], v[218:221], v[20:23]
	v_mfma_f32_16x16x32_bf16 v[12:15], v[194:197], v[218:221], v[12:15]
	v_mfma_f32_16x16x32_bf16 v[4:7], v[186:189], v[226:229], v[4:7]
	v_mfma_f32_16x16x32_bf16 v[0:3], v[194:197], v[226:229], v[0:3]
	v_mfma_f32_16x16x32_bf16 v[52:55], v[190:193], v[206:209], v[52:55]
	v_mfma_f32_16x16x32_bf16 v[44:47], v[198:201], v[206:209], v[44:47]
	v_mfma_f32_16x16x32_bf16 v[36:39], v[190:193], v[214:217], v[36:39]
	v_mfma_f32_16x16x32_bf16 v[28:31], v[198:201], v[214:217], v[28:31]
	v_mfma_f32_16x16x32_bf16 v[20:23], v[190:193], v[222:225], v[20:23]
	v_mfma_f32_16x16x32_bf16 v[12:15], v[198:201], v[222:225], v[12:15]
	v_mfma_f32_16x16x32_bf16 v[4:7], v[190:193], v[230:233], v[4:7]
	v_mfma_f32_16x16x32_bf16 v[0:3], v[198:201], v[230:233], v[0:3]
	s_barrier
	s_setprio 0
	s_add_i32 s46, s46, 2
	s_add_u32 s50, s50, 0x100
	s_addc_u32 s51, s51, 0
	s_add_u32 s4, s4, 0x100
	s_addc_u32 s5, s5, 0
	s_cmp_gt_u32 s46, 29
	s_cbranch_scc0 .LBB0_656
	s_and_b64 vcc, exec, s[40:41]
	s_cbranch_vccz .LBB0_659
	s_barrier

; #define PG8_STAGE(bufoff, gbase, voff) do { _Pragma("unroll") for (int _i = 0; _i < 2; ++_i) \
;         __builtin_amdgcn_global_load_lds((const unsigned*)((const char*)(gbase) + (voff)[_i]), (PG8_LAS unsigned*)(lds + (bufoff) + ldsw + _i * 8192), 16, 0, 0); } while (0)
; #define PG8_WAIT_V(n) asm volatile("s_waitcnt vmcnt(" #n ")" ::: "memory")
; #define PG8_WAIT_L(n) asm volatile("s_waitcnt lgkmcnt(" #n ")" ::: "memory")
; template <class Epi, class Sched, bool ALIGN_EPI = false, bool SP2 = false>
; __device__ __forceinline__ void gemm_phase(PG8_LAS unsigned char* lds, const Gemm g, const Sched& S, const Epi& E) {
;     ...
;         const char* nA = has_next ? (const char*)g.A + (size_t)nxt.pm * tstepA + (size_t)nxt.z * g.azs + (size_t)(nxt.k0 >> 6) * kstA : cA; const char* nB = has_next ? (const char*)g.Bt + (size_t)nxt.pn * tstepB + (size_t)nxt.z * g.bzs + (size_t)nxt.k0 * 2 : cB;
;         const int nt = cur.nt;
;         for (int t = 0; t < nt; t += 2) {
;             const bool last = (t == nt - 2);
;             const char* a1 = cA + (size_t)(t + 1) * kstA;
;             const char* a2 = last ? nA : cA + (size_t)(t + 2) * kstA; const char* b2 = last ? nB : cB + (size_t)(t + 2) * kstep;
;             const char* a3 = a2 + kstA; const char* b3 = b2 + kstep;
;             if (last && has_next) S.a_ready(nxt);
;             if constexpr (SP2) {
;             PG8_LDB(B0, 0, 0); PG8_LDB(B1, 0, 1); PG8_SCHED; PG8_LDA(At, 0, 0); PG8_STAGE(PG8_SA(1, 1), a1 + hstepA, voffA);
;             PG8_WAIT_V(8); PG8_WAIT_L(0); PG8_BAR; PG8_MMA(0, 0, At, B0); PG8_MMA(0, 1, At, B1); PG8_BAR; PG8_SCHED;
;             PG8_LDA(At, 0, 1); PG8_STAGE(PG8_SB(0, 0), b2, voffB); PG8_STAGE(PG8_SB(0, 1), b2 + hstepB, voffB); PG8_STAGE(PG8_SA(0, 0), a2, voffA);
;             PG8_WAIT_V(8); PG8_WAIT_L(0); PG8_BAR; PG8_MMA(1, 0, At, B0); PG8_MMA(1, 1, At, B1); PG8_BAR; PG8_SCHED;
;             PG8_LDB(B0, 1, 0); PG8_LDB(B1, 1, 1); PG8_SCHED; PG8_LDA(At, 1, 0); PG8_STAGE(PG8_SA(0, 1), a2 + hstepA, voffA);
;             PG8_WAIT_V(8); PG8_WAIT_L(0); PG8_BAR; PG8_MMA(0, 0, At, B0); PG8_MMA(0, 1, At, B1); PG8_BAR; PG8_SCHED;
;             PG8_LDA(At, 1, 1); PG8_STAGE(PG8_SB(1, 0), b3, voffB); PG8_STAGE(PG8_SB(1, 1), b3 + hstepB, voffB); PG8_STAGE(PG8_SA(1, 0), a3, voffA);
;             PG8_WAIT_V(8); PG8_WAIT_L(0); PG8_BAR; PG8_MMA(1, 0, At, B0); PG8_MMA(1, 1, At, B1); PG8_BAR; PG8_SCHED;
.LBB0_1048:
	s_or_b32 s58, s66, 1
	s_add_i32 s66, s66, 2
	s_mov_b32 s67, s59
	v_add_u32_e32 v140, s10, v179
	v_add_u32_e32 v182, s11, v179
	s_lshl_b64 s[4:5], s[58:59], 7
	s_lshl_b64 s[6:7], s[66:67], 7
	ds_read_b128 v[128:131], v140
	ds_read_b128 v[132:135], v140 offset:1024
	ds_read_b128 v[136:139], v140 offset:2048
	ds_read_b128 v[140:143], v140 offset:3072
	ds_read_b128 v[174:177], v182
	ds_read_b128 v[190:193], v182 offset:1024
	ds_read_b128 v[194:197], v182 offset:2048
	ds_read_b128 v[198:201], v182 offset:3072
	s_add_u32 s46, s60, s6
	s_addc_u32 s47, s61, s7
	s_and_b64 s[12:13], s[76:77], exec
	s_cselect_b32 vcc_hi, s47, s49
	s_cselect_b32 vcc_lo, s46, s48
	s_add_u32 s12, s62, s6
	s_addc_u32 s13, s63, s7
	s_and_b64 s[6:7], s[76:77], exec
	s_cselect_b32 s77, s13, s55
	s_cselect_b32 s76, s12, s54
	s_add_u32 s4, s35, s4
	s_addc_u32 s5, s39, s5
	v_lshl_add_u64 v[182:183], s[4:5], 0, v[144:145]
	s_add_i32 m0, s21, 0xc000
	ds_read_b128 v[202:205], v181
	ds_read_b128 v[206:209], v181 offset:1024
	ds_read_b128 v[210:213], v181 offset:2048
	ds_read_b128 v[214:217], v181 offset:3072
	ds_read_b128 v[218:221], v181 offset:4096
	ds_read_b128 v[222:225], v181 offset:5120
	ds_read_b128 v[226:229], v181 offset:6144
	ds_read_b128 v[230:233], v181 offset:7168
	global_load_lds_dwordx4 v[182:183], off
	v_lshl_add_u64 v[182:183], s[4:5], 0, v[148:149]
	s_add_i32 m0, s21, 0xe000
	s_nop 0
	global_load_lds_dwordx4 v[182:183], off
	s_waitcnt vmcnt(8)
	s_waitcnt lgkmcnt(0)
	s_setprio 1
	s_barrier
	v_mfma_f32_16x16x32_bf16 v[124:127], v[128:131], v[202:205], v[124:127]
	v_mfma_f32_16x16x32_bf16 v[120:123], v[136:139], v[202:205], v[120:123]
	v_mfma_f32_16x16x32_bf16 v[116:119], v[128:131], v[210:213], v[116:119]
	v_mfma_f32_16x16x32_bf16 v[112:115], v[136:139], v[210:213], v[112:115]
	v_mfma_f32_16x16x32_bf16 v[108:111], v[128:131], v[218:221], v[108:111]
	v_mfma_f32_16x16x32_bf16 v[104:107], v[136:139], v[218:221], v[104:107]
	v_mfma_f32_16x16x32_bf16 v[100:103], v[128:131], v[226:229], v[100:103]
	v_mfma_f32_16x16x32_bf16 v[96:99], v[136:139], v[226:229], v[96:99]
	v_mfma_f32_16x16x32_bf16 v[124:127], v[132:135], v[206:209], v[124:127]
	v_mfma_f32_16x16x32_bf16 v[120:123], v[140:143], v[206:209], v[120:123]
	v_mfma_f32_16x16x32_bf16 v[116:119], v[132:135], v[214:217], v[116:119]
	v_mfma_f32_16x16x32_bf16 v[112:115], v[140:143], v[214:217], v[112:115]
	v_mfma_f32_16x16x32_bf16 v[108:111], v[132:135], v[222:225], v[108:111]
	v_mfma_f32_16x16x32_bf16 v[104:107], v[140:143], v[222:225], v[104:107]
	v_mfma_f32_16x16x32_bf16 v[100:103], v[132:135], v[230:233], v[100:103]
	v_mfma_f32_16x16x32_bf16 v[96:99], v[140:143], v[230:233], v[96:99]
	s_setprio 0
	s_setprio 1
	v_mfma_f32_16x16x32_bf16 v[92:95], v[174:177], v[202:205], v[92:95]
	v_mfma_f32_16x16x32_bf16 v[88:91], v[194:197], v[202:205], v[88:91]
	v_mfma_f32_16x16x32_bf16 v[84:87], v[174:177], v[210:213], v[84:87]
	v_mfma_f32_16x16x32_bf16 v[80:83], v[194:197], v[210:213], v[80:83]
	v_mfma_f32_16x16x32_bf16 v[76:79], v[174:177], v[218:221], v[76:79]
	v_mfma_f32_16x16x32_bf16 v[72:75], v[194:197], v[218:221], v[72:75]
	v_mfma_f32_16x16x32_bf16 v[68:71], v[174:177], v[226:229], v[68:71]
	v_mfma_f32_16x16x32_bf16 v[64:67], v[194:197], v[226:229], v[64:67]
	v_mfma_f32_16x16x32_bf16 v[92:95], v[190:193], v[206:209], v[92:95]
	v_mfma_f32_16x16x32_bf16 v[88:91], v[198:201], v[206:209], v[88:91]
	v_mfma_f32_16x16x32_bf16 v[84:87], v[190:193], v[214:217], v[84:87]
	v_mfma_f32_16x16x32_bf16 v[80:83], v[198:201], v[214:217], v[80:83]
	v_mfma_f32_16x16x32_bf16 v[76:79], v[190:193], v[222:225], v[76:79]
	v_mfma_f32_16x16x32_bf16 v[72:75], v[198:201], v[222:225], v[72:75]
	v_mfma_f32_16x16x32_bf16 v[68:71], v[190:193], v[230:233], v[68:71]
	v_mfma_f32_16x16x32_bf16 v[64:67], v[198:201], v[230:233], v[64:67]
	s_barrier
	s_setprio 0
	s_add_i32 s4, s10, s94
	v_lshl_add_u64 v[182:183], s[76:77], 0, v[146:147]
	s_mov_b32 m0, s4
	ds_read_b128 v[202:205], v181 offset:16384
	ds_read_b128 v[206:209], v181 offset:17408
	ds_read_b128 v[210:213], v181 offset:18432
	ds_read_b128 v[214:217], v181 offset:19456
	ds_read_b128 v[218:221], v181 offset:20480
	ds_read_b128 v[222:225], v181 offset:21504
	ds_read_b128 v[226:229], v181 offset:22528
	ds_read_b128 v[230:233], v181 offset:23552
	global_load_lds_dwordx4 v[182:183], off
	s_add_i32 m0, s4, 0x2000
	s_add_u32 s4, s76, 0x80000
	v_lshl_add_u64 v[234:235], s[76:77], 0, v[150:151]
	s_addc_u32 s5, s77, 0
	s_add_i32 s6, s11, s94
	global_load_lds_dwordx4 v[234:235], off
	v_lshl_add_u64 v[236:237], s[4:5], 0, v[146:147]
	s_mov_b32 m0, s6
	v_lshl_add_u64 v[238:239], vcc, 0, v[148:149]
	global_load_lds_dwordx4 v[236:237], off
	v_lshl_add_u64 v[236:237], s[4:5], 0, v[150:151]
	s_add_i32 m0, s6, 0x2000
	s_nop 0
	global_load_lds_dwordx4 v[236:237], off
	v_lshl_add_u64 v[236:237], vcc, 0, v[144:145]
	s_mov_b32 m0, s21
	s_nop 0
	global_load_lds_dwordx4 v[236:237], off
	s_mov_b32 m0, s95
	s_nop 0
	global_load_lds_dwordx4 v[238:239], off
	s_waitcnt vmcnt(8)
	s_waitcnt lgkmcnt(0)
	s_setprio 1
	s_barrier
; #define PG8_STAGE(bufoff, gbase, voff) do { _Pragma("unroll") for (int _i = 0; _i < 2; ++_i) \
;         __builtin_amdgcn_global_load_lds((const unsigned*)((const char*)(gbase) + (voff)[_i]), (PG8_LAS unsigned*)(lds + (bufoff) + ldsw + _i * 8192), 16, 0, 0); } while (0)
; #define PG8_LDA(dst, b, h) do { _Pragma("unroll") for (int m = 0; m < 4; ++m) _Pragma("unroll") for (int k = 0; k < 2; ++k) dst[m][k] = *(const PG8_LAS bf16x8*)(lds + PG8_SA(b, h) + aoff + m * 2048 + k * 1024); } while (0)
; #define PG8_LDB(dst, b, h) do { _Pragma("unroll") for (int n = 0; n < 2; ++n) _Pragma("unroll") for (int k = 0; k < 2; ++k) dst[n][k] = *(const PG8_LAS bf16x8*)(lds + PG8_SB(b, h) + boff + n * 2048 + k * 1024); } while (0)
; #define PG8_MMA(ai, bj, At, Bt) do { __builtin_amdgcn_s_setprio(1); _Pragma("unroll") for (int m = 0; m < 4; ++m) _Pragma("unroll") for (int n = 0; n < 2; ++n) _Pragma("unroll") for (int k = 0; k < 2; ++k) \
;         acc[ai][bj][m][n] = __builtin_amdgcn_mfma_f32_16x16x32_bf16(Bt[n][k], At[m][k], acc[ai][bj][m][n], 0, 0, 0); __builtin_amdgcn_s_setprio(0); } while (0)
; #define PG8_WAIT_V(n) asm volatile("s_waitcnt vmcnt(" #n ")" ::: "memory")
; template <class Epi, class Sched, bool ALIGN_EPI = false, bool SP2 = false>
; __device__ __forceinline__ void gemm_phase(PG8_LAS unsigned char* lds, const Gemm g, const Sched& S, const Epi& E) {
;     ...
;             PG8_LDB(B0, 0, 0); PG8_LDB(B1, 0, 1); PG8_SCHED; PG8_LDA(At, 0, 0); PG8_STAGE(PG8_SA(1, 1), a1 + hstepA, voffA);
;             PG8_WAIT_V(8); PG8_WAIT_L(0); PG8_BAR; PG8_MMA(0, 0, At, B0); PG8_MMA(0, 1, At, B1); PG8_BAR; PG8_SCHED;
;             PG8_LDA(At, 0, 1); PG8_STAGE(PG8_SB(0, 0), b2, voffB); PG8_STAGE(PG8_SB(0, 1), b2 + hstepB, voffB); PG8_STAGE(PG8_SA(0, 0), a2, voffA);
;             PG8_WAIT_V(8); PG8_WAIT_L(0); PG8_BAR; PG8_MMA(1, 0, At, B0); PG8_MMA(1, 1, At, B1); PG8_BAR; PG8_SCHED;
;             PG8_LDB(B0, 1, 0); PG8_LDB(B1, 1, 1); PG8_SCHED; PG8_LDA(At, 1, 0); PG8_STAGE(PG8_SA(0, 1), a2 + hstepA, voffA);
;             PG8_WAIT_V(8); PG8_WAIT_L(0); PG8_BAR; PG8_MMA(0, 0, At, B0); PG8_MMA(0, 1, At, B1); PG8_BAR; PG8_SCHED;
;             PG8_LDA(At, 1, 1); PG8_STAGE(PG8_SB(1, 0), b3, voffB); PG8_STAGE(PG8_SB(1, 1), b3 + hstepB, voffB); PG8_STAGE(PG8_SA(1, 0), a3, voffA);
;             PG8_WAIT_V(8); PG8_WAIT_L(0); PG8_BAR; PG8_MMA(1, 0, At, B0); PG8_MMA(1, 1, At, B1); PG8_BAR; PG8_SCHED;
	v_mfma_f32_16x16x32_bf16 v[60:63], v[128:131], v[202:205], v[60:63]
	v_mfma_f32_16x16x32_bf16 v[56:59], v[136:139], v[202:205], v[56:59]
	v_mfma_f32_16x16x32_bf16 v[52:55], v[128:131], v[210:213], v[52:55]
	v_mfma_f32_16x16x32_bf16 v[48:51], v[136:139], v[210:213], v[48:51]
	v_mfma_f32_16x16x32_bf16 v[44:47], v[128:131], v[218:221], v[44:47]
	v_mfma_f32_16x16x32_bf16 v[40:43], v[136:139], v[218:221], v[40:43]
	v_mfma_f32_16x16x32_bf16 v[36:39], v[128:131], v[226:229], v[36:39]
	v_mfma_f32_16x16x32_bf16 v[32:35], v[136:139], v[226:229], v[32:35]
	v_mfma_f32_16x16x32_bf16 v[60:63], v[132:135], v[206:209], v[60:63]
	v_mfma_f32_16x16x32_bf16 v[56:59], v[140:143], v[206:209], v[56:59]
	v_mfma_f32_16x16x32_bf16 v[52:55], v[132:135], v[214:217], v[52:55]
	v_mfma_f32_16x16x32_bf16 v[48:51], v[140:143], v[214:217], v[48:51]
	v_mfma_f32_16x16x32_bf16 v[44:47], v[132:135], v[222:225], v[44:47]
	v_mfma_f32_16x16x32_bf16 v[40:43], v[140:143], v[222:225], v[40:43]
	v_mfma_f32_16x16x32_bf16 v[36:39], v[132:135], v[230:233], v[36:39]
	v_mfma_f32_16x16x32_bf16 v[32:35], v[140:143], v[230:233], v[32:35]
	s_setprio 0
	s_setprio 1
	v_mfma_f32_16x16x32_bf16 v[28:31], v[174:177], v[202:205], v[28:31]
	v_mfma_f32_16x16x32_bf16 v[24:27], v[194:197], v[202:205], v[24:27]
	v_mfma_f32_16x16x32_bf16 v[20:23], v[174:177], v[210:213], v[20:23]
	v_mfma_f32_16x16x32_bf16 v[16:19], v[194:197], v[210:213], v[16:19]
	v_mfma_f32_16x16x32_bf16 v[12:15], v[174:177], v[218:221], v[12:15]
	v_mfma_f32_16x16x32_bf16 v[8:11], v[194:197], v[218:221], v[8:11]
	v_mfma_f32_16x16x32_bf16 v[4:7], v[174:177], v[226:229], v[4:7]
	v_mfma_f32_16x16x32_bf16 v[0:3], v[194:197], v[226:229], v[0:3]
	v_mfma_f32_16x16x32_bf16 v[28:31], v[190:193], v[206:209], v[28:31]
	v_mfma_f32_16x16x32_bf16 v[24:27], v[198:201], v[206:209], v[24:27]
	v_mfma_f32_16x16x32_bf16 v[20:23], v[190:193], v[214:217], v[20:23]
	v_mfma_f32_16x16x32_bf16 v[16:19], v[198:201], v[214:217], v[16:19]
	v_mfma_f32_16x16x32_bf16 v[12:15], v[190:193], v[222:225], v[12:15]
	v_mfma_f32_16x16x32_bf16 v[8:11], v[198:201], v[222:225], v[8:11]
	v_mfma_f32_16x16x32_bf16 v[4:7], v[190:193], v[230:233], v[4:7]
	v_mfma_f32_16x16x32_bf16 v[0:3], v[198:201], v[230:233], v[0:3]
	s_barrier
	s_setprio 0
	s_add_i32 s6, 0, 0x18000
	s_add_i32 s7, 0, 0x1c000
	v_add_u32_e32 v140, s6, v179
	v_add_u32_e32 v198, s7, v179
	ds_read_b128 v[128:131], v140
	ds_read_b128 v[132:135], v140 offset:1024
	ds_read_b128 v[136:139], v140 offset:2048
	ds_read_b128 v[140:143], v140 offset:3072
	ds_read_b128 v[174:177], v198
	ds_read_b128 v[190:193], v198 offset:1024
	ds_read_b128 v[194:197], v198 offset:2048
	ds_read_b128 v[198:201], v198 offset:3072
	s_add_u32 s4, vcc_lo, 0x80000
	s_addc_u32 s5, vcc_hi, 0
	s_mov_b32 m0, s96
	v_lshl_add_u64 v[240:241], s[4:5], 0, v[144:145]
	ds_read_b128 v[202:205], v181 offset:32768
	ds_read_b128 v[206:209], v181 offset:33792
	ds_read_b128 v[210:213], v181 offset:34816
	ds_read_b128 v[214:217], v181 offset:35840
	ds_read_b128 v[218:221], v181 offset:36864
	ds_read_b128 v[222:225], v181 offset:37888
	ds_read_b128 v[226:229], v181 offset:38912
	ds_read_b128 v[230:233], v181 offset:39936
	global_load_lds_dwordx4 v[240:241], off
	v_lshl_add_u64 v[240:241], s[4:5], 0, v[148:149]
	s_mov_b32 m0, s97
	s_nop 0
	global_load_lds_dwordx4 v[240:241], off
	s_waitcnt vmcnt(8)
	s_waitcnt lgkmcnt(0)
	s_setprio 1
	s_barrier
	v_mfma_f32_16x16x32_bf16 v[124:127], v[128:131], v[202:205], v[124:127]
	v_mfma_f32_16x16x32_bf16 v[120:123], v[136:139], v[202:205], v[120:123]
	v_mfma_f32_16x16x32_bf16 v[116:119], v[128:131], v[210:213], v[116:119]
	v_mfma_f32_16x16x32_bf16 v[112:115], v[136:139], v[210:213], v[112:115]
	v_mfma_f32_16x16x32_bf16 v[108:111], v[128:131], v[218:221], v[108:111]
	v_mfma_f32_16x16x32_bf16 v[104:107], v[136:139], v[218:221], v[104:107]
	v_mfma_f32_16x16x32_bf16 v[100:103], v[128:131], v[226:229], v[100:103]
	v_mfma_f32_16x16x32_bf16 v[96:99], v[136:139], v[226:229], v[96:99]
	v_mfma_f32_16x16x32_bf16 v[124:127], v[132:135], v[206:209], v[124:127]
	v_mfma_f32_16x16x32_bf16 v[120:123], v[140:143], v[206:209], v[120:123]
	v_mfma_f32_16x16x32_bf16 v[116:119], v[132:135], v[214:217], v[116:119]
	v_mfma_f32_16x16x32_bf16 v[112:115], v[140:143], v[214:217], v[112:115]
	v_mfma_f32_16x16x32_bf16 v[108:111], v[132:135], v[222:225], v[108:111]
	v_mfma_f32_16x16x32_bf16 v[104:107], v[140:143], v[222:225], v[104:107]
	v_mfma_f32_16x16x32_bf16 v[100:103], v[132:135], v[230:233], v[100:103]
	v_mfma_f32_16x16x32_bf16 v[96:99], v[140:143], v[230:233], v[96:99]
	s_setprio 0
	s_setprio 1
	v_mfma_f32_16x16x32_bf16 v[92:95], v[174:177], v[202:205], v[92:95]
	v_mfma_f32_16x16x32_bf16 v[88:91], v[194:197], v[202:205], v[88:91]
	v_mfma_f32_16x16x32_bf16 v[84:87], v[174:177], v[210:213], v[84:87]
	v_mfma_f32_16x16x32_bf16 v[80:83], v[194:197], v[210:213], v[80:83]
	v_mfma_f32_16x16x32_bf16 v[76:79], v[174:177], v[218:221], v[76:79]
	v_mfma_f32_16x16x32_bf16 v[72:75], v[194:197], v[218:221], v[72:75]
	v_mfma_f32_16x16x32_bf16 v[68:71], v[174:177], v[226:229], v[68:71]
	v_mfma_f32_16x16x32_bf16 v[64:67], v[194:197], v[226:229], v[64:67]
	v_mfma_f32_16x16x32_bf16 v[92:95], v[190:193], v[206:209], v[92:95]
	v_mfma_f32_16x16x32_bf16 v[88:91], v[198:201], v[206:209], v[88:91]
	v_mfma_f32_16x16x32_bf16 v[84:87], v[190:193], v[214:217], v[84:87]
	v_mfma_f32_16x16x32_bf16 v[80:83], v[198:201], v[214:217], v[80:83]
	v_mfma_f32_16x16x32_bf16 v[76:79], v[190:193], v[222:225], v[76:79]
	v_mfma_f32_16x16x32_bf16 v[72:75], v[198:201], v[222:225], v[72:75]
	v_mfma_f32_16x16x32_bf16 v[68:71], v[190:193], v[230:233], v[68:71]
	v_mfma_f32_16x16x32_bf16 v[64:67], v[198:201], v[230:233], v[64:67]
	s_barrier
; #define PG8_STAGE(bufoff, gbase, voff) do { _Pragma("unroll") for (int _i = 0; _i < 2; ++_i) \
;         __builtin_amdgcn_global_load_lds((const unsigned*)((const char*)(gbase) + (voff)[_i]), (PG8_LAS unsigned*)(lds + (bufoff) + ldsw + _i * 8192), 16, 0, 0); } while (0)
; #define PG8_LDA(dst, b, h) do { _Pragma("unroll") for (int m = 0; m < 4; ++m) _Pragma("unroll") for (int k = 0; k < 2; ++k) dst[m][k] = *(const PG8_LAS bf16x8*)(lds + PG8_SA(b, h) + aoff + m * 2048 + k * 1024); } while (0)
; #define PG8_LDB(dst, b, h) do { _Pragma("unroll") for (int n = 0; n < 2; ++n) _Pragma("unroll") for (int k = 0; k < 2; ++k) dst[n][k] = *(const PG8_LAS bf16x8*)(lds + PG8_SB(b, h) + boff + n * 2048 + k * 1024); } while (0)
; #define PG8_MMA(ai, bj, At, Bt) do { __builtin_amdgcn_s_setprio(1); _Pragma("unroll") for (int m = 0; m < 4; ++m) _Pragma("unroll") for (int n = 0; n < 2; ++n) _Pragma("unroll") for (int k = 0; k < 2; ++k) \
;         acc[ai][bj][m][n] = __builtin_amdgcn_mfma_f32_16x16x32_bf16(Bt[n][k], At[m][k], acc[ai][bj][m][n], 0, 0, 0); __builtin_amdgcn_s_setprio(0); } while (0)
; template <class Epi, class Sched, bool ALIGN_EPI = false, bool SP2 = false>
; __device__ __forceinline__ void gemm_phase(PG8_LAS unsigned char* lds, const Gemm g, const Sched& S, const Epi& E) {
;     ...
;         for (int t = 0; t < nt; t += 2) {
;     ...
;             PG8_LDB(B0, 0, 0); PG8_LDB(B1, 0, 1); PG8_SCHED; PG8_LDA(At, 0, 0); PG8_STAGE(PG8_SA(1, 1), a1 + hstepA, voffA);
;             PG8_WAIT_V(8); PG8_WAIT_L(0); PG8_BAR; PG8_MMA(0, 0, At, B0); PG8_MMA(0, 1, At, B1); PG8_BAR; PG8_SCHED;
;             PG8_LDA(At, 0, 1); PG8_STAGE(PG8_SB(0, 0), b2, voffB); PG8_STAGE(PG8_SB(0, 1), b2 + hstepB, voffB); PG8_STAGE(PG8_SA(0, 0), a2, voffA);
;             PG8_WAIT_V(8); PG8_WAIT_L(0); PG8_BAR; PG8_MMA(1, 0, At, B0); PG8_MMA(1, 1, At, B1); PG8_BAR; PG8_SCHED;
;             PG8_LDB(B0, 1, 0); PG8_LDB(B1, 1, 1); PG8_SCHED; PG8_LDA(At, 1, 0); PG8_STAGE(PG8_SA(0, 1), a2 + hstepA, voffA);
;             PG8_WAIT_V(8); PG8_WAIT_L(0); PG8_BAR; PG8_MMA(0, 0, At, B0); PG8_MMA(0, 1, At, B1); PG8_BAR; PG8_SCHED;
;             PG8_LDA(At, 1, 1); PG8_STAGE(PG8_SB(1, 0), b3, voffB); PG8_STAGE(PG8_SB(1, 1), b3 + hstepB, voffB); PG8_STAGE(PG8_SA(1, 0), a3, voffA);
;             PG8_WAIT_V(8); PG8_WAIT_L(0); PG8_BAR; PG8_MMA(1, 0, At, B0); PG8_MMA(1, 1, At, B1); PG8_BAR; PG8_SCHED;
	s_setprio 0
	s_add_i32 s4, s6, s94
	v_lshl_add_u64 v[182:183], v[182:183], 0, s[70:71]
	s_mov_b32 m0, s4
	ds_read_b128 v[202:205], v181 offset:49152
	ds_read_b128 v[206:209], v181 offset:50176
	ds_read_b128 v[210:213], v181 offset:51200
	ds_read_b128 v[214:217], v181 offset:52224
	ds_read_b128 v[218:221], v181 offset:53248
	ds_read_b128 v[222:225], v181 offset:54272
	ds_read_b128 v[226:229], v181 offset:55296
	ds_read_b128 v[230:233], v181 offset:56320
	global_load_lds_dwordx4 v[182:183], off
	s_add_i32 m0, s4, 0x2000
	s_add_u32 s4, s76, 0x80080
	v_lshl_add_u64 v[182:183], v[234:235], 0, s[70:71]
	s_addc_u32 s5, s77, 0
	s_add_i32 s6, s7, s94
	global_load_lds_dwordx4 v[182:183], off
	v_lshl_add_u64 v[182:183], s[4:5], 0, v[146:147]
	s_mov_b32 m0, s6
	s_nop 0
	global_load_lds_dwordx4 v[182:183], off
	v_lshl_add_u64 v[182:183], s[4:5], 0, v[150:151]
	s_add_i32 m0, s6, 0x2000
	s_nop 0
	global_load_lds_dwordx4 v[182:183], off
	v_lshl_add_u64 v[182:183], v[236:237], 0, s[70:71]
	s_mov_b32 m0, s56
	s_nop 0
	global_load_lds_dwordx4 v[182:183], off
	v_lshl_add_u64 v[182:183], v[238:239], 0, s[70:71]
	s_mov_b32 m0, s57
	s_nop 0
	global_load_lds_dwordx4 v[182:183], off
	s_waitcnt vmcnt(8)
	s_waitcnt lgkmcnt(0)
	s_setprio 1
	s_barrier
	v_mfma_f32_16x16x32_bf16 v[60:63], v[128:131], v[202:205], v[60:63]
	v_mfma_f32_16x16x32_bf16 v[56:59], v[136:139], v[202:205], v[56:59]
	v_mfma_f32_16x16x32_bf16 v[52:55], v[128:131], v[210:213], v[52:55]
	v_mfma_f32_16x16x32_bf16 v[48:51], v[136:139], v[210:213], v[48:51]
	v_mfma_f32_16x16x32_bf16 v[44:47], v[128:131], v[218:221], v[44:47]
	v_mfma_f32_16x16x32_bf16 v[40:43], v[136:139], v[218:221], v[40:43]
	v_mfma_f32_16x16x32_bf16 v[36:39], v[128:131], v[226:229], v[36:39]
	v_mfma_f32_16x16x32_bf16 v[32:35], v[136:139], v[226:229], v[32:35]
	v_mfma_f32_16x16x32_bf16 v[60:63], v[132:135], v[206:209], v[60:63]
	v_mfma_f32_16x16x32_bf16 v[56:59], v[140:143], v[206:209], v[56:59]
	v_mfma_f32_16x16x32_bf16 v[52:55], v[132:135], v[214:217], v[52:55]
	v_mfma_f32_16x16x32_bf16 v[48:51], v[140:143], v[214:217], v[48:51]
	v_mfma_f32_16x16x32_bf16 v[44:47], v[132:135], v[222:225], v[44:47]
	v_mfma_f32_16x16x32_bf16 v[40:43], v[140:143], v[222:225], v[40:43]
	v_mfma_f32_16x16x32_bf16 v[36:39], v[132:135], v[230:233], v[36:39]
	v_mfma_f32_16x16x32_bf16 v[32:35], v[140:143], v[230:233], v[32:35]
	s_setprio 0
	s_setprio 1
	v_mfma_f32_16x16x32_bf16 v[28:31], v[174:177], v[202:205], v[28:31]
	v_mfma_f32_16x16x32_bf16 v[24:27], v[194:197], v[202:205], v[24:27]
	v_mfma_f32_16x16x32_bf16 v[20:23], v[174:177], v[210:213], v[20:23]
	v_mfma_f32_16x16x32_bf16 v[16:19], v[194:197], v[210:213], v[16:19]
	v_mfma_f32_16x16x32_bf16 v[12:15], v[174:177], v[218:221], v[12:15]
	v_mfma_f32_16x16x32_bf16 v[8:11], v[194:197], v[218:221], v[8:11]
	v_mfma_f32_16x16x32_bf16 v[4:7], v[174:177], v[226:229], v[4:7]
	v_mfma_f32_16x16x32_bf16 v[0:3], v[194:197], v[226:229], v[0:3]
	v_mfma_f32_16x16x32_bf16 v[28:31], v[190:193], v[206:209], v[28:31]
	v_mfma_f32_16x16x32_bf16 v[24:27], v[198:201], v[206:209], v[24:27]
	v_mfma_f32_16x16x32_bf16 v[20:23], v[190:193], v[214:217], v[20:23]
	v_mfma_f32_16x16x32_bf16 v[16:19], v[198:201], v[214:217], v[16:19]
	v_mfma_f32_16x16x32_bf16 v[12:15], v[190:193], v[222:225], v[12:15]
	v_mfma_f32_16x16x32_bf16 v[8:11], v[198:201], v[222:225], v[8:11]
	v_mfma_f32_16x16x32_bf16 v[4:7], v[190:193], v[230:233], v[4:7]
	v_mfma_f32_16x16x32_bf16 v[0:3], v[198:201], v[230:233], v[0:3]
	s_barrier
	s_setprio 0
	s_cmp_ge_i32 s66, s44
	s_cbranch_scc1 .LBB0_1066

; #define PG8_STAGE(bufoff, gbase, voff) do { _Pragma("unroll") for (int _i = 0; _i < 2; ++_i) \
;         __builtin_amdgcn_global_load_lds((const unsigned*)((const char*)(gbase) + (voff)[_i]), (PG8_LAS unsigned*)(lds + (bufoff) + ldsw + _i * 8192), 16, 0, 0); } while (0)
; #define PG8_WAIT_V(n) asm volatile("s_waitcnt vmcnt(" #n ")" ::: "memory")
; #define PG8_WAIT_L(n) asm volatile("s_waitcnt lgkmcnt(" #n ")" ::: "memory")
; template <class Epi, class Sched, bool ALIGN_EPI = false, bool SP2 = false>
; __device__ __forceinline__ void gemm_phase(PG8_LAS unsigned char* lds, const Gemm g, const Sched& S, const Epi& E) {
;     ...
;         const char* nA = has_next ? (const char*)g.A + (size_t)nxt.pm * tstepA + (size_t)nxt.z * g.azs + (size_t)(nxt.k0 >> 6) * kstA : cA; const char* nB = has_next ? (const char*)g.Bt + (size_t)nxt.pn * tstepB + (size_t)nxt.z * g.bzs + (size_t)nxt.k0 * 2 : cB;
;         const int nt = cur.nt;
;         for (int t = 0; t < nt; t += 2) {
;             const bool last = (t == nt - 2);
;             const char* a1 = cA + (size_t)(t + 1) * kstA;
;             const char* a2 = last ? nA : cA + (size_t)(t + 2) * kstA; const char* b2 = last ? nB : cB + (size_t)(t + 2) * kstep;
;             const char* a3 = a2 + kstA; const char* b3 = b2 + kstep;
;             if (last && has_next) S.a_ready(nxt);
;             if constexpr (SP2) {
;             PG8_LDB(B0, 0, 0); PG8_LDB(B1, 0, 1); PG8_SCHED; PG8_LDA(At, 0, 0); PG8_STAGE(PG8_SA(1, 1), a1 + hstepA, voffA);
;             PG8_WAIT_V(8); PG8_WAIT_L(0); PG8_BAR; PG8_MMA(0, 0, At, B0); PG8_MMA(0, 1, At, B1); PG8_BAR; PG8_SCHED;
;             PG8_LDA(At, 0, 1); PG8_STAGE(PG8_SB(0, 0), b2, voffB); PG8_STAGE(PG8_SB(0, 1), b2 + hstepB, voffB); PG8_STAGE(PG8_SA(0, 0), a2, voffA);
;             PG8_WAIT_V(8); PG8_WAIT_L(0); PG8_BAR; PG8_MMA(1, 0, At, B0); PG8_MMA(1, 1, At, B1); PG8_BAR; PG8_SCHED;
;             PG8_LDB(B0, 1, 0); PG8_LDB(B1, 1, 1); PG8_SCHED; PG8_LDA(At, 1, 0); PG8_STAGE(PG8_SA(0, 1), a2 + hstepA, voffA);
;             PG8_WAIT_V(8); PG8_WAIT_L(0); PG8_BAR; PG8_MMA(0, 0, At, B0); PG8_MMA(0, 1, At, B1); PG8_BAR; PG8_SCHED;
;             PG8_LDA(At, 1, 1); PG8_STAGE(PG8_SB(1, 0), b3, voffB); PG8_STAGE(PG8_SB(1, 1), b3 + hstepB, voffB); PG8_STAGE(PG8_SA(1, 0), a3, voffA);
;             PG8_WAIT_V(8); PG8_WAIT_L(0); PG8_BAR; PG8_MMA(1, 0, At, B0); PG8_MMA(1, 1, At, B1); PG8_BAR; PG8_SCHED;
.LBB0_1307:
	ds_read_b128 v[156:159], v152
	ds_read_b128 v[160:163], v152 offset:1024
	ds_read_b128 v[164:167], v152 offset:2048
	ds_read_b128 v[168:171], v152 offset:3072
	ds_read_b128 v[172:175], v153
	ds_read_b128 v[176:179], v153 offset:1024
	ds_read_b128 v[180:183], v153 offset:2048
	ds_read_b128 v[190:193], v153 offset:3072
	s_add_u32 s52, s50, 0xfff80080
	s_addc_u32 s53, s51, -1
	s_cmp_eq_u32 s63, 28
	s_cselect_b32 s59, s4, s53
	s_cselect_b32 s58, s5, s52
	s_cselect_b32 s53, s12, s41
	s_cselect_b32 s52, s13, s39
	v_lshl_add_u64 v[226:227], s[50:51], 0, v[142:143]
	s_add_i32 m0, s7, 0xc000
	ds_read_b128 v[194:197], v154
	ds_read_b128 v[198:201], v154 offset:1024
	ds_read_b128 v[202:205], v154 offset:2048
	ds_read_b128 v[206:209], v154 offset:3072
	ds_read_b128 v[210:213], v154 offset:4096
	ds_read_b128 v[214:217], v154 offset:5120
	ds_read_b128 v[218:221], v154 offset:6144
	ds_read_b128 v[222:225], v154 offset:7168
	global_load_lds_dwordx4 v[226:227], off
	v_lshl_add_u64 v[226:227], s[50:51], 0, v[144:145]
	s_add_i32 m0, s7, 0xe000
	s_nop 0
	global_load_lds_dwordx4 v[226:227], off
	s_waitcnt vmcnt(8)
	s_waitcnt lgkmcnt(0)
	s_setprio 1
	s_barrier
	v_mfma_f32_16x16x32_bf16 v[124:127], v[156:159], v[194:197], v[124:127]
	v_mfma_f32_16x16x32_bf16 v[120:123], v[164:167], v[194:197], v[120:123]
	v_mfma_f32_16x16x32_bf16 v[108:111], v[156:159], v[202:205], v[108:111]
	v_mfma_f32_16x16x32_bf16 v[104:107], v[164:167], v[202:205], v[104:107]
	v_mfma_f32_16x16x32_bf16 v[92:95], v[156:159], v[210:213], v[92:95]
	v_mfma_f32_16x16x32_bf16 v[88:91], v[164:167], v[210:213], v[88:91]
	v_mfma_f32_16x16x32_bf16 v[76:79], v[156:159], v[218:221], v[76:79]
	v_mfma_f32_16x16x32_bf16 v[72:75], v[164:167], v[218:221], v[72:75]
	v_mfma_f32_16x16x32_bf16 v[124:127], v[160:163], v[198:201], v[124:127]
	v_mfma_f32_16x16x32_bf16 v[120:123], v[168:171], v[198:201], v[120:123]
	v_mfma_f32_16x16x32_bf16 v[108:111], v[160:163], v[206:209], v[108:111]
	v_mfma_f32_16x16x32_bf16 v[104:107], v[168:171], v[206:209], v[104:107]
	v_mfma_f32_16x16x32_bf16 v[92:95], v[160:163], v[214:217], v[92:95]
	v_mfma_f32_16x16x32_bf16 v[88:91], v[168:171], v[214:217], v[88:91]
	v_mfma_f32_16x16x32_bf16 v[76:79], v[160:163], v[222:225], v[76:79]
	v_mfma_f32_16x16x32_bf16 v[72:75], v[168:171], v[222:225], v[72:75]
	s_setprio 0
	s_setprio 1
	v_mfma_f32_16x16x32_bf16 v[116:119], v[172:175], v[194:197], v[116:119]
	v_mfma_f32_16x16x32_bf16 v[112:115], v[180:183], v[194:197], v[112:115]
	v_mfma_f32_16x16x32_bf16 v[100:103], v[172:175], v[202:205], v[100:103]
	v_mfma_f32_16x16x32_bf16 v[96:99], v[180:183], v[202:205], v[96:99]
	v_mfma_f32_16x16x32_bf16 v[84:87], v[172:175], v[210:213], v[84:87]
	v_mfma_f32_16x16x32_bf16 v[80:83], v[180:183], v[210:213], v[80:83]
	v_mfma_f32_16x16x32_bf16 v[68:71], v[172:175], v[218:221], v[68:71]
	v_mfma_f32_16x16x32_bf16 v[64:67], v[180:183], v[218:221], v[64:67]
	v_mfma_f32_16x16x32_bf16 v[116:119], v[176:179], v[198:201], v[116:119]
	v_mfma_f32_16x16x32_bf16 v[112:115], v[190:193], v[198:201], v[112:115]
	v_mfma_f32_16x16x32_bf16 v[100:103], v[176:179], v[206:209], v[100:103]
	v_mfma_f32_16x16x32_bf16 v[96:99], v[190:193], v[206:209], v[96:99]
	v_mfma_f32_16x16x32_bf16 v[84:87], v[176:179], v[214:217], v[84:87]
	v_mfma_f32_16x16x32_bf16 v[80:83], v[190:193], v[214:217], v[80:83]
	v_mfma_f32_16x16x32_bf16 v[68:71], v[176:179], v[222:225], v[68:71]
	v_mfma_f32_16x16x32_bf16 v[64:67], v[190:193], v[222:225], v[64:67]
	s_barrier
	s_setprio 0
	s_add_i32 s64, s57, s6
	v_lshl_add_u64 v[226:227], s[52:53], 0, v[130:131]
	s_mov_b32 m0, s64
	ds_read_b128 v[194:197], v154 offset:16384
	ds_read_b128 v[198:201], v154 offset:17408
	ds_read_b128 v[202:205], v154 offset:18432
	ds_read_b128 v[206:209], v154 offset:19456
	ds_read_b128 v[210:213], v154 offset:20480
	ds_read_b128 v[214:217], v154 offset:21504
	ds_read_b128 v[218:221], v154 offset:22528
	ds_read_b128 v[222:225], v154 offset:23552
	global_load_lds_dwordx4 v[226:227], off
	s_add_i32 m0, s64, 0x2000
	s_add_u32 s64, s52, 0x80000
	v_lshl_add_u64 v[228:229], s[52:53], 0, v[134:135]
	s_addc_u32 s65, s53, 0
	s_add_i32 s66, s61, s6
	global_load_lds_dwordx4 v[228:229], off
	v_lshl_add_u64 v[230:231], s[64:65], 0, v[130:131]
	s_mov_b32 m0, s66
	v_lshl_add_u64 v[232:233], s[58:59], 0, v[132:133]
	global_load_lds_dwordx4 v[230:231], off
	v_lshl_add_u64 v[230:231], s[64:65], 0, v[134:135]
	s_add_i32 m0, s66, 0x2000
	s_nop 0
	global_load_lds_dwordx4 v[230:231], off
	v_lshl_add_u64 v[230:231], s[58:59], 0, v[128:129]
	s_mov_b32 m0, s7
	s_nop 0
	global_load_lds_dwordx4 v[230:231], off
	s_mov_b32 m0, s8
	s_nop 0
	global_load_lds_dwordx4 v[232:233], off
	s_waitcnt vmcnt(8)
	s_waitcnt lgkmcnt(0)
	s_setprio 1
	s_barrier
; #define PG8_STAGE(bufoff, gbase, voff) do { _Pragma("unroll") for (int _i = 0; _i < 2; ++_i) \
;         __builtin_amdgcn_global_load_lds((const unsigned*)((const char*)(gbase) + (voff)[_i]), (PG8_LAS unsigned*)(lds + (bufoff) + ldsw + _i * 8192), 16, 0, 0); } while (0)
; #define PG8_LDA(dst, b, h) do { _Pragma("unroll") for (int m = 0; m < 4; ++m) _Pragma("unroll") for (int k = 0; k < 2; ++k) dst[m][k] = *(const PG8_LAS bf16x8*)(lds + PG8_SA(b, h) + aoff + m * 2048 + k * 1024); } while (0)
; #define PG8_LDB(dst, b, h) do { _Pragma("unroll") for (int n = 0; n < 2; ++n) _Pragma("unroll") for (int k = 0; k < 2; ++k) dst[n][k] = *(const PG8_LAS bf16x8*)(lds + PG8_SB(b, h) + boff + n * 2048 + k * 1024); } while (0)
; #define PG8_MMA(ai, bj, At, Bt) do { __builtin_amdgcn_s_setprio(1); _Pragma("unroll") for (int m = 0; m < 4; ++m) _Pragma("unroll") for (int n = 0; n < 2; ++n) _Pragma("unroll") for (int k = 0; k < 2; ++k) \
;         acc[ai][bj][m][n] = __builtin_amdgcn_mfma_f32_16x16x32_bf16(Bt[n][k], At[m][k], acc[ai][bj][m][n], 0, 0, 0); __builtin_amdgcn_s_setprio(0); } while (0)
; #define PG8_WAIT_V(n) asm volatile("s_waitcnt vmcnt(" #n ")" ::: "memory")
; template <class Epi, class Sched, bool ALIGN_EPI = false, bool SP2 = false>
; __device__ __forceinline__ void gemm_phase(PG8_LAS unsigned char* lds, const Gemm g, const Sched& S, const Epi& E) {
;     ...
;             PG8_LDB(B0, 0, 0); PG8_LDB(B1, 0, 1); PG8_SCHED; PG8_LDA(At, 0, 0); PG8_STAGE(PG8_SA(1, 1), a1 + hstepA, voffA);
;             PG8_WAIT_V(8); PG8_WAIT_L(0); PG8_BAR; PG8_MMA(0, 0, At, B0); PG8_MMA(0, 1, At, B1); PG8_BAR; PG8_SCHED;
;             PG8_LDA(At, 0, 1); PG8_STAGE(PG8_SB(0, 0), b2, voffB); PG8_STAGE(PG8_SB(0, 1), b2 + hstepB, voffB); PG8_STAGE(PG8_SA(0, 0), a2, voffA);
;             PG8_WAIT_V(8); PG8_WAIT_L(0); PG8_BAR; PG8_MMA(1, 0, At, B0); PG8_MMA(1, 1, At, B1); PG8_BAR; PG8_SCHED;
;             PG8_LDB(B0, 1, 0); PG8_LDB(B1, 1, 1); PG8_SCHED; PG8_LDA(At, 1, 0); PG8_STAGE(PG8_SA(0, 1), a2 + hstepA, voffA);
;             PG8_WAIT_V(8); PG8_WAIT_L(0); PG8_BAR; PG8_MMA(0, 0, At, B0); PG8_MMA(0, 1, At, B1); PG8_BAR; PG8_SCHED;
;             PG8_LDA(At, 1, 1); PG8_STAGE(PG8_SB(1, 0), b3, voffB); PG8_STAGE(PG8_SB(1, 1), b3 + hstepB, voffB); PG8_STAGE(PG8_SA(1, 0), a3, voffA);
;             PG8_WAIT_V(8); PG8_WAIT_L(0); PG8_BAR; PG8_MMA(1, 0, At, B0); PG8_MMA(1, 1, At, B1); PG8_BAR; PG8_SCHED;
	v_mfma_f32_16x16x32_bf16 v[60:63], v[156:159], v[194:197], v[60:63]
	v_mfma_f32_16x16x32_bf16 v[56:59], v[164:167], v[194:197], v[56:59]
	v_mfma_f32_16x16x32_bf16 v[44:47], v[156:159], v[202:205], v[44:47]
	v_mfma_f32_16x16x32_bf16 v[40:43], v[164:167], v[202:205], v[40:43]
	v_mfma_f32_16x16x32_bf16 v[28:31], v[156:159], v[210:213], v[28:31]
	v_mfma_f32_16x16x32_bf16 v[24:27], v[164:167], v[210:213], v[24:27]
	v_mfma_f32_16x16x32_bf16 v[12:15], v[156:159], v[218:221], v[12:15]
	v_mfma_f32_16x16x32_bf16 v[8:11], v[164:167], v[218:221], v[8:11]
	v_mfma_f32_16x16x32_bf16 v[60:63], v[160:163], v[198:201], v[60:63]
	v_mfma_f32_16x16x32_bf16 v[56:59], v[168:171], v[198:201], v[56:59]
	v_mfma_f32_16x16x32_bf16 v[44:47], v[160:163], v[206:209], v[44:47]
	v_mfma_f32_16x16x32_bf16 v[40:43], v[168:171], v[206:209], v[40:43]
	v_mfma_f32_16x16x32_bf16 v[28:31], v[160:163], v[214:217], v[28:31]
	v_mfma_f32_16x16x32_bf16 v[24:27], v[168:171], v[214:217], v[24:27]
	v_mfma_f32_16x16x32_bf16 v[12:15], v[160:163], v[222:225], v[12:15]
	v_mfma_f32_16x16x32_bf16 v[8:11], v[168:171], v[222:225], v[8:11]
	s_setprio 0
	s_setprio 1
	v_mfma_f32_16x16x32_bf16 v[52:55], v[172:175], v[194:197], v[52:55]
	v_mfma_f32_16x16x32_bf16 v[48:51], v[180:183], v[194:197], v[48:51]
	v_mfma_f32_16x16x32_bf16 v[36:39], v[172:175], v[202:205], v[36:39]
	v_mfma_f32_16x16x32_bf16 v[32:35], v[180:183], v[202:205], v[32:35]
	v_mfma_f32_16x16x32_bf16 v[20:23], v[172:175], v[210:213], v[20:23]
	v_mfma_f32_16x16x32_bf16 v[16:19], v[180:183], v[210:213], v[16:19]
	v_mfma_f32_16x16x32_bf16 v[4:7], v[172:175], v[218:221], v[4:7]
	v_mfma_f32_16x16x32_bf16 v[0:3], v[180:183], v[218:221], v[0:3]
	v_mfma_f32_16x16x32_bf16 v[52:55], v[176:179], v[198:201], v[52:55]
	v_mfma_f32_16x16x32_bf16 v[48:51], v[190:193], v[198:201], v[48:51]
	v_mfma_f32_16x16x32_bf16 v[36:39], v[176:179], v[206:209], v[36:39]
	v_mfma_f32_16x16x32_bf16 v[32:35], v[190:193], v[206:209], v[32:35]
	v_mfma_f32_16x16x32_bf16 v[20:23], v[176:179], v[214:217], v[20:23]
	v_mfma_f32_16x16x32_bf16 v[16:19], v[190:193], v[214:217], v[16:19]
	v_mfma_f32_16x16x32_bf16 v[4:7], v[176:179], v[222:225], v[4:7]
	v_mfma_f32_16x16x32_bf16 v[0:3], v[190:193], v[222:225], v[0:3]
	s_barrier
	s_setprio 0
	s_add_i32 s64, 0, 0x18000
	v_add_u32_e32 v155, s64, v150
	s_add_i32 s65, 0, 0x1c000
	ds_read_b128 v[156:159], v155
	ds_read_b128 v[160:163], v155 offset:1024
	ds_read_b128 v[164:167], v155 offset:2048
	ds_read_b128 v[168:171], v155 offset:3072
	v_add_u32_e32 v155, s65, v150
	ds_read_b128 v[172:175], v155
	ds_read_b128 v[176:179], v155 offset:1024
	ds_read_b128 v[180:183], v155 offset:2048
	ds_read_b128 v[190:193], v155 offset:3072
	s_add_u32 s58, s58, 0x80000
	s_addc_u32 s59, s59, 0
	s_mov_b32 m0, s9
	v_lshl_add_u64 v[234:235], s[58:59], 0, v[128:129]
	ds_read_b128 v[194:197], v154 offset:32768
	ds_read_b128 v[198:201], v154 offset:33792
	ds_read_b128 v[202:205], v154 offset:34816
	ds_read_b128 v[206:209], v154 offset:35840
	ds_read_b128 v[210:213], v154 offset:36864
	ds_read_b128 v[214:217], v154 offset:37888
	ds_read_b128 v[218:221], v154 offset:38912
	ds_read_b128 v[222:225], v154 offset:39936
	global_load_lds_dwordx4 v[234:235], off
	v_lshl_add_u64 v[234:235], s[58:59], 0, v[132:133]
	s_mov_b32 m0, s11
	s_nop 0
	global_load_lds_dwordx4 v[234:235], off
	s_waitcnt vmcnt(8)
	s_waitcnt lgkmcnt(0)
	s_setprio 1
	s_barrier
	v_mfma_f32_16x16x32_bf16 v[124:127], v[156:159], v[194:197], v[124:127]
	v_mfma_f32_16x16x32_bf16 v[120:123], v[164:167], v[194:197], v[120:123]
	v_mfma_f32_16x16x32_bf16 v[108:111], v[156:159], v[202:205], v[108:111]
	v_mfma_f32_16x16x32_bf16 v[104:107], v[164:167], v[202:205], v[104:107]
	v_mfma_f32_16x16x32_bf16 v[92:95], v[156:159], v[210:213], v[92:95]
	v_mfma_f32_16x16x32_bf16 v[88:91], v[164:167], v[210:213], v[88:91]
	v_mfma_f32_16x16x32_bf16 v[76:79], v[156:159], v[218:221], v[76:79]
	v_mfma_f32_16x16x32_bf16 v[72:75], v[164:167], v[218:221], v[72:75]
	v_mfma_f32_16x16x32_bf16 v[124:127], v[160:163], v[198:201], v[124:127]
	v_mfma_f32_16x16x32_bf16 v[120:123], v[168:171], v[198:201], v[120:123]
	v_mfma_f32_16x16x32_bf16 v[108:111], v[160:163], v[206:209], v[108:111]
	v_mfma_f32_16x16x32_bf16 v[104:107], v[168:171], v[206:209], v[104:107]
	v_mfma_f32_16x16x32_bf16 v[92:95], v[160:163], v[214:217], v[92:95]
	v_mfma_f32_16x16x32_bf16 v[88:91], v[168:171], v[214:217], v[88:91]
	v_mfma_f32_16x16x32_bf16 v[76:79], v[160:163], v[222:225], v[76:79]
	v_mfma_f32_16x16x32_bf16 v[72:75], v[168:171], v[222:225], v[72:75]
	s_setprio 0
	s_setprio 1
	v_mfma_f32_16x16x32_bf16 v[116:119], v[172:175], v[194:197], v[116:119]
	v_mfma_f32_16x16x32_bf16 v[112:115], v[180:183], v[194:197], v[112:115]
	v_mfma_f32_16x16x32_bf16 v[100:103], v[172:175], v[202:205], v[100:103]
	v_mfma_f32_16x16x32_bf16 v[96:99], v[180:183], v[202:205], v[96:99]
	v_mfma_f32_16x16x32_bf16 v[84:87], v[172:175], v[210:213], v[84:87]
	v_mfma_f32_16x16x32_bf16 v[80:83], v[180:183], v[210:213], v[80:83]
	v_mfma_f32_16x16x32_bf16 v[68:71], v[172:175], v[218:221], v[68:71]
	v_mfma_f32_16x16x32_bf16 v[64:67], v[180:183], v[218:221], v[64:67]
	v_mfma_f32_16x16x32_bf16 v[116:119], v[176:179], v[198:201], v[116:119]
	v_mfma_f32_16x16x32_bf16 v[112:115], v[190:193], v[198:201], v[112:115]
	v_mfma_f32_16x16x32_bf16 v[100:103], v[176:179], v[206:209], v[100:103]
	v_mfma_f32_16x16x32_bf16 v[96:99], v[190:193], v[206:209], v[96:99]
	v_mfma_f32_16x16x32_bf16 v[84:87], v[176:179], v[214:217], v[84:87]
	v_mfma_f32_16x16x32_bf16 v[80:83], v[190:193], v[214:217], v[80:83]
	v_mfma_f32_16x16x32_bf16 v[68:71], v[176:179], v[222:225], v[68:71]
	v_mfma_f32_16x16x32_bf16 v[64:67], v[190:193], v[222:225], v[64:67]
	s_barrier
; #define PG8_STAGE(bufoff, gbase, voff) do { _Pragma("unroll") for (int _i = 0; _i < 2; ++_i) \
;         __builtin_amdgcn_global_load_lds((const unsigned*)((const char*)(gbase) + (voff)[_i]), (PG8_LAS unsigned*)(lds + (bufoff) + ldsw + _i * 8192), 16, 0, 0); } while (0)
; #define PG8_LDA(dst, b, h) do { _Pragma("unroll") for (int m = 0; m < 4; ++m) _Pragma("unroll") for (int k = 0; k < 2; ++k) dst[m][k] = *(const PG8_LAS bf16x8*)(lds + PG8_SA(b, h) + aoff + m * 2048 + k * 1024); } while (0)
; #define PG8_MMA(ai, bj, At, Bt) do { __builtin_amdgcn_s_setprio(1); _Pragma("unroll") for (int m = 0; m < 4; ++m) _Pragma("unroll") for (int n = 0; n < 2; ++n) _Pragma("unroll") for (int k = 0; k < 2; ++k) \
;         acc[ai][bj][m][n] = __builtin_amdgcn_mfma_f32_16x16x32_bf16(Bt[n][k], At[m][k], acc[ai][bj][m][n], 0, 0, 0); __builtin_amdgcn_s_setprio(0); } while (0)
; #define PG8_WAIT_V(n) asm volatile("s_waitcnt vmcnt(" #n ")" ::: "memory")
; #define PG8_WAIT_L(n) asm volatile("s_waitcnt lgkmcnt(" #n ")" ::: "memory")
; #define PG8_BAR __builtin_amdgcn_s_barrier()
; #define PG8_SCHED __builtin_amdgcn_sched_barrier(0)
; template <class Epi, class Sched, bool ALIGN_EPI = false, bool SP2 = false>
; __device__ __forceinline__ void gemm_phase(PG8_LAS unsigned char* lds, const Gemm g, const Sched& S, const Epi& E) {
;     ...
;             PG8_LDA(At, 1, 1); PG8_STAGE(PG8_SB(1, 0), b3, voffB); PG8_STAGE(PG8_SB(1, 1), b3 + hstepB, voffB); PG8_STAGE(PG8_SA(1, 0), a3, voffA);
;             PG8_WAIT_V(8); PG8_WAIT_L(0); PG8_BAR; PG8_MMA(1, 0, At, B0); PG8_MMA(1, 1, At, B1); PG8_BAR; PG8_SCHED;
;     ...
;         if constexpr (ALIGN_EPI) { if (wr == 0) PG8_BAR; }
	s_setprio 0
	s_add_i32 s58, s64, s6
	v_lshl_add_u64 v[226:227], v[226:227], 0, s[20:21]
	s_mov_b32 m0, s58
	ds_read_b128 v[194:197], v154 offset:49152
	ds_read_b128 v[198:201], v154 offset:50176
	ds_read_b128 v[202:205], v154 offset:51200
	ds_read_b128 v[206:209], v154 offset:52224
	ds_read_b128 v[210:213], v154 offset:53248
	ds_read_b128 v[214:217], v154 offset:54272
	ds_read_b128 v[218:221], v154 offset:55296
	ds_read_b128 v[222:225], v154 offset:56320
	global_load_lds_dwordx4 v[226:227], off
	s_add_i32 m0, s58, 0x2000
	s_add_u32 s52, s52, 0x80080
	v_lshl_add_u64 v[226:227], v[228:229], 0, s[20:21]
	s_addc_u32 s53, s53, 0
	s_add_i32 s58, s65, s6
	global_load_lds_dwordx4 v[226:227], off
	v_lshl_add_u64 v[226:227], s[52:53], 0, v[130:131]
	s_mov_b32 m0, s58
	s_nop 0
	global_load_lds_dwordx4 v[226:227], off
	v_lshl_add_u64 v[226:227], s[52:53], 0, v[134:135]
	s_add_i32 m0, s58, 0x2000
	s_nop 0
	global_load_lds_dwordx4 v[226:227], off
	v_lshl_add_u64 v[226:227], v[230:231], 0, s[20:21]
	s_mov_b32 m0, s55
	s_nop 0
	global_load_lds_dwordx4 v[226:227], off
	v_lshl_add_u64 v[226:227], v[232:233], 0, s[20:21]
	s_mov_b32 m0, s56
	s_nop 0
	global_load_lds_dwordx4 v[226:227], off
	s_waitcnt vmcnt(8)
	s_waitcnt lgkmcnt(0)
	s_setprio 1
	s_barrier
	v_mfma_f32_16x16x32_bf16 v[60:63], v[156:159], v[194:197], v[60:63]
	v_mfma_f32_16x16x32_bf16 v[56:59], v[164:167], v[194:197], v[56:59]
	v_mfma_f32_16x16x32_bf16 v[44:47], v[156:159], v[202:205], v[44:47]
	v_mfma_f32_16x16x32_bf16 v[40:43], v[164:167], v[202:205], v[40:43]
	v_mfma_f32_16x16x32_bf16 v[28:31], v[156:159], v[210:213], v[28:31]
	v_mfma_f32_16x16x32_bf16 v[24:27], v[164:167], v[210:213], v[24:27]
	v_mfma_f32_16x16x32_bf16 v[12:15], v[156:159], v[218:221], v[12:15]
	v_mfma_f32_16x16x32_bf16 v[8:11], v[164:167], v[218:221], v[8:11]
	v_mfma_f32_16x16x32_bf16 v[60:63], v[160:163], v[198:201], v[60:63]
	v_mfma_f32_16x16x32_bf16 v[56:59], v[168:171], v[198:201], v[56:59]
	v_mfma_f32_16x16x32_bf16 v[44:47], v[160:163], v[206:209], v[44:47]
	v_mfma_f32_16x16x32_bf16 v[40:43], v[168:171], v[206:209], v[40:43]
	v_mfma_f32_16x16x32_bf16 v[28:31], v[160:163], v[214:217], v[28:31]
	v_mfma_f32_16x16x32_bf16 v[24:27], v[168:171], v[214:217], v[24:27]
	v_mfma_f32_16x16x32_bf16 v[12:15], v[160:163], v[222:225], v[12:15]
	v_mfma_f32_16x16x32_bf16 v[8:11], v[168:171], v[222:225], v[8:11]
	s_setprio 0
	s_setprio 1
	v_mfma_f32_16x16x32_bf16 v[52:55], v[172:175], v[194:197], v[52:55]
	v_mfma_f32_16x16x32_bf16 v[48:51], v[180:183], v[194:197], v[48:51]
	v_mfma_f32_16x16x32_bf16 v[36:39], v[172:175], v[202:205], v[36:39]
	v_mfma_f32_16x16x32_bf16 v[32:35], v[180:183], v[202:205], v[32:35]
	v_mfma_f32_16x16x32_bf16 v[20:23], v[172:175], v[210:213], v[20:23]
	v_mfma_f32_16x16x32_bf16 v[16:19], v[180:183], v[210:213], v[16:19]
	v_mfma_f32_16x16x32_bf16 v[4:7], v[172:175], v[218:221], v[4:7]
	v_mfma_f32_16x16x32_bf16 v[0:3], v[180:183], v[218:221], v[0:3]
	v_mfma_f32_16x16x32_bf16 v[52:55], v[176:179], v[198:201], v[52:55]
	v_mfma_f32_16x16x32_bf16 v[48:51], v[190:193], v[198:201], v[48:51]
	v_mfma_f32_16x16x32_bf16 v[36:39], v[176:179], v[206:209], v[36:39]
	v_mfma_f32_16x16x32_bf16 v[32:35], v[190:193], v[206:209], v[32:35]
	v_mfma_f32_16x16x32_bf16 v[20:23], v[176:179], v[214:217], v[20:23]
	v_mfma_f32_16x16x32_bf16 v[16:19], v[190:193], v[214:217], v[16:19]
	v_mfma_f32_16x16x32_bf16 v[4:7], v[176:179], v[222:225], v[4:7]
	v_mfma_f32_16x16x32_bf16 v[0:3], v[190:193], v[222:225], v[0:3]
	s_barrier
	s_setprio 0
	s_add_i32 s63, s63, 2
	s_add_u32 s50, s50, 0x100
	s_addc_u32 s51, s51, 0
	s_add_u32 s39, s39, 0x100
	s_addc_u32 s41, s41, 0
	s_cmp_gt_u32 s63, 29
	s_cbranch_scc0 .LBB0_1307
	s_and_b64 vcc, exec, s[34:35]
	s_cbranch_vccz .LBB0_1310
	s_barrier

; #define PG8_STAGE(bufoff, gbase, voff) do { _Pragma("unroll") for (int _i = 0; _i < 2; ++_i) \
;         __builtin_amdgcn_global_load_lds((const unsigned*)((const char*)(gbase) + (voff)[_i]), (PG8_LAS unsigned*)(lds + (bufoff) + ldsw + _i * 8192), 16, 0, 0); } while (0)
; #define PG8_LDA(dst, b, h) do { _Pragma("unroll") for (int m = 0; m < 4; ++m) _Pragma("unroll") for (int k = 0; k < 2; ++k) dst[m][k] = *(const PG8_LAS bf16x8*)(lds + PG8_SA(b, h) + aoff + m * 2048 + k * 1024); } while (0)
; #define PG8_LDB(dst, b, h) do { _Pragma("unroll") for (int n = 0; n < 2; ++n) _Pragma("unroll") for (int k = 0; k < 2; ++k) dst[n][k] = *(const PG8_LAS bf16x8*)(lds + PG8_SB(b, h) + boff + n * 2048 + k * 1024); } while (0)
; #define PG8_MMA(ai, bj, At, Bt) do { __builtin_amdgcn_s_setprio(1); _Pragma("unroll") for (int m = 0; m < 4; ++m) _Pragma("unroll") for (int n = 0; n < 2; ++n) _Pragma("unroll") for (int k = 0; k < 2; ++k) \
;         acc[ai][bj][m][n] = __builtin_amdgcn_mfma_f32_16x16x32_bf16(Bt[n][k], At[m][k], acc[ai][bj][m][n], 0, 0, 0); __builtin_amdgcn_s_setprio(0); } while (0)
; #define PG8_WAIT_V(n) asm volatile("s_waitcnt vmcnt(" #n ")" ::: "memory")
; #define PG8_BAR __builtin_amdgcn_s_barrier()
; template <class Epi, class Sched, bool ALIGN_EPI = false, bool SP2 = false>
; __device__ __forceinline__ void gemm_phase(PG8_LAS unsigned char* lds, const Gemm g, const Sched& S, const Epi& E) {
;     ...
;         for (int t = 0; t < nt; t += 2) {
;             const bool last = (t == nt - 2);
;             const char* a1 = cA + (size_t)(t + 1) * kstA;
;             const char* a2 = last ? nA : cA + (size_t)(t + 2) * kstA; const char* b2 = last ? nB : cB + (size_t)(t + 2) * kstep;
;             const char* a3 = a2 + kstA; const char* b3 = b2 + kstep;
;             if (last && has_next) S.a_ready(nxt);
;             if constexpr (SP2) {
;             PG8_LDB(B0, 0, 0); PG8_LDB(B1, 0, 1); PG8_SCHED; PG8_LDA(At, 0, 0); PG8_STAGE(PG8_SA(1, 1), a1 + hstepA, voffA);
;             PG8_WAIT_V(8); PG8_WAIT_L(0); PG8_BAR; PG8_MMA(0, 0, At, B0); PG8_MMA(0, 1, At, B1); PG8_BAR; PG8_SCHED;
;             PG8_LDA(At, 0, 1); PG8_STAGE(PG8_SB(0, 0), b2, voffB); PG8_STAGE(PG8_SB(0, 1), b2 + hstepB, voffB); PG8_STAGE(PG8_SA(0, 0), a2, voffA);
;             PG8_WAIT_V(8); PG8_WAIT_L(0); PG8_BAR; PG8_MMA(1, 0, At, B0); PG8_MMA(1, 1, At, B1); PG8_BAR; PG8_SCHED;
.LBB0_1404:
	s_or_b32 s48, s68, 1
	s_add_i32 s68, s68, 2
	s_mov_b32 s69, s49
	s_lshl_b64 s[4:5], s[48:49], 15
	s_lshl_b64 s[6:7], s[68:69], 15
	s_add_u32 s12, s34, s6
	v_add_u32_e32 v170, s10, v177
	v_add_u32_e32 v174, s11, v177
	s_addc_u32 s13, s35, s7
	ds_read_b128 v[158:161], v170
	ds_read_b128 v[162:165], v170 offset:1024
	ds_read_b128 v[166:169], v170 offset:2048
	ds_read_b128 v[170:173], v170 offset:3072
	ds_read_b128 v[180:183], v174
	ds_read_b128 v[190:193], v174 offset:1024
	ds_read_b128 v[194:197], v174 offset:2048
	ds_read_b128 v[198:201], v174 offset:3072
	s_and_b64 s[6:7], s[50:51], exec
	s_cselect_b32 s59, s13, s61
	s_cselect_b32 s58, s12, s60
	s_lshl_b64 s[6:7], s[68:69], 7
	s_add_u32 s12, s40, s6
	s_addc_u32 s13, s41, s7
	s_and_b64 s[6:7], s[50:51], exec
	s_cselect_b32 s53, s13, s63
	s_cselect_b32 s52, s12, s62
	s_add_u32 s50, s58, 0x8000
	s_addc_u32 s51, s59, 0
	s_add_u32 s4, s21, s4
	s_addc_u32 s5, s39, s5
	v_lshl_add_u64 v[174:175], s[4:5], 0, v[128:129]
	s_add_i32 m0, s74, 0xc000
	ds_read_b128 v[202:205], v179
	ds_read_b128 v[206:209], v179 offset:1024
	ds_read_b128 v[210:213], v179 offset:2048
	ds_read_b128 v[214:217], v179 offset:3072
	ds_read_b128 v[218:221], v179 offset:4096
	ds_read_b128 v[222:225], v179 offset:5120
	ds_read_b128 v[226:229], v179 offset:6144
	ds_read_b128 v[230:233], v179 offset:7168
	global_load_lds_dwordx4 v[174:175], off
	v_lshl_add_u64 v[174:175], s[4:5], 0, v[132:133]
	s_add_i32 m0, s74, 0xe000
	s_nop 0
	global_load_lds_dwordx4 v[174:175], off
	s_waitcnt vmcnt(8)
	s_waitcnt lgkmcnt(0)
	s_setprio 1
	s_barrier
	v_mfma_f32_16x16x32_bf16 v[124:127], v[158:161], v[202:205], v[124:127]
	v_mfma_f32_16x16x32_bf16 v[120:123], v[166:169], v[202:205], v[120:123]
	v_mfma_f32_16x16x32_bf16 v[116:119], v[158:161], v[210:213], v[116:119]
	v_mfma_f32_16x16x32_bf16 v[112:115], v[166:169], v[210:213], v[112:115]
	v_mfma_f32_16x16x32_bf16 v[108:111], v[158:161], v[218:221], v[108:111]
	v_mfma_f32_16x16x32_bf16 v[104:107], v[166:169], v[218:221], v[104:107]
	v_mfma_f32_16x16x32_bf16 v[100:103], v[158:161], v[226:229], v[100:103]
	v_mfma_f32_16x16x32_bf16 v[96:99], v[166:169], v[226:229], v[96:99]
	v_mfma_f32_16x16x32_bf16 v[124:127], v[162:165], v[206:209], v[124:127]
	v_mfma_f32_16x16x32_bf16 v[120:123], v[170:173], v[206:209], v[120:123]
	v_mfma_f32_16x16x32_bf16 v[116:119], v[162:165], v[214:217], v[116:119]
	v_mfma_f32_16x16x32_bf16 v[112:115], v[170:173], v[214:217], v[112:115]
	v_mfma_f32_16x16x32_bf16 v[108:111], v[162:165], v[222:225], v[108:111]
	v_mfma_f32_16x16x32_bf16 v[104:107], v[170:173], v[222:225], v[104:107]
	v_mfma_f32_16x16x32_bf16 v[100:103], v[162:165], v[230:233], v[100:103]
	v_mfma_f32_16x16x32_bf16 v[96:99], v[170:173], v[230:233], v[96:99]
	s_setprio 0
	s_setprio 1
	v_mfma_f32_16x16x32_bf16 v[92:95], v[180:183], v[202:205], v[92:95]
	v_mfma_f32_16x16x32_bf16 v[88:91], v[194:197], v[202:205], v[88:91]
	v_mfma_f32_16x16x32_bf16 v[84:87], v[180:183], v[210:213], v[84:87]
	v_mfma_f32_16x16x32_bf16 v[80:83], v[194:197], v[210:213], v[80:83]
	v_mfma_f32_16x16x32_bf16 v[76:79], v[180:183], v[218:221], v[76:79]
	v_mfma_f32_16x16x32_bf16 v[72:75], v[194:197], v[218:221], v[72:75]
	v_mfma_f32_16x16x32_bf16 v[68:71], v[180:183], v[226:229], v[68:71]
	v_mfma_f32_16x16x32_bf16 v[64:67], v[194:197], v[226:229], v[64:67]
	v_mfma_f32_16x16x32_bf16 v[92:95], v[190:193], v[206:209], v[92:95]
	v_mfma_f32_16x16x32_bf16 v[88:91], v[198:201], v[206:209], v[88:91]
	v_mfma_f32_16x16x32_bf16 v[84:87], v[190:193], v[214:217], v[84:87]
	v_mfma_f32_16x16x32_bf16 v[80:83], v[198:201], v[214:217], v[80:83]
	v_mfma_f32_16x16x32_bf16 v[76:79], v[190:193], v[222:225], v[76:79]
	v_mfma_f32_16x16x32_bf16 v[72:75], v[198:201], v[222:225], v[72:75]
	v_mfma_f32_16x16x32_bf16 v[68:71], v[190:193], v[230:233], v[68:71]
	v_mfma_f32_16x16x32_bf16 v[64:67], v[198:201], v[230:233], v[64:67]
	s_barrier
	s_setprio 0
	s_add_i32 s4, s10, s77
	v_lshl_add_u64 v[174:175], s[52:53], 0, v[130:131]
	s_mov_b32 m0, s4
	ds_read_b128 v[202:205], v179 offset:16384
	ds_read_b128 v[206:209], v179 offset:17408
	ds_read_b128 v[210:213], v179 offset:18432
	ds_read_b128 v[214:217], v179 offset:19456
	ds_read_b128 v[218:221], v179 offset:20480
	ds_read_b128 v[222:225], v179 offset:21504
	ds_read_b128 v[226:229], v179 offset:22528
	ds_read_b128 v[230:233], v179 offset:23552
	global_load_lds_dwordx4 v[174:175], off
	s_add_i32 m0, s4, 0x2000
	s_add_u32 s4, s52, 0x160000
	v_lshl_add_u64 v[234:235], s[52:53], 0, v[134:135]
	s_addc_u32 s5, s53, 0
	s_add_i32 s6, s11, s77
	global_load_lds_dwordx4 v[234:235], off
	v_lshl_add_u64 v[236:237], s[4:5], 0, v[130:131]
	s_mov_b32 m0, s6
	s_nop 0
	global_load_lds_dwordx4 v[236:237], off
	v_lshl_add_u64 v[236:237], s[4:5], 0, v[134:135]
	s_add_i32 m0, s6, 0x2000
	s_nop 0
	global_load_lds_dwordx4 v[236:237], off
	v_lshl_add_u64 v[236:237], s[58:59], 0, v[128:129]
	s_mov_b32 m0, s74
	s_nop 0
	global_load_lds_dwordx4 v[236:237], off
	v_lshl_add_u64 v[236:237], s[58:59], 0, v[132:133]
	s_mov_b32 m0, s96
	s_nop 0
	global_load_lds_dwordx4 v[236:237], off
	s_waitcnt vmcnt(8)
	s_waitcnt lgkmcnt(0)
	s_setprio 1
	s_barrier
; #define PG8_STAGE(bufoff, gbase, voff) do { _Pragma("unroll") for (int _i = 0; _i < 2; ++_i) \
;         __builtin_amdgcn_global_load_lds((const unsigned*)((const char*)(gbase) + (voff)[_i]), (PG8_LAS unsigned*)(lds + (bufoff) + ldsw + _i * 8192), 16, 0, 0); } while (0)
; #define PG8_LDA(dst, b, h) do { _Pragma("unroll") for (int m = 0; m < 4; ++m) _Pragma("unroll") for (int k = 0; k < 2; ++k) dst[m][k] = *(const PG8_LAS bf16x8*)(lds + PG8_SA(b, h) + aoff + m * 2048 + k * 1024); } while (0)
; #define PG8_LDB(dst, b, h) do { _Pragma("unroll") for (int n = 0; n < 2; ++n) _Pragma("unroll") for (int k = 0; k < 2; ++k) dst[n][k] = *(const PG8_LAS bf16x8*)(lds + PG8_SB(b, h) + boff + n * 2048 + k * 1024); } while (0)
; #define PG8_MMA(ai, bj, At, Bt) do { __builtin_amdgcn_s_setprio(1); _Pragma("unroll") for (int m = 0; m < 4; ++m) _Pragma("unroll") for (int n = 0; n < 2; ++n) _Pragma("unroll") for (int k = 0; k < 2; ++k) \
;         acc[ai][bj][m][n] = __builtin_amdgcn_mfma_f32_16x16x32_bf16(Bt[n][k], At[m][k], acc[ai][bj][m][n], 0, 0, 0); __builtin_amdgcn_s_setprio(0); } while (0)
; #define PG8_WAIT_V(n) asm volatile("s_waitcnt vmcnt(" #n ")" ::: "memory")
; #define PG8_WAIT_L(n) asm volatile("s_waitcnt lgkmcnt(" #n ")" ::: "memory")
; #define PG8_BAR __builtin_amdgcn_s_barrier()
; #define PG8_SCHED __builtin_amdgcn_sched_barrier(0)
; template <class Epi, class Sched, bool ALIGN_EPI = false, bool SP2 = false>
; __device__ __forceinline__ void gemm_phase(PG8_LAS unsigned char* lds, const Gemm g, const Sched& S, const Epi& E) {
;     ...
;             PG8_WAIT_V(8); PG8_WAIT_L(0); PG8_BAR; PG8_MMA(1, 0, At, B0); PG8_MMA(1, 1, At, B1); PG8_BAR; PG8_SCHED;
;             PG8_LDB(B0, 1, 0); PG8_LDB(B1, 1, 1); PG8_SCHED; PG8_LDA(At, 1, 0); PG8_STAGE(PG8_SA(0, 1), a2 + hstepA, voffA);
;             PG8_WAIT_V(8); PG8_WAIT_L(0); PG8_BAR; PG8_MMA(0, 0, At, B0); PG8_MMA(0, 1, At, B1); PG8_BAR; PG8_SCHED;
	v_mfma_f32_16x16x32_bf16 v[60:63], v[158:161], v[202:205], v[60:63]
	v_mfma_f32_16x16x32_bf16 v[56:59], v[166:169], v[202:205], v[56:59]
	v_mfma_f32_16x16x32_bf16 v[52:55], v[158:161], v[210:213], v[52:55]
	v_mfma_f32_16x16x32_bf16 v[48:51], v[166:169], v[210:213], v[48:51]
	v_mfma_f32_16x16x32_bf16 v[44:47], v[158:161], v[218:221], v[44:47]
	v_mfma_f32_16x16x32_bf16 v[40:43], v[166:169], v[218:221], v[40:43]
	v_mfma_f32_16x16x32_bf16 v[36:39], v[158:161], v[226:229], v[36:39]
	v_mfma_f32_16x16x32_bf16 v[32:35], v[166:169], v[226:229], v[32:35]
	v_mfma_f32_16x16x32_bf16 v[60:63], v[162:165], v[206:209], v[60:63]
	v_mfma_f32_16x16x32_bf16 v[56:59], v[170:173], v[206:209], v[56:59]
	v_mfma_f32_16x16x32_bf16 v[52:55], v[162:165], v[214:217], v[52:55]
	v_mfma_f32_16x16x32_bf16 v[48:51], v[170:173], v[214:217], v[48:51]
	v_mfma_f32_16x16x32_bf16 v[44:47], v[162:165], v[222:225], v[44:47]
	v_mfma_f32_16x16x32_bf16 v[40:43], v[170:173], v[222:225], v[40:43]
	v_mfma_f32_16x16x32_bf16 v[36:39], v[162:165], v[230:233], v[36:39]
	v_mfma_f32_16x16x32_bf16 v[32:35], v[170:173], v[230:233], v[32:35]
	s_setprio 0
	s_setprio 1
	v_mfma_f32_16x16x32_bf16 v[28:31], v[180:183], v[202:205], v[28:31]
	v_mfma_f32_16x16x32_bf16 v[24:27], v[194:197], v[202:205], v[24:27]
	v_mfma_f32_16x16x32_bf16 v[20:23], v[180:183], v[210:213], v[20:23]
	v_mfma_f32_16x16x32_bf16 v[16:19], v[194:197], v[210:213], v[16:19]
	v_mfma_f32_16x16x32_bf16 v[12:15], v[180:183], v[218:221], v[12:15]
	v_mfma_f32_16x16x32_bf16 v[8:11], v[194:197], v[218:221], v[8:11]
	v_mfma_f32_16x16x32_bf16 v[4:7], v[180:183], v[226:229], v[4:7]
	v_mfma_f32_16x16x32_bf16 v[0:3], v[194:197], v[226:229], v[0:3]
	v_mfma_f32_16x16x32_bf16 v[28:31], v[190:193], v[206:209], v[28:31]
	v_mfma_f32_16x16x32_bf16 v[24:27], v[198:201], v[206:209], v[24:27]
	v_mfma_f32_16x16x32_bf16 v[20:23], v[190:193], v[214:217], v[20:23]
	v_mfma_f32_16x16x32_bf16 v[16:19], v[198:201], v[214:217], v[16:19]
	v_mfma_f32_16x16x32_bf16 v[12:15], v[190:193], v[222:225], v[12:15]
	v_mfma_f32_16x16x32_bf16 v[8:11], v[198:201], v[222:225], v[8:11]
	v_mfma_f32_16x16x32_bf16 v[4:7], v[190:193], v[230:233], v[4:7]
	v_mfma_f32_16x16x32_bf16 v[0:3], v[198:201], v[230:233], v[0:3]
	s_barrier
	s_setprio 0
	s_add_i32 s6, 0, 0x18000
	s_add_i32 s7, 0, 0x1c000
	v_add_u32_e32 v170, s6, v177
	v_add_u32_e32 v198, s7, v177
	ds_read_b128 v[158:161], v170
	ds_read_b128 v[162:165], v170 offset:1024
	ds_read_b128 v[166:169], v170 offset:2048
	ds_read_b128 v[170:173], v170 offset:3072
	ds_read_b128 v[180:183], v198
	ds_read_b128 v[190:193], v198 offset:1024
	ds_read_b128 v[194:197], v198 offset:2048
	ds_read_b128 v[198:201], v198 offset:3072
	s_add_u32 s4, s58, 0x4000
	s_addc_u32 s5, s59, 0
	s_mov_b32 m0, s97
	v_lshl_add_u64 v[236:237], s[4:5], 0, v[128:129]
	ds_read_b128 v[202:205], v179 offset:32768
	ds_read_b128 v[206:209], v179 offset:33792
	ds_read_b128 v[210:213], v179 offset:34816
	ds_read_b128 v[214:217], v179 offset:35840
	ds_read_b128 v[218:221], v179 offset:36864
	ds_read_b128 v[222:225], v179 offset:37888
	ds_read_b128 v[226:229], v179 offset:38912
	ds_read_b128 v[230:233], v179 offset:39936
	global_load_lds_dwordx4 v[236:237], off
	v_lshl_add_u64 v[236:237], s[4:5], 0, v[132:133]
	s_mov_b32 m0, s75
	s_nop 0
	global_load_lds_dwordx4 v[236:237], off
	s_waitcnt vmcnt(8)
	s_waitcnt lgkmcnt(0)
	s_setprio 1
	s_barrier
	v_mfma_f32_16x16x32_bf16 v[124:127], v[158:161], v[202:205], v[124:127]
	v_mfma_f32_16x16x32_bf16 v[120:123], v[166:169], v[202:205], v[120:123]
	v_mfma_f32_16x16x32_bf16 v[116:119], v[158:161], v[210:213], v[116:119]
	v_mfma_f32_16x16x32_bf16 v[112:115], v[166:169], v[210:213], v[112:115]
	v_mfma_f32_16x16x32_bf16 v[108:111], v[158:161], v[218:221], v[108:111]
	v_mfma_f32_16x16x32_bf16 v[104:107], v[166:169], v[218:221], v[104:107]
	v_mfma_f32_16x16x32_bf16 v[100:103], v[158:161], v[226:229], v[100:103]
	v_mfma_f32_16x16x32_bf16 v[96:99], v[166:169], v[226:229], v[96:99]
	v_mfma_f32_16x16x32_bf16 v[124:127], v[162:165], v[206:209], v[124:127]
	v_mfma_f32_16x16x32_bf16 v[120:123], v[170:173], v[206:209], v[120:123]
	v_mfma_f32_16x16x32_bf16 v[116:119], v[162:165], v[214:217], v[116:119]
	v_mfma_f32_16x16x32_bf16 v[112:115], v[170:173], v[214:217], v[112:115]
	v_mfma_f32_16x16x32_bf16 v[108:111], v[162:165], v[222:225], v[108:111]
	v_mfma_f32_16x16x32_bf16 v[104:107], v[170:173], v[222:225], v[104:107]
	v_mfma_f32_16x16x32_bf16 v[100:103], v[162:165], v[230:233], v[100:103]
	v_mfma_f32_16x16x32_bf16 v[96:99], v[170:173], v[230:233], v[96:99]
	s_setprio 0
	s_setprio 1
	v_mfma_f32_16x16x32_bf16 v[92:95], v[180:183], v[202:205], v[92:95]
	v_mfma_f32_16x16x32_bf16 v[88:91], v[194:197], v[202:205], v[88:91]
	v_mfma_f32_16x16x32_bf16 v[84:87], v[180:183], v[210:213], v[84:87]
	v_mfma_f32_16x16x32_bf16 v[80:83], v[194:197], v[210:213], v[80:83]
	v_mfma_f32_16x16x32_bf16 v[76:79], v[180:183], v[218:221], v[76:79]
	v_mfma_f32_16x16x32_bf16 v[72:75], v[194:197], v[218:221], v[72:75]
	v_mfma_f32_16x16x32_bf16 v[68:71], v[180:183], v[226:229], v[68:71]
	v_mfma_f32_16x16x32_bf16 v[64:67], v[194:197], v[226:229], v[64:67]
	v_mfma_f32_16x16x32_bf16 v[92:95], v[190:193], v[206:209], v[92:95]
	v_mfma_f32_16x16x32_bf16 v[88:91], v[198:201], v[206:209], v[88:91]
	v_mfma_f32_16x16x32_bf16 v[84:87], v[190:193], v[214:217], v[84:87]
	v_mfma_f32_16x16x32_bf16 v[80:83], v[198:201], v[214:217], v[80:83]
	v_mfma_f32_16x16x32_bf16 v[76:79], v[190:193], v[222:225], v[76:79]
	v_mfma_f32_16x16x32_bf16 v[72:75], v[198:201], v[222:225], v[72:75]
	v_mfma_f32_16x16x32_bf16 v[68:71], v[190:193], v[230:233], v[68:71]
	v_mfma_f32_16x16x32_bf16 v[64:67], v[198:201], v[230:233], v[64:67]
	s_barrier
; #define PG8_STAGE(bufoff, gbase, voff) do { _Pragma("unroll") for (int _i = 0; _i < 2; ++_i) \
;         __builtin_amdgcn_global_load_lds((const unsigned*)((const char*)(gbase) + (voff)[_i]), (PG8_LAS unsigned*)(lds + (bufoff) + ldsw + _i * 8192), 16, 0, 0); } while (0)
; #define PG8_LDA(dst, b, h) do { _Pragma("unroll") for (int m = 0; m < 4; ++m) _Pragma("unroll") for (int k = 0; k < 2; ++k) dst[m][k] = *(const PG8_LAS bf16x8*)(lds + PG8_SA(b, h) + aoff + m * 2048 + k * 1024); } while (0)
; #define PG8_MMA(ai, bj, At, Bt) do { __builtin_amdgcn_s_setprio(1); _Pragma("unroll") for (int m = 0; m < 4; ++m) _Pragma("unroll") for (int n = 0; n < 2; ++n) _Pragma("unroll") for (int k = 0; k < 2; ++k) \
;         acc[ai][bj][m][n] = __builtin_amdgcn_mfma_f32_16x16x32_bf16(Bt[n][k], At[m][k], acc[ai][bj][m][n], 0, 0, 0); __builtin_amdgcn_s_setprio(0); } while (0)
; #define PG8_WAIT_V(n) asm volatile("s_waitcnt vmcnt(" #n ")" ::: "memory")
; #define PG8_WAIT_L(n) asm volatile("s_waitcnt lgkmcnt(" #n ")" ::: "memory")
; #define PG8_BAR __builtin_amdgcn_s_barrier()
; #define PG8_SCHED __builtin_amdgcn_sched_barrier(0)
; template <class Epi, class Sched, bool ALIGN_EPI = false, bool SP2 = false>
; __device__ __forceinline__ void gemm_phase(PG8_LAS unsigned char* lds, const Gemm g, const Sched& S, const Epi& E) {
;     ...
;         for (int t = 0; t < nt; t += 2) {
;     ...
;             PG8_LDA(At, 1, 1); PG8_STAGE(PG8_SB(1, 0), b3, voffB); PG8_STAGE(PG8_SB(1, 1), b3 + hstepB, voffB); PG8_STAGE(PG8_SA(1, 0), a3, voffA);
;             PG8_WAIT_V(8); PG8_WAIT_L(0); PG8_BAR; PG8_MMA(1, 0, At, B0); PG8_MMA(1, 1, At, B1); PG8_BAR; PG8_SCHED;
	s_setprio 0
	s_add_i32 s4, s6, s77
	v_lshl_add_u64 v[174:175], v[174:175], 0, s[64:65]
	s_mov_b32 m0, s4
	ds_read_b128 v[202:205], v179 offset:49152
	ds_read_b128 v[206:209], v179 offset:50176
	ds_read_b128 v[210:213], v179 offset:51200
	ds_read_b128 v[214:217], v179 offset:52224
	ds_read_b128 v[218:221], v179 offset:53248
	ds_read_b128 v[222:225], v179 offset:54272
	ds_read_b128 v[226:229], v179 offset:55296
	ds_read_b128 v[230:233], v179 offset:56320
	global_load_lds_dwordx4 v[174:175], off
	s_add_i32 m0, s4, 0x2000
	s_add_u32 s4, s52, 0x160080
	v_lshl_add_u64 v[174:175], v[234:235], 0, s[64:65]
	s_addc_u32 s5, s53, 0
	s_add_i32 s6, s7, s77
	global_load_lds_dwordx4 v[174:175], off
	v_lshl_add_u64 v[174:175], s[4:5], 0, v[130:131]
	s_mov_b32 m0, s6
	s_nop 0
	global_load_lds_dwordx4 v[174:175], off
	v_lshl_add_u64 v[174:175], s[4:5], 0, v[134:135]
	s_add_i32 m0, s6, 0x2000
	s_nop 0
	global_load_lds_dwordx4 v[174:175], off
	v_lshl_add_u64 v[174:175], s[50:51], 0, v[128:129]
	s_mov_b32 m0, s43
	s_nop 0
	global_load_lds_dwordx4 v[174:175], off
	v_lshl_add_u64 v[174:175], s[50:51], 0, v[132:133]
	s_mov_b32 m0, s56
	s_nop 0
	global_load_lds_dwordx4 v[174:175], off
	s_waitcnt vmcnt(8)
	s_waitcnt lgkmcnt(0)
	s_setprio 1
	s_barrier
	v_mfma_f32_16x16x32_bf16 v[60:63], v[158:161], v[202:205], v[60:63]
	v_mfma_f32_16x16x32_bf16 v[56:59], v[166:169], v[202:205], v[56:59]
	v_mfma_f32_16x16x32_bf16 v[52:55], v[158:161], v[210:213], v[52:55]
	v_mfma_f32_16x16x32_bf16 v[48:51], v[166:169], v[210:213], v[48:51]
	v_mfma_f32_16x16x32_bf16 v[44:47], v[158:161], v[218:221], v[44:47]
	v_mfma_f32_16x16x32_bf16 v[40:43], v[166:169], v[218:221], v[40:43]
	v_mfma_f32_16x16x32_bf16 v[36:39], v[158:161], v[226:229], v[36:39]
	v_mfma_f32_16x16x32_bf16 v[32:35], v[166:169], v[226:229], v[32:35]
	v_mfma_f32_16x16x32_bf16 v[60:63], v[162:165], v[206:209], v[60:63]
	v_mfma_f32_16x16x32_bf16 v[56:59], v[170:173], v[206:209], v[56:59]
	v_mfma_f32_16x16x32_bf16 v[52:55], v[162:165], v[214:217], v[52:55]
	v_mfma_f32_16x16x32_bf16 v[48:51], v[170:173], v[214:217], v[48:51]
	v_mfma_f32_16x16x32_bf16 v[44:47], v[162:165], v[222:225], v[44:47]
	v_mfma_f32_16x16x32_bf16 v[40:43], v[170:173], v[222:225], v[40:43]
	v_mfma_f32_16x16x32_bf16 v[36:39], v[162:165], v[230:233], v[36:39]
	v_mfma_f32_16x16x32_bf16 v[32:35], v[170:173], v[230:233], v[32:35]
	s_setprio 0
	s_setprio 1
	v_mfma_f32_16x16x32_bf16 v[28:31], v[180:183], v[202:205], v[28:31]
	v_mfma_f32_16x16x32_bf16 v[24:27], v[194:197], v[202:205], v[24:27]
	v_mfma_f32_16x16x32_bf16 v[20:23], v[180:183], v[210:213], v[20:23]
	v_mfma_f32_16x16x32_bf16 v[16:19], v[194:197], v[210:213], v[16:19]
	v_mfma_f32_16x16x32_bf16 v[12:15], v[180:183], v[218:221], v[12:15]
	v_mfma_f32_16x16x32_bf16 v[8:11], v[194:197], v[218:221], v[8:11]
	v_mfma_f32_16x16x32_bf16 v[4:7], v[180:183], v[226:229], v[4:7]
	v_mfma_f32_16x16x32_bf16 v[0:3], v[194:197], v[226:229], v[0:3]
	v_mfma_f32_16x16x32_bf16 v[28:31], v[190:193], v[206:209], v[28:31]
	v_mfma_f32_16x16x32_bf16 v[24:27], v[198:201], v[206:209], v[24:27]
	v_mfma_f32_16x16x32_bf16 v[20:23], v[190:193], v[214:217], v[20:23]
	v_mfma_f32_16x16x32_bf16 v[16:19], v[198:201], v[214:217], v[16:19]
	v_mfma_f32_16x16x32_bf16 v[12:15], v[190:193], v[222:225], v[12:15]
	v_mfma_f32_16x16x32_bf16 v[8:11], v[198:201], v[222:225], v[8:11]
	v_mfma_f32_16x16x32_bf16 v[4:7], v[190:193], v[230:233], v[4:7]
	v_mfma_f32_16x16x32_bf16 v[0:3], v[198:201], v[230:233], v[0:3]
	s_barrier
	s_setprio 0
	s_cmp_ge_i32 s68, s57
	s_cbranch_scc1 .LBB0_1416

; #define PG8_STAGE(bufoff, gbase, voff) do { _Pragma("unroll") for (int _i = 0; _i < 2; ++_i) \
;         __builtin_amdgcn_global_load_lds((const unsigned*)((const char*)(gbase) + (voff)[_i]), (PG8_LAS unsigned*)(lds + (bufoff) + ldsw + _i * 8192), 16, 0, 0); } while (0)
; #define PG8_LDA(dst, b, h) do { _Pragma("unroll") for (int m = 0; m < 4; ++m) _Pragma("unroll") for (int k = 0; k < 2; ++k) dst[m][k] = *(const PG8_LAS bf16x8*)(lds + PG8_SA(b, h) + aoff + m * 2048 + k * 1024); } while (0)
; #define PG8_LDB(dst, b, h) do { _Pragma("unroll") for (int n = 0; n < 2; ++n) _Pragma("unroll") for (int k = 0; k < 2; ++k) dst[n][k] = *(const PG8_LAS bf16x8*)(lds + PG8_SB(b, h) + boff + n * 2048 + k * 1024); } while (0)
; #define PG8_MMA(ai, bj, At, Bt) do { __builtin_amdgcn_s_setprio(1); _Pragma("unroll") for (int m = 0; m < 4; ++m) _Pragma("unroll") for (int n = 0; n < 2; ++n) _Pragma("unroll") for (int k = 0; k < 2; ++k) \
;         acc[ai][bj][m][n] = __builtin_amdgcn_mfma_f32_16x16x32_bf16(Bt[n][k], At[m][k], acc[ai][bj][m][n], 0, 0, 0); __builtin_amdgcn_s_setprio(0); } while (0)
; #define PG8_WAIT_V(n) asm volatile("s_waitcnt vmcnt(" #n ")" ::: "memory")
; #define PG8_WAIT_L(n) asm volatile("s_waitcnt lgkmcnt(" #n ")" ::: "memory")
; #define PG8_BAR __builtin_amdgcn_s_barrier()
; template <class Epi, class Sched, bool ALIGN_EPI = false, bool SP2 = false>
; __device__ __forceinline__ void gemm_phase(PG8_LAS unsigned char* lds, const Gemm g, const Sched& S, const Epi& E) {
;     ...
;             const char* a1 = cA + (size_t)(t + 1) * kstA;
;             const char* a2 = last ? nA : cA + (size_t)(t + 2) * kstA; const char* b2 = last ? nB : cB + (size_t)(t + 2) * kstep;
;             const char* a3 = a2 + kstA; const char* b3 = b2 + kstep;
;             if (last && has_next) S.a_ready(nxt);
;             if constexpr (SP2) {
;             PG8_LDB(B0, 0, 0); PG8_LDB(B1, 0, 1); PG8_SCHED; PG8_LDA(At, 0, 0); PG8_STAGE(PG8_SA(1, 1), a1 + hstepA, voffA);
;             PG8_WAIT_V(8); PG8_WAIT_L(0); PG8_BAR; PG8_MMA(0, 0, At, B0); PG8_MMA(0, 1, At, B1); PG8_BAR; PG8_SCHED;
;             PG8_LDA(At, 0, 1); PG8_STAGE(PG8_SB(0, 0), b2, voffB); PG8_STAGE(PG8_SB(0, 1), b2 + hstepB, voffB); PG8_STAGE(PG8_SA(0, 0), a2, voffA);
;             PG8_WAIT_V(8); PG8_WAIT_L(0); PG8_BAR; PG8_MMA(1, 0, At, B0); PG8_MMA(1, 1, At, B1); PG8_BAR; PG8_SCHED;
.LBB0_1657:
	ds_read_b128 v[156:159], v152
	ds_read_b128 v[160:163], v152 offset:1024
	ds_read_b128 v[164:167], v152 offset:2048
	ds_read_b128 v[168:171], v152 offset:3072
	ds_read_b128 v[172:175], v153
	ds_read_b128 v[176:179], v153 offset:1024
	ds_read_b128 v[180:183], v153 offset:2048
	ds_read_b128 v[190:193], v153 offset:3072
	s_add_u32 s52, s50, 0xfff80080
	s_addc_u32 s53, s51, -1
	s_cmp_eq_u32 s63, 28
	s_cselect_b32 s59, s4, s53
	s_cselect_b32 s58, s5, s52
	s_cselect_b32 s53, s12, s41
	s_cselect_b32 s52, s13, s39
	v_lshl_add_u64 v[226:227], s[50:51], 0, v[142:143]
	s_add_i32 m0, s7, 0xc000
	ds_read_b128 v[194:197], v154
	ds_read_b128 v[198:201], v154 offset:1024
	ds_read_b128 v[202:205], v154 offset:2048
	ds_read_b128 v[206:209], v154 offset:3072
	ds_read_b128 v[210:213], v154 offset:4096
	ds_read_b128 v[214:217], v154 offset:5120
	ds_read_b128 v[218:221], v154 offset:6144
	ds_read_b128 v[222:225], v154 offset:7168
	global_load_lds_dwordx4 v[226:227], off
	v_lshl_add_u64 v[226:227], s[50:51], 0, v[144:145]
	s_add_i32 m0, s7, 0xe000
	s_nop 0
	global_load_lds_dwordx4 v[226:227], off
	s_waitcnt vmcnt(8)
	s_waitcnt lgkmcnt(0)
	s_setprio 1
	s_barrier
	v_mfma_f32_16x16x32_bf16 v[124:127], v[156:159], v[194:197], v[124:127]
	v_mfma_f32_16x16x32_bf16 v[120:123], v[164:167], v[194:197], v[120:123]
	v_mfma_f32_16x16x32_bf16 v[108:111], v[156:159], v[202:205], v[108:111]
	v_mfma_f32_16x16x32_bf16 v[104:107], v[164:167], v[202:205], v[104:107]
	v_mfma_f32_16x16x32_bf16 v[92:95], v[156:159], v[210:213], v[92:95]
	v_mfma_f32_16x16x32_bf16 v[88:91], v[164:167], v[210:213], v[88:91]
	v_mfma_f32_16x16x32_bf16 v[76:79], v[156:159], v[218:221], v[76:79]
	v_mfma_f32_16x16x32_bf16 v[72:75], v[164:167], v[218:221], v[72:75]
	v_mfma_f32_16x16x32_bf16 v[124:127], v[160:163], v[198:201], v[124:127]
	v_mfma_f32_16x16x32_bf16 v[120:123], v[168:171], v[198:201], v[120:123]
	v_mfma_f32_16x16x32_bf16 v[108:111], v[160:163], v[206:209], v[108:111]
	v_mfma_f32_16x16x32_bf16 v[104:107], v[168:171], v[206:209], v[104:107]
	v_mfma_f32_16x16x32_bf16 v[92:95], v[160:163], v[214:217], v[92:95]
	v_mfma_f32_16x16x32_bf16 v[88:91], v[168:171], v[214:217], v[88:91]
	v_mfma_f32_16x16x32_bf16 v[76:79], v[160:163], v[222:225], v[76:79]
	v_mfma_f32_16x16x32_bf16 v[72:75], v[168:171], v[222:225], v[72:75]
	s_setprio 0
	s_setprio 1
	v_mfma_f32_16x16x32_bf16 v[116:119], v[172:175], v[194:197], v[116:119]
	v_mfma_f32_16x16x32_bf16 v[112:115], v[180:183], v[194:197], v[112:115]
	v_mfma_f32_16x16x32_bf16 v[100:103], v[172:175], v[202:205], v[100:103]
	v_mfma_f32_16x16x32_bf16 v[96:99], v[180:183], v[202:205], v[96:99]
	v_mfma_f32_16x16x32_bf16 v[84:87], v[172:175], v[210:213], v[84:87]
	v_mfma_f32_16x16x32_bf16 v[80:83], v[180:183], v[210:213], v[80:83]
	v_mfma_f32_16x16x32_bf16 v[68:71], v[172:175], v[218:221], v[68:71]
	v_mfma_f32_16x16x32_bf16 v[64:67], v[180:183], v[218:221], v[64:67]
	v_mfma_f32_16x16x32_bf16 v[116:119], v[176:179], v[198:201], v[116:119]
	v_mfma_f32_16x16x32_bf16 v[112:115], v[190:193], v[198:201], v[112:115]
	v_mfma_f32_16x16x32_bf16 v[100:103], v[176:179], v[206:209], v[100:103]
	v_mfma_f32_16x16x32_bf16 v[96:99], v[190:193], v[206:209], v[96:99]
	v_mfma_f32_16x16x32_bf16 v[84:87], v[176:179], v[214:217], v[84:87]
	v_mfma_f32_16x16x32_bf16 v[80:83], v[190:193], v[214:217], v[80:83]
	v_mfma_f32_16x16x32_bf16 v[68:71], v[176:179], v[222:225], v[68:71]
	v_mfma_f32_16x16x32_bf16 v[64:67], v[190:193], v[222:225], v[64:67]
	s_barrier
	s_setprio 0
	s_add_i32 s64, s56, s6
	v_lshl_add_u64 v[226:227], s[52:53], 0, v[130:131]
	s_mov_b32 m0, s64
	ds_read_b128 v[194:197], v154 offset:16384
	ds_read_b128 v[198:201], v154 offset:17408
	ds_read_b128 v[202:205], v154 offset:18432
	ds_read_b128 v[206:209], v154 offset:19456
	ds_read_b128 v[210:213], v154 offset:20480
	ds_read_b128 v[214:217], v154 offset:21504
	ds_read_b128 v[218:221], v154 offset:22528
	ds_read_b128 v[222:225], v154 offset:23552
	global_load_lds_dwordx4 v[226:227], off
	s_add_i32 m0, s64, 0x2000
	s_add_u32 s64, s52, 0x80000
	v_lshl_add_u64 v[228:229], s[52:53], 0, v[134:135]
	s_addc_u32 s65, s53, 0
	s_add_i32 s66, s57, s6
	global_load_lds_dwordx4 v[228:229], off
	v_lshl_add_u64 v[230:231], s[64:65], 0, v[130:131]
	s_mov_b32 m0, s66
	v_lshl_add_u64 v[232:233], s[58:59], 0, v[132:133]
	global_load_lds_dwordx4 v[230:231], off
	v_lshl_add_u64 v[230:231], s[64:65], 0, v[134:135]
	s_add_i32 m0, s66, 0x2000
	s_nop 0
	global_load_lds_dwordx4 v[230:231], off
	v_lshl_add_u64 v[230:231], s[58:59], 0, v[128:129]
	s_mov_b32 m0, s7
	s_nop 0
	global_load_lds_dwordx4 v[230:231], off
	s_mov_b32 m0, s8
	s_nop 0
	global_load_lds_dwordx4 v[232:233], off
	s_waitcnt vmcnt(8)
	s_waitcnt lgkmcnt(0)
	s_setprio 1
	s_barrier
; #define PG8_STAGE(bufoff, gbase, voff) do { _Pragma("unroll") for (int _i = 0; _i < 2; ++_i) \
;         __builtin_amdgcn_global_load_lds((const unsigned*)((const char*)(gbase) + (voff)[_i]), (PG8_LAS unsigned*)(lds + (bufoff) + ldsw + _i * 8192), 16, 0, 0); } while (0)
; #define PG8_LDA(dst, b, h) do { _Pragma("unroll") for (int m = 0; m < 4; ++m) _Pragma("unroll") for (int k = 0; k < 2; ++k) dst[m][k] = *(const PG8_LAS bf16x8*)(lds + PG8_SA(b, h) + aoff + m * 2048 + k * 1024); } while (0)
; #define PG8_LDB(dst, b, h) do { _Pragma("unroll") for (int n = 0; n < 2; ++n) _Pragma("unroll") for (int k = 0; k < 2; ++k) dst[n][k] = *(const PG8_LAS bf16x8*)(lds + PG8_SB(b, h) + boff + n * 2048 + k * 1024); } while (0)
; #define PG8_MMA(ai, bj, At, Bt) do { __builtin_amdgcn_s_setprio(1); _Pragma("unroll") for (int m = 0; m < 4; ++m) _Pragma("unroll") for (int n = 0; n < 2; ++n) _Pragma("unroll") for (int k = 0; k < 2; ++k) \
;         acc[ai][bj][m][n] = __builtin_amdgcn_mfma_f32_16x16x32_bf16(Bt[n][k], At[m][k], acc[ai][bj][m][n], 0, 0, 0); __builtin_amdgcn_s_setprio(0); } while (0)
; #define PG8_WAIT_V(n) asm volatile("s_waitcnt vmcnt(" #n ")" ::: "memory")
; #define PG8_WAIT_L(n) asm volatile("s_waitcnt lgkmcnt(" #n ")" ::: "memory")
; #define PG8_BAR __builtin_amdgcn_s_barrier()
; #define PG8_SCHED __builtin_amdgcn_sched_barrier(0)
; template <class Epi, class Sched, bool ALIGN_EPI = false, bool SP2 = false>
; __device__ __forceinline__ void gemm_phase(PG8_LAS unsigned char* lds, const Gemm g, const Sched& S, const Epi& E) {
;     ...
;             PG8_WAIT_V(8); PG8_WAIT_L(0); PG8_BAR; PG8_MMA(1, 0, At, B0); PG8_MMA(1, 1, At, B1); PG8_BAR; PG8_SCHED;
;             PG8_LDB(B0, 1, 0); PG8_LDB(B1, 1, 1); PG8_SCHED; PG8_LDA(At, 1, 0); PG8_STAGE(PG8_SA(0, 1), a2 + hstepA, voffA);
;             PG8_WAIT_V(8); PG8_WAIT_L(0); PG8_BAR; PG8_MMA(0, 0, At, B0); PG8_MMA(0, 1, At, B1); PG8_BAR; PG8_SCHED;
	v_mfma_f32_16x16x32_bf16 v[60:63], v[156:159], v[194:197], v[60:63]
	v_mfma_f32_16x16x32_bf16 v[56:59], v[164:167], v[194:197], v[56:59]
	v_mfma_f32_16x16x32_bf16 v[44:47], v[156:159], v[202:205], v[44:47]
	v_mfma_f32_16x16x32_bf16 v[40:43], v[164:167], v[202:205], v[40:43]
	v_mfma_f32_16x16x32_bf16 v[28:31], v[156:159], v[210:213], v[28:31]
	v_mfma_f32_16x16x32_bf16 v[24:27], v[164:167], v[210:213], v[24:27]
	v_mfma_f32_16x16x32_bf16 v[12:15], v[156:159], v[218:221], v[12:15]
	v_mfma_f32_16x16x32_bf16 v[8:11], v[164:167], v[218:221], v[8:11]
	v_mfma_f32_16x16x32_bf16 v[60:63], v[160:163], v[198:201], v[60:63]
	v_mfma_f32_16x16x32_bf16 v[56:59], v[168:171], v[198:201], v[56:59]
	v_mfma_f32_16x16x32_bf16 v[44:47], v[160:163], v[206:209], v[44:47]
	v_mfma_f32_16x16x32_bf16 v[40:43], v[168:171], v[206:209], v[40:43]
	v_mfma_f32_16x16x32_bf16 v[28:31], v[160:163], v[214:217], v[28:31]
	v_mfma_f32_16x16x32_bf16 v[24:27], v[168:171], v[214:217], v[24:27]
	v_mfma_f32_16x16x32_bf16 v[12:15], v[160:163], v[222:225], v[12:15]
	v_mfma_f32_16x16x32_bf16 v[8:11], v[168:171], v[222:225], v[8:11]
	s_setprio 0
	s_setprio 1
	v_mfma_f32_16x16x32_bf16 v[52:55], v[172:175], v[194:197], v[52:55]
	v_mfma_f32_16x16x32_bf16 v[48:51], v[180:183], v[194:197], v[48:51]
	v_mfma_f32_16x16x32_bf16 v[36:39], v[172:175], v[202:205], v[36:39]
	v_mfma_f32_16x16x32_bf16 v[32:35], v[180:183], v[202:205], v[32:35]
	v_mfma_f32_16x16x32_bf16 v[20:23], v[172:175], v[210:213], v[20:23]
	v_mfma_f32_16x16x32_bf16 v[16:19], v[180:183], v[210:213], v[16:19]
	v_mfma_f32_16x16x32_bf16 v[4:7], v[172:175], v[218:221], v[4:7]
	v_mfma_f32_16x16x32_bf16 v[0:3], v[180:183], v[218:221], v[0:3]
	v_mfma_f32_16x16x32_bf16 v[52:55], v[176:179], v[198:201], v[52:55]
	v_mfma_f32_16x16x32_bf16 v[48:51], v[190:193], v[198:201], v[48:51]
	v_mfma_f32_16x16x32_bf16 v[36:39], v[176:179], v[206:209], v[36:39]
	v_mfma_f32_16x16x32_bf16 v[32:35], v[190:193], v[206:209], v[32:35]
	v_mfma_f32_16x16x32_bf16 v[20:23], v[176:179], v[214:217], v[20:23]
	v_mfma_f32_16x16x32_bf16 v[16:19], v[190:193], v[214:217], v[16:19]
	v_mfma_f32_16x16x32_bf16 v[4:7], v[176:179], v[222:225], v[4:7]
	v_mfma_f32_16x16x32_bf16 v[0:3], v[190:193], v[222:225], v[0:3]
	s_barrier
	s_setprio 0
	s_add_i32 s64, 0, 0x18000
	v_add_u32_e32 v155, s64, v150
	s_add_i32 s65, 0, 0x1c000
	ds_read_b128 v[156:159], v155
	ds_read_b128 v[160:163], v155 offset:1024
	ds_read_b128 v[164:167], v155 offset:2048
	ds_read_b128 v[168:171], v155 offset:3072
	v_add_u32_e32 v155, s65, v150
	ds_read_b128 v[172:175], v155
	ds_read_b128 v[176:179], v155 offset:1024
	ds_read_b128 v[180:183], v155 offset:2048
	ds_read_b128 v[190:193], v155 offset:3072
	s_add_u32 s58, s58, 0x80000
	s_addc_u32 s59, s59, 0
	s_mov_b32 m0, s9
	v_lshl_add_u64 v[234:235], s[58:59], 0, v[128:129]
	ds_read_b128 v[194:197], v154 offset:32768
	ds_read_b128 v[198:201], v154 offset:33792
	ds_read_b128 v[202:205], v154 offset:34816
	ds_read_b128 v[206:209], v154 offset:35840
	ds_read_b128 v[210:213], v154 offset:36864
	ds_read_b128 v[214:217], v154 offset:37888
	ds_read_b128 v[218:221], v154 offset:38912
	ds_read_b128 v[222:225], v154 offset:39936
	global_load_lds_dwordx4 v[234:235], off
	v_lshl_add_u64 v[234:235], s[58:59], 0, v[132:133]
	s_mov_b32 m0, s11
	s_nop 0
	global_load_lds_dwordx4 v[234:235], off
	s_waitcnt vmcnt(8)
	s_waitcnt lgkmcnt(0)
	s_setprio 1
	s_barrier
	v_mfma_f32_16x16x32_bf16 v[124:127], v[156:159], v[194:197], v[124:127]
	v_mfma_f32_16x16x32_bf16 v[120:123], v[164:167], v[194:197], v[120:123]
	v_mfma_f32_16x16x32_bf16 v[108:111], v[156:159], v[202:205], v[108:111]
	v_mfma_f32_16x16x32_bf16 v[104:107], v[164:167], v[202:205], v[104:107]
	v_mfma_f32_16x16x32_bf16 v[92:95], v[156:159], v[210:213], v[92:95]
	v_mfma_f32_16x16x32_bf16 v[88:91], v[164:167], v[210:213], v[88:91]
	v_mfma_f32_16x16x32_bf16 v[76:79], v[156:159], v[218:221], v[76:79]
	v_mfma_f32_16x16x32_bf16 v[72:75], v[164:167], v[218:221], v[72:75]
	v_mfma_f32_16x16x32_bf16 v[124:127], v[160:163], v[198:201], v[124:127]
	v_mfma_f32_16x16x32_bf16 v[120:123], v[168:171], v[198:201], v[120:123]
	v_mfma_f32_16x16x32_bf16 v[108:111], v[160:163], v[206:209], v[108:111]
	v_mfma_f32_16x16x32_bf16 v[104:107], v[168:171], v[206:209], v[104:107]
	v_mfma_f32_16x16x32_bf16 v[92:95], v[160:163], v[214:217], v[92:95]
	v_mfma_f32_16x16x32_bf16 v[88:91], v[168:171], v[214:217], v[88:91]
	v_mfma_f32_16x16x32_bf16 v[76:79], v[160:163], v[222:225], v[76:79]
	v_mfma_f32_16x16x32_bf16 v[72:75], v[168:171], v[222:225], v[72:75]
	s_setprio 0
	s_setprio 1
	v_mfma_f32_16x16x32_bf16 v[116:119], v[172:175], v[194:197], v[116:119]
	v_mfma_f32_16x16x32_bf16 v[112:115], v[180:183], v[194:197], v[112:115]
	v_mfma_f32_16x16x32_bf16 v[100:103], v[172:175], v[202:205], v[100:103]
	v_mfma_f32_16x16x32_bf16 v[96:99], v[180:183], v[202:205], v[96:99]
	v_mfma_f32_16x16x32_bf16 v[84:87], v[172:175], v[210:213], v[84:87]
	v_mfma_f32_16x16x32_bf16 v[80:83], v[180:183], v[210:213], v[80:83]
	v_mfma_f32_16x16x32_bf16 v[68:71], v[172:175], v[218:221], v[68:71]
	v_mfma_f32_16x16x32_bf16 v[64:67], v[180:183], v[218:221], v[64:67]
	v_mfma_f32_16x16x32_bf16 v[116:119], v[176:179], v[198:201], v[116:119]
	v_mfma_f32_16x16x32_bf16 v[112:115], v[190:193], v[198:201], v[112:115]
	v_mfma_f32_16x16x32_bf16 v[100:103], v[176:179], v[206:209], v[100:103]
	v_mfma_f32_16x16x32_bf16 v[96:99], v[190:193], v[206:209], v[96:99]
	v_mfma_f32_16x16x32_bf16 v[84:87], v[176:179], v[214:217], v[84:87]
	v_mfma_f32_16x16x32_bf16 v[80:83], v[190:193], v[214:217], v[80:83]
	v_mfma_f32_16x16x32_bf16 v[68:71], v[176:179], v[222:225], v[68:71]
	v_mfma_f32_16x16x32_bf16 v[64:67], v[190:193], v[222:225], v[64:67]
	s_barrier
; #define PG8_STAGE(bufoff, gbase, voff) do { _Pragma("unroll") for (int _i = 0; _i < 2; ++_i) \
;         __builtin_amdgcn_global_load_lds((const unsigned*)((const char*)(gbase) + (voff)[_i]), (PG8_LAS unsigned*)(lds + (bufoff) + ldsw + _i * 8192), 16, 0, 0); } while (0)
; #define PG8_LDA(dst, b, h) do { _Pragma("unroll") for (int m = 0; m < 4; ++m) _Pragma("unroll") for (int k = 0; k < 2; ++k) dst[m][k] = *(const PG8_LAS bf16x8*)(lds + PG8_SA(b, h) + aoff + m * 2048 + k * 1024); } while (0)
; #define PG8_MMA(ai, bj, At, Bt) do { __builtin_amdgcn_s_setprio(1); _Pragma("unroll") for (int m = 0; m < 4; ++m) _Pragma("unroll") for (int n = 0; n < 2; ++n) _Pragma("unroll") for (int k = 0; k < 2; ++k) \
;         acc[ai][bj][m][n] = __builtin_amdgcn_mfma_f32_16x16x32_bf16(Bt[n][k], At[m][k], acc[ai][bj][m][n], 0, 0, 0); __builtin_amdgcn_s_setprio(0); } while (0)
; #define PG8_WAIT_V(n) asm volatile("s_waitcnt vmcnt(" #n ")" ::: "memory")
; #define PG8_WAIT_L(n) asm volatile("s_waitcnt lgkmcnt(" #n ")" ::: "memory")
; #define PG8_BAR __builtin_amdgcn_s_barrier()
; #define PG8_SCHED __builtin_amdgcn_sched_barrier(0)
; template <class Epi, class Sched, bool ALIGN_EPI = false, bool SP2 = false>
; __device__ __forceinline__ void gemm_phase(PG8_LAS unsigned char* lds, const Gemm g, const Sched& S, const Epi& E) {
;     ...
;             PG8_LDA(At, 1, 1); PG8_STAGE(PG8_SB(1, 0), b3, voffB); PG8_STAGE(PG8_SB(1, 1), b3 + hstepB, voffB); PG8_STAGE(PG8_SA(1, 0), a3, voffA);
;             PG8_WAIT_V(8); PG8_WAIT_L(0); PG8_BAR; PG8_MMA(1, 0, At, B0); PG8_MMA(1, 1, At, B1); PG8_BAR; PG8_SCHED;
;     ...
;         if constexpr (ALIGN_EPI) { if (wr == 0) PG8_BAR; }
	s_setprio 0
	s_add_i32 s58, s64, s6
	v_lshl_add_u64 v[226:227], v[226:227], 0, s[20:21]
	s_mov_b32 m0, s58
	ds_read_b128 v[194:197], v154 offset:49152
	ds_read_b128 v[198:201], v154 offset:50176
	ds_read_b128 v[202:205], v154 offset:51200
	ds_read_b128 v[206:209], v154 offset:52224
	ds_read_b128 v[210:213], v154 offset:53248
	ds_read_b128 v[214:217], v154 offset:54272
	ds_read_b128 v[218:221], v154 offset:55296
	ds_read_b128 v[222:225], v154 offset:56320
	global_load_lds_dwordx4 v[226:227], off
	s_add_i32 m0, s58, 0x2000
	s_add_u32 s52, s52, 0x80080
	v_lshl_add_u64 v[226:227], v[228:229], 0, s[20:21]
	s_addc_u32 s53, s53, 0
	s_add_i32 s58, s65, s6
	global_load_lds_dwordx4 v[226:227], off
	v_lshl_add_u64 v[226:227], s[52:53], 0, v[130:131]
	s_mov_b32 m0, s58
	s_nop 0
	global_load_lds_dwordx4 v[226:227], off
	v_lshl_add_u64 v[226:227], s[52:53], 0, v[134:135]
	s_add_i32 m0, s58, 0x2000
	s_nop 0
	global_load_lds_dwordx4 v[226:227], off
	v_lshl_add_u64 v[226:227], v[230:231], 0, s[20:21]
	s_mov_b32 m0, s46
	s_nop 0
	global_load_lds_dwordx4 v[226:227], off
	v_lshl_add_u64 v[226:227], v[232:233], 0, s[20:21]
	s_mov_b32 m0, s47
	s_nop 0
	global_load_lds_dwordx4 v[226:227], off
	s_waitcnt vmcnt(8)
	s_waitcnt lgkmcnt(0)
	s_setprio 1
	s_barrier
	v_mfma_f32_16x16x32_bf16 v[60:63], v[156:159], v[194:197], v[60:63]
	v_mfma_f32_16x16x32_bf16 v[56:59], v[164:167], v[194:197], v[56:59]
	v_mfma_f32_16x16x32_bf16 v[44:47], v[156:159], v[202:205], v[44:47]
	v_mfma_f32_16x16x32_bf16 v[40:43], v[164:167], v[202:205], v[40:43]
	v_mfma_f32_16x16x32_bf16 v[28:31], v[156:159], v[210:213], v[28:31]
	v_mfma_f32_16x16x32_bf16 v[24:27], v[164:167], v[210:213], v[24:27]
	v_mfma_f32_16x16x32_bf16 v[12:15], v[156:159], v[218:221], v[12:15]
	v_mfma_f32_16x16x32_bf16 v[8:11], v[164:167], v[218:221], v[8:11]
	v_mfma_f32_16x16x32_bf16 v[60:63], v[160:163], v[198:201], v[60:63]
	v_mfma_f32_16x16x32_bf16 v[56:59], v[168:171], v[198:201], v[56:59]
	v_mfma_f32_16x16x32_bf16 v[44:47], v[160:163], v[206:209], v[44:47]
	v_mfma_f32_16x16x32_bf16 v[40:43], v[168:171], v[206:209], v[40:43]
	v_mfma_f32_16x16x32_bf16 v[28:31], v[160:163], v[214:217], v[28:31]
	v_mfma_f32_16x16x32_bf16 v[24:27], v[168:171], v[214:217], v[24:27]
	v_mfma_f32_16x16x32_bf16 v[12:15], v[160:163], v[222:225], v[12:15]
	v_mfma_f32_16x16x32_bf16 v[8:11], v[168:171], v[222:225], v[8:11]
	s_setprio 0
	s_setprio 1
	v_mfma_f32_16x16x32_bf16 v[52:55], v[172:175], v[194:197], v[52:55]
	v_mfma_f32_16x16x32_bf16 v[48:51], v[180:183], v[194:197], v[48:51]
	v_mfma_f32_16x16x32_bf16 v[36:39], v[172:175], v[202:205], v[36:39]
	v_mfma_f32_16x16x32_bf16 v[32:35], v[180:183], v[202:205], v[32:35]
	v_mfma_f32_16x16x32_bf16 v[20:23], v[172:175], v[210:213], v[20:23]
	v_mfma_f32_16x16x32_bf16 v[16:19], v[180:183], v[210:213], v[16:19]
	v_mfma_f32_16x16x32_bf16 v[4:7], v[172:175], v[218:221], v[4:7]
	v_mfma_f32_16x16x32_bf16 v[0:3], v[180:183], v[218:221], v[0:3]
	v_mfma_f32_16x16x32_bf16 v[52:55], v[176:179], v[198:201], v[52:55]
	v_mfma_f32_16x16x32_bf16 v[48:51], v[190:193], v[198:201], v[48:51]
	v_mfma_f32_16x16x32_bf16 v[36:39], v[176:179], v[206:209], v[36:39]
	v_mfma_f32_16x16x32_bf16 v[32:35], v[190:193], v[206:209], v[32:35]
	v_mfma_f32_16x16x32_bf16 v[20:23], v[176:179], v[214:217], v[20:23]
	v_mfma_f32_16x16x32_bf16 v[16:19], v[190:193], v[214:217], v[16:19]
	v_mfma_f32_16x16x32_bf16 v[4:7], v[176:179], v[222:225], v[4:7]
	v_mfma_f32_16x16x32_bf16 v[0:3], v[190:193], v[222:225], v[0:3]
	s_barrier
	s_setprio 0
	s_add_i32 s63, s63, 2
	s_add_u32 s50, s50, 0x100
	s_addc_u32 s51, s51, 0
	s_add_u32 s39, s39, 0x100
	s_addc_u32 s41, s41, 0
	s_cmp_gt_u32 s63, 29
	s_cbranch_scc0 .LBB0_1657
	s_and_b64 vcc, exec, s[34:35]
	s_cbranch_vccz .LBB0_1660
	s_barrier

; #define PG8_STAGE(bufoff, gbase, voff) do { _Pragma("unroll") for (int _i = 0; _i < 2; ++_i) \
;         __builtin_amdgcn_global_load_lds((const unsigned*)((const char*)(gbase) + (voff)[_i]), (PG8_LAS unsigned*)(lds + (bufoff) + ldsw + _i * 8192), 16, 0, 0); } while (0)
; #define PG8_LDA(dst, b, h) do { _Pragma("unroll") for (int m = 0; m < 4; ++m) _Pragma("unroll") for (int k = 0; k < 2; ++k) dst[m][k] = *(const PG8_LAS bf16x8*)(lds + PG8_SA(b, h) + aoff + m * 2048 + k * 1024); } while (0)
; #define PG8_LDB(dst, b, h) do { _Pragma("unroll") for (int n = 0; n < 2; ++n) _Pragma("unroll") for (int k = 0; k < 2; ++k) dst[n][k] = *(const PG8_LAS bf16x8*)(lds + PG8_SB(b, h) + boff + n * 2048 + k * 1024); } while (0)
; #define PG8_MMA(ai, bj, At, Bt) do { __builtin_amdgcn_s_setprio(1); _Pragma("unroll") for (int m = 0; m < 4; ++m) _Pragma("unroll") for (int n = 0; n < 2; ++n) _Pragma("unroll") for (int k = 0; k < 2; ++k) \
;         acc[ai][bj][m][n] = __builtin_amdgcn_mfma_f32_16x16x32_bf16(Bt[n][k], At[m][k], acc[ai][bj][m][n], 0, 0, 0); __builtin_amdgcn_s_setprio(0); } while (0)
; #define PG8_WAIT_V(n) asm volatile("s_waitcnt vmcnt(" #n ")" ::: "memory")
; #define PG8_BAR __builtin_amdgcn_s_barrier()
; template <class Epi, class Sched, bool ALIGN_EPI = false, bool SP2 = false>
; __device__ __forceinline__ void gemm_phase(PG8_LAS unsigned char* lds, const Gemm g, const Sched& S, const Epi& E) {
;     ...
;         for (int t = 0; t < nt; t += 2) {
;             const bool last = (t == nt - 2);
;             const char* a1 = cA + (size_t)(t + 1) * kstA;
;             const char* a2 = last ? nA : cA + (size_t)(t + 2) * kstA; const char* b2 = last ? nB : cB + (size_t)(t + 2) * kstep;
;             const char* a3 = a2 + kstA; const char* b3 = b2 + kstep;
;             if (last && has_next) S.a_ready(nxt);
;             if constexpr (SP2) {
;             PG8_LDB(B0, 0, 0); PG8_LDB(B1, 0, 1); PG8_SCHED; PG8_LDA(At, 0, 0); PG8_STAGE(PG8_SA(1, 1), a1 + hstepA, voffA);
;             PG8_WAIT_V(8); PG8_WAIT_L(0); PG8_BAR; PG8_MMA(0, 0, At, B0); PG8_MMA(0, 1, At, B1); PG8_BAR; PG8_SCHED;
;             PG8_LDA(At, 0, 1); PG8_STAGE(PG8_SB(0, 0), b2, voffB); PG8_STAGE(PG8_SB(0, 1), b2 + hstepB, voffB); PG8_STAGE(PG8_SA(0, 0), a2, voffA);
;             PG8_WAIT_V(8); PG8_WAIT_L(0); PG8_BAR; PG8_MMA(1, 0, At, B0); PG8_MMA(1, 1, At, B1); PG8_BAR; PG8_SCHED;
.LBB0_1754:
	s_or_b32 s44, s62, 1
	s_add_i32 s62, s62, 2
	s_mov_b32 s63, s45
	s_lshl_b64 s[4:5], s[44:45], 15
	s_lshl_b64 s[6:7], s[62:63], 15
	s_add_u32 s12, s34, s6
	v_add_u32_e32 v170, s10, v177
	v_add_u32_e32 v174, s11, v177
	s_addc_u32 s13, s35, s7
	ds_read_b128 v[158:161], v170
	ds_read_b128 v[162:165], v170 offset:1024
	ds_read_b128 v[166:169], v170 offset:2048
	ds_read_b128 v[170:173], v170 offset:3072
	ds_read_b128 v[180:183], v174
	ds_read_b128 v[190:193], v174 offset:1024
	ds_read_b128 v[194:197], v174 offset:2048
	ds_read_b128 v[198:201], v174 offset:3072
	s_and_b64 s[6:7], s[50:51], exec
	s_cselect_b32 s69, s13, s59
	s_cselect_b32 s68, s12, s58
	s_lshl_b64 s[6:7], s[62:63], 7
	s_add_u32 s12, s40, s6
	s_addc_u32 s13, s41, s7
	s_and_b64 s[6:7], s[50:51], exec
	s_cselect_b32 s53, s13, s61
	s_cselect_b32 s52, s12, s60
	s_add_u32 s50, s68, 0x8000
	s_addc_u32 s51, s69, 0
	s_add_u32 s4, s21, s4
	s_addc_u32 s5, s39, s5
	v_lshl_add_u64 v[174:175], s[4:5], 0, v[128:129]
	s_add_i32 m0, s74, 0xc000
	ds_read_b128 v[202:205], v179
	ds_read_b128 v[206:209], v179 offset:1024
	ds_read_b128 v[210:213], v179 offset:2048
	ds_read_b128 v[214:217], v179 offset:3072
	ds_read_b128 v[218:221], v179 offset:4096
	ds_read_b128 v[222:225], v179 offset:5120
	ds_read_b128 v[226:229], v179 offset:6144
	ds_read_b128 v[230:233], v179 offset:7168
	global_load_lds_dwordx4 v[174:175], off
	v_lshl_add_u64 v[174:175], s[4:5], 0, v[132:133]
	s_add_i32 m0, s74, 0xe000
	s_nop 0
	global_load_lds_dwordx4 v[174:175], off
	s_waitcnt vmcnt(8)
	s_waitcnt lgkmcnt(0)
	s_setprio 1
	s_barrier
	v_mfma_f32_16x16x32_bf16 v[124:127], v[158:161], v[202:205], v[124:127]
	v_mfma_f32_16x16x32_bf16 v[120:123], v[166:169], v[202:205], v[120:123]
	v_mfma_f32_16x16x32_bf16 v[116:119], v[158:161], v[210:213], v[116:119]
	v_mfma_f32_16x16x32_bf16 v[112:115], v[166:169], v[210:213], v[112:115]
	v_mfma_f32_16x16x32_bf16 v[108:111], v[158:161], v[218:221], v[108:111]
	v_mfma_f32_16x16x32_bf16 v[104:107], v[166:169], v[218:221], v[104:107]
	v_mfma_f32_16x16x32_bf16 v[100:103], v[158:161], v[226:229], v[100:103]
	v_mfma_f32_16x16x32_bf16 v[96:99], v[166:169], v[226:229], v[96:99]
	v_mfma_f32_16x16x32_bf16 v[124:127], v[162:165], v[206:209], v[124:127]
	v_mfma_f32_16x16x32_bf16 v[120:123], v[170:173], v[206:209], v[120:123]
	v_mfma_f32_16x16x32_bf16 v[116:119], v[162:165], v[214:217], v[116:119]
	v_mfma_f32_16x16x32_bf16 v[112:115], v[170:173], v[214:217], v[112:115]
	v_mfma_f32_16x16x32_bf16 v[108:111], v[162:165], v[222:225], v[108:111]
	v_mfma_f32_16x16x32_bf16 v[104:107], v[170:173], v[222:225], v[104:107]
	v_mfma_f32_16x16x32_bf16 v[100:103], v[162:165], v[230:233], v[100:103]
	v_mfma_f32_16x16x32_bf16 v[96:99], v[170:173], v[230:233], v[96:99]
	s_setprio 0
	s_setprio 1
	v_mfma_f32_16x16x32_bf16 v[92:95], v[180:183], v[202:205], v[92:95]
	v_mfma_f32_16x16x32_bf16 v[88:91], v[194:197], v[202:205], v[88:91]
	v_mfma_f32_16x16x32_bf16 v[84:87], v[180:183], v[210:213], v[84:87]
	v_mfma_f32_16x16x32_bf16 v[80:83], v[194:197], v[210:213], v[80:83]
	v_mfma_f32_16x16x32_bf16 v[76:79], v[180:183], v[218:221], v[76:79]
	v_mfma_f32_16x16x32_bf16 v[72:75], v[194:197], v[218:221], v[72:75]
	v_mfma_f32_16x16x32_bf16 v[68:71], v[180:183], v[226:229], v[68:71]
	v_mfma_f32_16x16x32_bf16 v[64:67], v[194:197], v[226:229], v[64:67]
	v_mfma_f32_16x16x32_bf16 v[92:95], v[190:193], v[206:209], v[92:95]
	v_mfma_f32_16x16x32_bf16 v[88:91], v[198:201], v[206:209], v[88:91]
	v_mfma_f32_16x16x32_bf16 v[84:87], v[190:193], v[214:217], v[84:87]
	v_mfma_f32_16x16x32_bf16 v[80:83], v[198:201], v[214:217], v[80:83]
	v_mfma_f32_16x16x32_bf16 v[76:79], v[190:193], v[222:225], v[76:79]
	v_mfma_f32_16x16x32_bf16 v[72:75], v[198:201], v[222:225], v[72:75]
	v_mfma_f32_16x16x32_bf16 v[68:71], v[190:193], v[230:233], v[68:71]
	v_mfma_f32_16x16x32_bf16 v[64:67], v[198:201], v[230:233], v[64:67]
	s_barrier
	s_setprio 0
	s_add_i32 s4, s10, s71
	v_lshl_add_u64 v[174:175], s[52:53], 0, v[130:131]
	s_mov_b32 m0, s4
	ds_read_b128 v[202:205], v179 offset:16384
	ds_read_b128 v[206:209], v179 offset:17408
	ds_read_b128 v[210:213], v179 offset:18432
	ds_read_b128 v[214:217], v179 offset:19456
	ds_read_b128 v[218:221], v179 offset:20480
	ds_read_b128 v[222:225], v179 offset:21504
	ds_read_b128 v[226:229], v179 offset:22528
	ds_read_b128 v[230:233], v179 offset:23552
	global_load_lds_dwordx4 v[174:175], off
	s_add_i32 m0, s4, 0x2000
	s_add_u32 s4, s52, 0x160000
	v_lshl_add_u64 v[234:235], s[52:53], 0, v[134:135]
	s_addc_u32 s5, s53, 0
	s_add_i32 s6, s11, s71
	global_load_lds_dwordx4 v[234:235], off
	v_lshl_add_u64 v[236:237], s[4:5], 0, v[130:131]
	s_mov_b32 m0, s6
	s_nop 0
	global_load_lds_dwordx4 v[236:237], off
	v_lshl_add_u64 v[236:237], s[4:5], 0, v[134:135]
	s_add_i32 m0, s6, 0x2000
	s_nop 0
	global_load_lds_dwordx4 v[236:237], off
	v_lshl_add_u64 v[236:237], s[68:69], 0, v[128:129]
	s_mov_b32 m0, s74
	s_nop 0
	global_load_lds_dwordx4 v[236:237], off
	v_lshl_add_u64 v[236:237], s[68:69], 0, v[132:133]
	s_mov_b32 m0, s76
	s_nop 0
	global_load_lds_dwordx4 v[236:237], off
	s_waitcnt vmcnt(8)
	s_waitcnt lgkmcnt(0)
	s_setprio 1
	s_barrier
; #define PG8_STAGE(bufoff, gbase, voff) do { _Pragma("unroll") for (int _i = 0; _i < 2; ++_i) \
;         __builtin_amdgcn_global_load_lds((const unsigned*)((const char*)(gbase) + (voff)[_i]), (PG8_LAS unsigned*)(lds + (bufoff) + ldsw + _i * 8192), 16, 0, 0); } while (0)
; #define PG8_LDA(dst, b, h) do { _Pragma("unroll") for (int m = 0; m < 4; ++m) _Pragma("unroll") for (int k = 0; k < 2; ++k) dst[m][k] = *(const PG8_LAS bf16x8*)(lds + PG8_SA(b, h) + aoff + m * 2048 + k * 1024); } while (0)
; #define PG8_LDB(dst, b, h) do { _Pragma("unroll") for (int n = 0; n < 2; ++n) _Pragma("unroll") for (int k = 0; k < 2; ++k) dst[n][k] = *(const PG8_LAS bf16x8*)(lds + PG8_SB(b, h) + boff + n * 2048 + k * 1024); } while (0)
; #define PG8_MMA(ai, bj, At, Bt) do { __builtin_amdgcn_s_setprio(1); _Pragma("unroll") for (int m = 0; m < 4; ++m) _Pragma("unroll") for (int n = 0; n < 2; ++n) _Pragma("unroll") for (int k = 0; k < 2; ++k) \
;         acc[ai][bj][m][n] = __builtin_amdgcn_mfma_f32_16x16x32_bf16(Bt[n][k], At[m][k], acc[ai][bj][m][n], 0, 0, 0); __builtin_amdgcn_s_setprio(0); } while (0)
; #define PG8_WAIT_V(n) asm volatile("s_waitcnt vmcnt(" #n ")" ::: "memory")
; #define PG8_WAIT_L(n) asm volatile("s_waitcnt lgkmcnt(" #n ")" ::: "memory")
; #define PG8_BAR __builtin_amdgcn_s_barrier()
; #define PG8_SCHED __builtin_amdgcn_sched_barrier(0)
; template <class Epi, class Sched, bool ALIGN_EPI = false, bool SP2 = false>
; __device__ __forceinline__ void gemm_phase(PG8_LAS unsigned char* lds, const Gemm g, const Sched& S, const Epi& E) {
;     ...
;             PG8_WAIT_V(8); PG8_WAIT_L(0); PG8_BAR; PG8_MMA(1, 0, At, B0); PG8_MMA(1, 1, At, B1); PG8_BAR; PG8_SCHED;
;             PG8_LDB(B0, 1, 0); PG8_LDB(B1, 1, 1); PG8_SCHED; PG8_LDA(At, 1, 0); PG8_STAGE(PG8_SA(0, 1), a2 + hstepA, voffA);
;             PG8_WAIT_V(8); PG8_WAIT_L(0); PG8_BAR; PG8_MMA(0, 0, At, B0); PG8_MMA(0, 1, At, B1); PG8_BAR; PG8_SCHED;
	v_mfma_f32_16x16x32_bf16 v[60:63], v[158:161], v[202:205], v[60:63]
	v_mfma_f32_16x16x32_bf16 v[56:59], v[166:169], v[202:205], v[56:59]
	v_mfma_f32_16x16x32_bf16 v[52:55], v[158:161], v[210:213], v[52:55]
	v_mfma_f32_16x16x32_bf16 v[48:51], v[166:169], v[210:213], v[48:51]
	v_mfma_f32_16x16x32_bf16 v[44:47], v[158:161], v[218:221], v[44:47]
	v_mfma_f32_16x16x32_bf16 v[40:43], v[166:169], v[218:221], v[40:43]
	v_mfma_f32_16x16x32_bf16 v[36:39], v[158:161], v[226:229], v[36:39]
	v_mfma_f32_16x16x32_bf16 v[32:35], v[166:169], v[226:229], v[32:35]
	v_mfma_f32_16x16x32_bf16 v[60:63], v[162:165], v[206:209], v[60:63]
	v_mfma_f32_16x16x32_bf16 v[56:59], v[170:173], v[206:209], v[56:59]
	v_mfma_f32_16x16x32_bf16 v[52:55], v[162:165], v[214:217], v[52:55]
	v_mfma_f32_16x16x32_bf16 v[48:51], v[170:173], v[214:217], v[48:51]
	v_mfma_f32_16x16x32_bf16 v[44:47], v[162:165], v[222:225], v[44:47]
	v_mfma_f32_16x16x32_bf16 v[40:43], v[170:173], v[222:225], v[40:43]
	v_mfma_f32_16x16x32_bf16 v[36:39], v[162:165], v[230:233], v[36:39]
	v_mfma_f32_16x16x32_bf16 v[32:35], v[170:173], v[230:233], v[32:35]
	s_setprio 0
	s_setprio 1
	v_mfma_f32_16x16x32_bf16 v[28:31], v[180:183], v[202:205], v[28:31]
	v_mfma_f32_16x16x32_bf16 v[24:27], v[194:197], v[202:205], v[24:27]
	v_mfma_f32_16x16x32_bf16 v[20:23], v[180:183], v[210:213], v[20:23]
	v_mfma_f32_16x16x32_bf16 v[16:19], v[194:197], v[210:213], v[16:19]
	v_mfma_f32_16x16x32_bf16 v[12:15], v[180:183], v[218:221], v[12:15]
	v_mfma_f32_16x16x32_bf16 v[8:11], v[194:197], v[218:221], v[8:11]
	v_mfma_f32_16x16x32_bf16 v[4:7], v[180:183], v[226:229], v[4:7]
	v_mfma_f32_16x16x32_bf16 v[0:3], v[194:197], v[226:229], v[0:3]
	v_mfma_f32_16x16x32_bf16 v[28:31], v[190:193], v[206:209], v[28:31]
	v_mfma_f32_16x16x32_bf16 v[24:27], v[198:201], v[206:209], v[24:27]
	v_mfma_f32_16x16x32_bf16 v[20:23], v[190:193], v[214:217], v[20:23]
	v_mfma_f32_16x16x32_bf16 v[16:19], v[198:201], v[214:217], v[16:19]
	v_mfma_f32_16x16x32_bf16 v[12:15], v[190:193], v[222:225], v[12:15]
	v_mfma_f32_16x16x32_bf16 v[8:11], v[198:201], v[222:225], v[8:11]
	v_mfma_f32_16x16x32_bf16 v[4:7], v[190:193], v[230:233], v[4:7]
	v_mfma_f32_16x16x32_bf16 v[0:3], v[198:201], v[230:233], v[0:3]
	s_barrier
	s_setprio 0
	s_add_i32 s6, 0, 0x18000
	s_add_i32 s7, 0, 0x1c000
	v_add_u32_e32 v170, s6, v177
	v_add_u32_e32 v198, s7, v177
	ds_read_b128 v[158:161], v170
	ds_read_b128 v[162:165], v170 offset:1024
	ds_read_b128 v[166:169], v170 offset:2048
	ds_read_b128 v[170:173], v170 offset:3072
	ds_read_b128 v[180:183], v198
	ds_read_b128 v[190:193], v198 offset:1024
	ds_read_b128 v[194:197], v198 offset:2048
	ds_read_b128 v[198:201], v198 offset:3072
	s_add_u32 s4, s68, 0x4000
	s_addc_u32 s5, s69, 0
	s_mov_b32 m0, s77
	v_lshl_add_u64 v[236:237], s[4:5], 0, v[128:129]
	ds_read_b128 v[202:205], v179 offset:32768
	ds_read_b128 v[206:209], v179 offset:33792
	ds_read_b128 v[210:213], v179 offset:34816
	ds_read_b128 v[214:217], v179 offset:35840
	ds_read_b128 v[218:221], v179 offset:36864
	ds_read_b128 v[222:225], v179 offset:37888
	ds_read_b128 v[226:229], v179 offset:38912
	ds_read_b128 v[230:233], v179 offset:39936
	global_load_lds_dwordx4 v[236:237], off
	v_lshl_add_u64 v[236:237], s[4:5], 0, v[132:133]
	s_mov_b32 m0, s75
	s_nop 0
	global_load_lds_dwordx4 v[236:237], off
	s_waitcnt vmcnt(8)
	s_waitcnt lgkmcnt(0)
	s_setprio 1
	s_barrier
	v_mfma_f32_16x16x32_bf16 v[124:127], v[158:161], v[202:205], v[124:127]
	v_mfma_f32_16x16x32_bf16 v[120:123], v[166:169], v[202:205], v[120:123]
	v_mfma_f32_16x16x32_bf16 v[116:119], v[158:161], v[210:213], v[116:119]
	v_mfma_f32_16x16x32_bf16 v[112:115], v[166:169], v[210:213], v[112:115]
	v_mfma_f32_16x16x32_bf16 v[108:111], v[158:161], v[218:221], v[108:111]
	v_mfma_f32_16x16x32_bf16 v[104:107], v[166:169], v[218:221], v[104:107]
	v_mfma_f32_16x16x32_bf16 v[100:103], v[158:161], v[226:229], v[100:103]
	v_mfma_f32_16x16x32_bf16 v[96:99], v[166:169], v[226:229], v[96:99]
	v_mfma_f32_16x16x32_bf16 v[124:127], v[162:165], v[206:209], v[124:127]
	v_mfma_f32_16x16x32_bf16 v[120:123], v[170:173], v[206:209], v[120:123]
	v_mfma_f32_16x16x32_bf16 v[116:119], v[162:165], v[214:217], v[116:119]
	v_mfma_f32_16x16x32_bf16 v[112:115], v[170:173], v[214:217], v[112:115]
	v_mfma_f32_16x16x32_bf16 v[108:111], v[162:165], v[222:225], v[108:111]
	v_mfma_f32_16x16x32_bf16 v[104:107], v[170:173], v[222:225], v[104:107]
	v_mfma_f32_16x16x32_bf16 v[100:103], v[162:165], v[230:233], v[100:103]
	v_mfma_f32_16x16x32_bf16 v[96:99], v[170:173], v[230:233], v[96:99]
	s_setprio 0
	s_setprio 1
	v_mfma_f32_16x16x32_bf16 v[92:95], v[180:183], v[202:205], v[92:95]
	v_mfma_f32_16x16x32_bf16 v[88:91], v[194:197], v[202:205], v[88:91]
	v_mfma_f32_16x16x32_bf16 v[84:87], v[180:183], v[210:213], v[84:87]
	v_mfma_f32_16x16x32_bf16 v[80:83], v[194:197], v[210:213], v[80:83]
	v_mfma_f32_16x16x32_bf16 v[76:79], v[180:183], v[218:221], v[76:79]
	v_mfma_f32_16x16x32_bf16 v[72:75], v[194:197], v[218:221], v[72:75]
	v_mfma_f32_16x16x32_bf16 v[68:71], v[180:183], v[226:229], v[68:71]
	v_mfma_f32_16x16x32_bf16 v[64:67], v[194:197], v[226:229], v[64:67]
	v_mfma_f32_16x16x32_bf16 v[92:95], v[190:193], v[206:209], v[92:95]
	v_mfma_f32_16x16x32_bf16 v[88:91], v[198:201], v[206:209], v[88:91]
	v_mfma_f32_16x16x32_bf16 v[84:87], v[190:193], v[214:217], v[84:87]
	v_mfma_f32_16x16x32_bf16 v[80:83], v[198:201], v[214:217], v[80:83]
	v_mfma_f32_16x16x32_bf16 v[76:79], v[190:193], v[222:225], v[76:79]
	v_mfma_f32_16x16x32_bf16 v[72:75], v[198:201], v[222:225], v[72:75]
	v_mfma_f32_16x16x32_bf16 v[68:71], v[190:193], v[230:233], v[68:71]
	v_mfma_f32_16x16x32_bf16 v[64:67], v[198:201], v[230:233], v[64:67]
	s_barrier
; #define PG8_STAGE(bufoff, gbase, voff) do { _Pragma("unroll") for (int _i = 0; _i < 2; ++_i) \
;         __builtin_amdgcn_global_load_lds((const unsigned*)((const char*)(gbase) + (voff)[_i]), (PG8_LAS unsigned*)(lds + (bufoff) + ldsw + _i * 8192), 16, 0, 0); } while (0)
; #define PG8_LDA(dst, b, h) do { _Pragma("unroll") for (int m = 0; m < 4; ++m) _Pragma("unroll") for (int k = 0; k < 2; ++k) dst[m][k] = *(const PG8_LAS bf16x8*)(lds + PG8_SA(b, h) + aoff + m * 2048 + k * 1024); } while (0)
; #define PG8_MMA(ai, bj, At, Bt) do { __builtin_amdgcn_s_setprio(1); _Pragma("unroll") for (int m = 0; m < 4; ++m) _Pragma("unroll") for (int n = 0; n < 2; ++n) _Pragma("unroll") for (int k = 0; k < 2; ++k) \
;         acc[ai][bj][m][n] = __builtin_amdgcn_mfma_f32_16x16x32_bf16(Bt[n][k], At[m][k], acc[ai][bj][m][n], 0, 0, 0); __builtin_amdgcn_s_setprio(0); } while (0)
; #define PG8_WAIT_V(n) asm volatile("s_waitcnt vmcnt(" #n ")" ::: "memory")
; #define PG8_WAIT_L(n) asm volatile("s_waitcnt lgkmcnt(" #n ")" ::: "memory")
; #define PG8_BAR __builtin_amdgcn_s_barrier()
; #define PG8_SCHED __builtin_amdgcn_sched_barrier(0)
; template <class Epi, class Sched, bool ALIGN_EPI = false, bool SP2 = false>
; __device__ __forceinline__ void gemm_phase(PG8_LAS unsigned char* lds, const Gemm g, const Sched& S, const Epi& E) {
;     ...
;         for (int t = 0; t < nt; t += 2) {
;     ...
;             PG8_LDA(At, 1, 1); PG8_STAGE(PG8_SB(1, 0), b3, voffB); PG8_STAGE(PG8_SB(1, 1), b3 + hstepB, voffB); PG8_STAGE(PG8_SA(1, 0), a3, voffA);
;             PG8_WAIT_V(8); PG8_WAIT_L(0); PG8_BAR; PG8_MMA(1, 0, At, B0); PG8_MMA(1, 1, At, B1); PG8_BAR; PG8_SCHED;
	s_setprio 0
	s_add_i32 s4, s6, s71
	v_lshl_add_u64 v[174:175], v[174:175], 0, s[54:55]
	s_mov_b32 m0, s4
	ds_read_b128 v[202:205], v179 offset:49152
	ds_read_b128 v[206:209], v179 offset:50176
	ds_read_b128 v[210:213], v179 offset:51200
	ds_read_b128 v[214:217], v179 offset:52224
	ds_read_b128 v[218:221], v179 offset:53248
	ds_read_b128 v[222:225], v179 offset:54272
	ds_read_b128 v[226:229], v179 offset:55296
	ds_read_b128 v[230:233], v179 offset:56320
	global_load_lds_dwordx4 v[174:175], off
	s_add_i32 m0, s4, 0x2000
	s_add_u32 s4, s52, 0x160080
	v_lshl_add_u64 v[174:175], v[234:235], 0, s[54:55]
	s_addc_u32 s5, s53, 0
	s_add_i32 s6, s7, s71
	global_load_lds_dwordx4 v[174:175], off
	v_lshl_add_u64 v[174:175], s[4:5], 0, v[130:131]
	s_mov_b32 m0, s6
	s_nop 0
	global_load_lds_dwordx4 v[174:175], off
	v_lshl_add_u64 v[174:175], s[4:5], 0, v[134:135]
	s_add_i32 m0, s6, 0x2000
	s_nop 0
	global_load_lds_dwordx4 v[174:175], off
	v_lshl_add_u64 v[174:175], s[50:51], 0, v[128:129]
	s_mov_b32 m0, s95
	s_nop 0
	global_load_lds_dwordx4 v[174:175], off
	v_lshl_add_u64 v[174:175], s[50:51], 0, v[132:133]
	s_mov_b32 m0, s96
	s_nop 0
	global_load_lds_dwordx4 v[174:175], off
	s_waitcnt vmcnt(8)
	s_waitcnt lgkmcnt(0)
	s_setprio 1
	s_barrier
	v_mfma_f32_16x16x32_bf16 v[60:63], v[158:161], v[202:205], v[60:63]
	v_mfma_f32_16x16x32_bf16 v[56:59], v[166:169], v[202:205], v[56:59]
	v_mfma_f32_16x16x32_bf16 v[52:55], v[158:161], v[210:213], v[52:55]
	v_mfma_f32_16x16x32_bf16 v[48:51], v[166:169], v[210:213], v[48:51]
	v_mfma_f32_16x16x32_bf16 v[44:47], v[158:161], v[218:221], v[44:47]
	v_mfma_f32_16x16x32_bf16 v[40:43], v[166:169], v[218:221], v[40:43]
	v_mfma_f32_16x16x32_bf16 v[36:39], v[158:161], v[226:229], v[36:39]
	v_mfma_f32_16x16x32_bf16 v[32:35], v[166:169], v[226:229], v[32:35]
	v_mfma_f32_16x16x32_bf16 v[60:63], v[162:165], v[206:209], v[60:63]
	v_mfma_f32_16x16x32_bf16 v[56:59], v[170:173], v[206:209], v[56:59]
	v_mfma_f32_16x16x32_bf16 v[52:55], v[162:165], v[214:217], v[52:55]
	v_mfma_f32_16x16x32_bf16 v[48:51], v[170:173], v[214:217], v[48:51]
	v_mfma_f32_16x16x32_bf16 v[44:47], v[162:165], v[222:225], v[44:47]
	v_mfma_f32_16x16x32_bf16 v[40:43], v[170:173], v[222:225], v[40:43]
	v_mfma_f32_16x16x32_bf16 v[36:39], v[162:165], v[230:233], v[36:39]
	v_mfma_f32_16x16x32_bf16 v[32:35], v[170:173], v[230:233], v[32:35]
	s_setprio 0
	s_setprio 1
	v_mfma_f32_16x16x32_bf16 v[28:31], v[180:183], v[202:205], v[28:31]
	v_mfma_f32_16x16x32_bf16 v[24:27], v[194:197], v[202:205], v[24:27]
	v_mfma_f32_16x16x32_bf16 v[20:23], v[180:183], v[210:213], v[20:23]
	v_mfma_f32_16x16x32_bf16 v[16:19], v[194:197], v[210:213], v[16:19]
	v_mfma_f32_16x16x32_bf16 v[12:15], v[180:183], v[218:221], v[12:15]
	v_mfma_f32_16x16x32_bf16 v[8:11], v[194:197], v[218:221], v[8:11]
	v_mfma_f32_16x16x32_bf16 v[4:7], v[180:183], v[226:229], v[4:7]
	v_mfma_f32_16x16x32_bf16 v[0:3], v[194:197], v[226:229], v[0:3]
	v_mfma_f32_16x16x32_bf16 v[28:31], v[190:193], v[206:209], v[28:31]
	v_mfma_f32_16x16x32_bf16 v[24:27], v[198:201], v[206:209], v[24:27]
	v_mfma_f32_16x16x32_bf16 v[20:23], v[190:193], v[214:217], v[20:23]
	v_mfma_f32_16x16x32_bf16 v[16:19], v[198:201], v[214:217], v[16:19]
	v_mfma_f32_16x16x32_bf16 v[12:15], v[190:193], v[222:225], v[12:15]
	v_mfma_f32_16x16x32_bf16 v[8:11], v[198:201], v[222:225], v[8:11]
	v_mfma_f32_16x16x32_bf16 v[4:7], v[190:193], v[230:233], v[4:7]
	v_mfma_f32_16x16x32_bf16 v[0:3], v[198:201], v[230:233], v[0:3]
	s_barrier
	s_setprio 0
	s_cmp_ge_i32 s62, s97
	s_cbranch_scc1 .LBB0_1766

; #define PG8_STAGE(bufoff, gbase, voff) do { _Pragma("unroll") for (int _i = 0; _i < 2; ++_i) \
;         __builtin_amdgcn_global_load_lds((const unsigned*)((const char*)(gbase) + (voff)[_i]), (PG8_LAS unsigned*)(lds + (bufoff) + ldsw + _i * 8192), 16, 0, 0); } while (0)
; #define PG8_LDA(dst, b, h) do { _Pragma("unroll") for (int m = 0; m < 4; ++m) _Pragma("unroll") for (int k = 0; k < 2; ++k) dst[m][k] = *(const PG8_LAS bf16x8*)(lds + PG8_SA(b, h) + aoff + m * 2048 + k * 1024); } while (0)
; #define PG8_LDB(dst, b, h) do { _Pragma("unroll") for (int n = 0; n < 2; ++n) _Pragma("unroll") for (int k = 0; k < 2; ++k) dst[n][k] = *(const PG8_LAS bf16x8*)(lds + PG8_SB(b, h) + boff + n * 2048 + k * 1024); } while (0)
; #define PG8_MMA(ai, bj, At, Bt) do { __builtin_amdgcn_s_setprio(1); _Pragma("unroll") for (int m = 0; m < 4; ++m) _Pragma("unroll") for (int n = 0; n < 2; ++n) _Pragma("unroll") for (int k = 0; k < 2; ++k) \
;         acc[ai][bj][m][n] = __builtin_amdgcn_mfma_f32_16x16x32_bf16(Bt[n][k], At[m][k], acc[ai][bj][m][n], 0, 0, 0); __builtin_amdgcn_s_setprio(0); } while (0)
; #define PG8_WAIT_V(n) asm volatile("s_waitcnt vmcnt(" #n ")" ::: "memory")
; #define PG8_WAIT_L(n) asm volatile("s_waitcnt lgkmcnt(" #n ")" ::: "memory")
; #define PG8_BAR __builtin_amdgcn_s_barrier()
; template <class Epi, class Sched, bool ALIGN_EPI = false, bool SP2 = false>
; __device__ __forceinline__ void gemm_phase(PG8_LAS unsigned char* lds, const Gemm g, const Sched& S, const Epi& E) {
;     ...
;             const char* a1 = cA + (size_t)(t + 1) * kstA;
;             const char* a2 = last ? nA : cA + (size_t)(t + 2) * kstA; const char* b2 = last ? nB : cB + (size_t)(t + 2) * kstep;
;             const char* a3 = a2 + kstA; const char* b3 = b2 + kstep;
;             if (last && has_next) S.a_ready(nxt);
;             if constexpr (SP2) {
;             PG8_LDB(B0, 0, 0); PG8_LDB(B1, 0, 1); PG8_SCHED; PG8_LDA(At, 0, 0); PG8_STAGE(PG8_SA(1, 1), a1 + hstepA, voffA);
;             PG8_WAIT_V(8); PG8_WAIT_L(0); PG8_BAR; PG8_MMA(0, 0, At, B0); PG8_MMA(0, 1, At, B1); PG8_BAR; PG8_SCHED;
;             PG8_LDA(At, 0, 1); PG8_STAGE(PG8_SB(0, 0), b2, voffB); PG8_STAGE(PG8_SB(0, 1), b2 + hstepB, voffB); PG8_STAGE(PG8_SA(0, 0), a2, voffA);
;             PG8_WAIT_V(8); PG8_WAIT_L(0); PG8_BAR; PG8_MMA(1, 0, At, B0); PG8_MMA(1, 1, At, B1); PG8_BAR; PG8_SCHED;
.LBB0_2050:
	ds_read_b128 v[128:131], v159
	ds_read_b128 v[132:135], v159 offset:1024
	ds_read_b128 v[164:167], v159 offset:2048
	ds_read_b128 v[168:171], v159 offset:3072
	ds_read_b128 v[172:175], v160
	ds_read_b128 v[176:179], v160 offset:1024
	ds_read_b128 v[180:183], v160 offset:2048
	ds_read_b128 v[190:193], v160 offset:3072
	s_add_u32 s13, s20, 0xfff80080
	s_addc_u32 s33, s21, -1
	s_cmp_eq_u32 s12, 28
	s_cselect_b32 s41, s1, s33
	s_cselect_b32 s40, s3, s13
	s_cselect_b32 s39, s4, s11
	s_cselect_b32 s38, s5, s10
	v_lshl_add_u64 v[226:227], s[20:21], 0, v[148:149]
	s_add_i32 m0, s7, 0xc000
	ds_read_b128 v[194:197], v161
	ds_read_b128 v[198:201], v161 offset:1024
	ds_read_b128 v[202:205], v161 offset:2048
	ds_read_b128 v[206:209], v161 offset:3072
	ds_read_b128 v[210:213], v161 offset:4096
	ds_read_b128 v[214:217], v161 offset:5120
	ds_read_b128 v[218:221], v161 offset:6144
	ds_read_b128 v[222:225], v161 offset:7168
	global_load_lds_dwordx4 v[226:227], off
	v_lshl_add_u64 v[226:227], s[20:21], 0, v[150:151]
	s_add_i32 m0, s7, 0xe000
	s_nop 0
	global_load_lds_dwordx4 v[226:227], off
	s_waitcnt vmcnt(8)
	s_waitcnt lgkmcnt(0)
	s_setprio 1
	s_barrier
	v_mfma_f32_16x16x32_bf16 v[124:127], v[128:131], v[194:197], v[124:127]
	v_mfma_f32_16x16x32_bf16 v[120:123], v[164:167], v[194:197], v[120:123]
	v_mfma_f32_16x16x32_bf16 v[108:111], v[128:131], v[202:205], v[108:111]
	v_mfma_f32_16x16x32_bf16 v[104:107], v[164:167], v[202:205], v[104:107]
	v_mfma_f32_16x16x32_bf16 v[92:95], v[128:131], v[210:213], v[92:95]
	v_mfma_f32_16x16x32_bf16 v[88:91], v[164:167], v[210:213], v[88:91]
	v_mfma_f32_16x16x32_bf16 v[76:79], v[128:131], v[218:221], v[76:79]
	v_mfma_f32_16x16x32_bf16 v[72:75], v[164:167], v[218:221], v[72:75]
	v_mfma_f32_16x16x32_bf16 v[124:127], v[132:135], v[198:201], v[124:127]
	v_mfma_f32_16x16x32_bf16 v[120:123], v[168:171], v[198:201], v[120:123]
	v_mfma_f32_16x16x32_bf16 v[108:111], v[132:135], v[206:209], v[108:111]
	v_mfma_f32_16x16x32_bf16 v[104:107], v[168:171], v[206:209], v[104:107]
	v_mfma_f32_16x16x32_bf16 v[92:95], v[132:135], v[214:217], v[92:95]
	v_mfma_f32_16x16x32_bf16 v[88:91], v[168:171], v[214:217], v[88:91]
	v_mfma_f32_16x16x32_bf16 v[76:79], v[132:135], v[222:225], v[76:79]
	v_mfma_f32_16x16x32_bf16 v[72:75], v[168:171], v[222:225], v[72:75]
	s_setprio 0
	s_setprio 1
	v_mfma_f32_16x16x32_bf16 v[116:119], v[172:175], v[194:197], v[116:119]
	v_mfma_f32_16x16x32_bf16 v[112:115], v[180:183], v[194:197], v[112:115]
	v_mfma_f32_16x16x32_bf16 v[100:103], v[172:175], v[202:205], v[100:103]
	v_mfma_f32_16x16x32_bf16 v[96:99], v[180:183], v[202:205], v[96:99]
	v_mfma_f32_16x16x32_bf16 v[84:87], v[172:175], v[210:213], v[84:87]
	v_mfma_f32_16x16x32_bf16 v[80:83], v[180:183], v[210:213], v[80:83]
	v_mfma_f32_16x16x32_bf16 v[68:71], v[172:175], v[218:221], v[68:71]
	v_mfma_f32_16x16x32_bf16 v[64:67], v[180:183], v[218:221], v[64:67]
	v_mfma_f32_16x16x32_bf16 v[116:119], v[176:179], v[198:201], v[116:119]
	v_mfma_f32_16x16x32_bf16 v[112:115], v[190:193], v[198:201], v[112:115]
	v_mfma_f32_16x16x32_bf16 v[100:103], v[176:179], v[206:209], v[100:103]
	v_mfma_f32_16x16x32_bf16 v[96:99], v[190:193], v[206:209], v[96:99]
	v_mfma_f32_16x16x32_bf16 v[84:87], v[176:179], v[214:217], v[84:87]
	v_mfma_f32_16x16x32_bf16 v[80:83], v[190:193], v[214:217], v[80:83]
	v_mfma_f32_16x16x32_bf16 v[68:71], v[176:179], v[222:225], v[68:71]
	v_mfma_f32_16x16x32_bf16 v[64:67], v[190:193], v[222:225], v[64:67]
	s_barrier
	s_setprio 0
	s_add_i32 s13, s69, s6
	v_lshl_add_u64 v[226:227], s[38:39], 0, v[138:139]
	s_mov_b32 m0, s13
	ds_read_b128 v[194:197], v161 offset:16384
	ds_read_b128 v[198:201], v161 offset:17408
	ds_read_b128 v[202:205], v161 offset:18432
	ds_read_b128 v[206:209], v161 offset:19456
	ds_read_b128 v[210:213], v161 offset:20480
	ds_read_b128 v[214:217], v161 offset:21504
	ds_read_b128 v[218:221], v161 offset:22528
	ds_read_b128 v[222:225], v161 offset:23552
	global_load_lds_dwordx4 v[226:227], off
	s_add_i32 m0, s13, 0x2000
	s_add_u32 s44, s38, 0x80000
	v_lshl_add_u64 v[228:229], s[38:39], 0, v[142:143]
	s_addc_u32 s45, s39, 0
	s_add_i32 s13, s70, s6
	global_load_lds_dwordx4 v[228:229], off
	v_lshl_add_u64 v[230:231], s[44:45], 0, v[138:139]
	s_mov_b32 m0, s13
	v_lshl_add_u64 v[232:233], s[40:41], 0, v[140:141]
	global_load_lds_dwordx4 v[230:231], off
	v_lshl_add_u64 v[230:231], s[44:45], 0, v[142:143]
	s_add_i32 m0, s13, 0x2000
	s_nop 0
	global_load_lds_dwordx4 v[230:231], off
	v_lshl_add_u64 v[230:231], s[40:41], 0, v[136:137]
	s_mov_b32 m0, s7
	s_nop 0
	global_load_lds_dwordx4 v[230:231], off
	s_mov_b32 m0, s8
	s_nop 0
	global_load_lds_dwordx4 v[232:233], off
	s_waitcnt vmcnt(8)
	s_waitcnt lgkmcnt(0)
	s_setprio 1
	s_barrier
; #define PG8_STAGE(bufoff, gbase, voff) do { _Pragma("unroll") for (int _i = 0; _i < 2; ++_i) \
;         __builtin_amdgcn_global_load_lds((const unsigned*)((const char*)(gbase) + (voff)[_i]), (PG8_LAS unsigned*)(lds + (bufoff) + ldsw + _i * 8192), 16, 0, 0); } while (0)
; #define PG8_LDA(dst, b, h) do { _Pragma("unroll") for (int m = 0; m < 4; ++m) _Pragma("unroll") for (int k = 0; k < 2; ++k) dst[m][k] = *(const PG8_LAS bf16x8*)(lds + PG8_SA(b, h) + aoff + m * 2048 + k * 1024); } while (0)
; #define PG8_LDB(dst, b, h) do { _Pragma("unroll") for (int n = 0; n < 2; ++n) _Pragma("unroll") for (int k = 0; k < 2; ++k) dst[n][k] = *(const PG8_LAS bf16x8*)(lds + PG8_SB(b, h) + boff + n * 2048 + k * 1024); } while (0)
; #define PG8_MMA(ai, bj, At, Bt) do { __builtin_amdgcn_s_setprio(1); _Pragma("unroll") for (int m = 0; m < 4; ++m) _Pragma("unroll") for (int n = 0; n < 2; ++n) _Pragma("unroll") for (int k = 0; k < 2; ++k) \
;         acc[ai][bj][m][n] = __builtin_amdgcn_mfma_f32_16x16x32_bf16(Bt[n][k], At[m][k], acc[ai][bj][m][n], 0, 0, 0); __builtin_amdgcn_s_setprio(0); } while (0)
; #define PG8_WAIT_V(n) asm volatile("s_waitcnt vmcnt(" #n ")" ::: "memory")
; #define PG8_WAIT_L(n) asm volatile("s_waitcnt lgkmcnt(" #n ")" ::: "memory")
; #define PG8_BAR __builtin_amdgcn_s_barrier()
; #define PG8_SCHED __builtin_amdgcn_sched_barrier(0)
; template <class Epi, class Sched, bool ALIGN_EPI = false, bool SP2 = false>
; __device__ __forceinline__ void gemm_phase(PG8_LAS unsigned char* lds, const Gemm g, const Sched& S, const Epi& E) {
;     ...
;             PG8_WAIT_V(8); PG8_WAIT_L(0); PG8_BAR; PG8_MMA(1, 0, At, B0); PG8_MMA(1, 1, At, B1); PG8_BAR; PG8_SCHED;
;             PG8_LDB(B0, 1, 0); PG8_LDB(B1, 1, 1); PG8_SCHED; PG8_LDA(At, 1, 0); PG8_STAGE(PG8_SA(0, 1), a2 + hstepA, voffA);
;             PG8_WAIT_V(8); PG8_WAIT_L(0); PG8_BAR; PG8_MMA(0, 0, At, B0); PG8_MMA(0, 1, At, B1); PG8_BAR; PG8_SCHED;
	v_mfma_f32_16x16x32_bf16 v[60:63], v[128:131], v[194:197], v[60:63]
	v_mfma_f32_16x16x32_bf16 v[56:59], v[164:167], v[194:197], v[56:59]
	v_mfma_f32_16x16x32_bf16 v[44:47], v[128:131], v[202:205], v[44:47]
	v_mfma_f32_16x16x32_bf16 v[40:43], v[164:167], v[202:205], v[40:43]
	v_mfma_f32_16x16x32_bf16 v[28:31], v[128:131], v[210:213], v[28:31]
	v_mfma_f32_16x16x32_bf16 v[24:27], v[164:167], v[210:213], v[24:27]
	v_mfma_f32_16x16x32_bf16 v[12:15], v[128:131], v[218:221], v[12:15]
	v_mfma_f32_16x16x32_bf16 v[8:11], v[164:167], v[218:221], v[8:11]
	v_mfma_f32_16x16x32_bf16 v[60:63], v[132:135], v[198:201], v[60:63]
	v_mfma_f32_16x16x32_bf16 v[56:59], v[168:171], v[198:201], v[56:59]
	v_mfma_f32_16x16x32_bf16 v[44:47], v[132:135], v[206:209], v[44:47]
	v_mfma_f32_16x16x32_bf16 v[40:43], v[168:171], v[206:209], v[40:43]
	v_mfma_f32_16x16x32_bf16 v[28:31], v[132:135], v[214:217], v[28:31]
	v_mfma_f32_16x16x32_bf16 v[24:27], v[168:171], v[214:217], v[24:27]
	v_mfma_f32_16x16x32_bf16 v[12:15], v[132:135], v[222:225], v[12:15]
	v_mfma_f32_16x16x32_bf16 v[8:11], v[168:171], v[222:225], v[8:11]
	s_setprio 0
	s_setprio 1
	v_mfma_f32_16x16x32_bf16 v[52:55], v[172:175], v[194:197], v[52:55]
	v_mfma_f32_16x16x32_bf16 v[48:51], v[180:183], v[194:197], v[48:51]
	v_mfma_f32_16x16x32_bf16 v[36:39], v[172:175], v[202:205], v[36:39]
	v_mfma_f32_16x16x32_bf16 v[32:35], v[180:183], v[202:205], v[32:35]
	v_mfma_f32_16x16x32_bf16 v[20:23], v[172:175], v[210:213], v[20:23]
	v_mfma_f32_16x16x32_bf16 v[16:19], v[180:183], v[210:213], v[16:19]
	v_mfma_f32_16x16x32_bf16 v[4:7], v[172:175], v[218:221], v[4:7]
	v_mfma_f32_16x16x32_bf16 v[0:3], v[180:183], v[218:221], v[0:3]
	v_mfma_f32_16x16x32_bf16 v[52:55], v[176:179], v[198:201], v[52:55]
	v_mfma_f32_16x16x32_bf16 v[48:51], v[190:193], v[198:201], v[48:51]
	v_mfma_f32_16x16x32_bf16 v[36:39], v[176:179], v[206:209], v[36:39]
	v_mfma_f32_16x16x32_bf16 v[32:35], v[190:193], v[206:209], v[32:35]
	v_mfma_f32_16x16x32_bf16 v[20:23], v[176:179], v[214:217], v[20:23]
	v_mfma_f32_16x16x32_bf16 v[16:19], v[190:193], v[214:217], v[16:19]
	v_mfma_f32_16x16x32_bf16 v[4:7], v[176:179], v[222:225], v[4:7]
	v_mfma_f32_16x16x32_bf16 v[0:3], v[190:193], v[222:225], v[0:3]
	s_barrier
	s_setprio 0
	s_add_i32 s13, 0, 0x18000
	v_add_u32_e32 v144, s13, v157
	s_add_i32 s33, 0, 0x1c000
	ds_read_b128 v[128:131], v144
	ds_read_b128 v[132:135], v144 offset:1024
	ds_read_b128 v[164:167], v144 offset:2048
	ds_read_b128 v[168:171], v144 offset:3072
	v_add_u32_e32 v144, s33, v157
	ds_read_b128 v[172:175], v144
	ds_read_b128 v[176:179], v144 offset:1024
	ds_read_b128 v[180:183], v144 offset:2048
	ds_read_b128 v[190:193], v144 offset:3072
	s_add_u32 s40, s40, 0x80000
	s_addc_u32 s41, s41, 0
	s_mov_b32 m0, s9
	v_lshl_add_u64 v[234:235], s[40:41], 0, v[136:137]
	ds_read_b128 v[194:197], v161 offset:32768
	ds_read_b128 v[198:201], v161 offset:33792
	ds_read_b128 v[202:205], v161 offset:34816
	ds_read_b128 v[206:209], v161 offset:35840
	ds_read_b128 v[210:213], v161 offset:36864
	ds_read_b128 v[214:217], v161 offset:37888
	ds_read_b128 v[218:221], v161 offset:38912
	ds_read_b128 v[222:225], v161 offset:39936
	global_load_lds_dwordx4 v[234:235], off
	v_lshl_add_u64 v[234:235], s[40:41], 0, v[140:141]
	s_mov_b32 m0, s35
	s_nop 0
	global_load_lds_dwordx4 v[234:235], off
	s_waitcnt vmcnt(8)
	s_waitcnt lgkmcnt(0)
	s_setprio 1
	s_barrier
	v_mfma_f32_16x16x32_bf16 v[124:127], v[128:131], v[194:197], v[124:127]
	v_mfma_f32_16x16x32_bf16 v[120:123], v[164:167], v[194:197], v[120:123]
	v_mfma_f32_16x16x32_bf16 v[108:111], v[128:131], v[202:205], v[108:111]
	v_mfma_f32_16x16x32_bf16 v[104:107], v[164:167], v[202:205], v[104:107]
	v_mfma_f32_16x16x32_bf16 v[92:95], v[128:131], v[210:213], v[92:95]
	v_mfma_f32_16x16x32_bf16 v[88:91], v[164:167], v[210:213], v[88:91]
	v_mfma_f32_16x16x32_bf16 v[76:79], v[128:131], v[218:221], v[76:79]
	v_mfma_f32_16x16x32_bf16 v[72:75], v[164:167], v[218:221], v[72:75]
	v_mfma_f32_16x16x32_bf16 v[124:127], v[132:135], v[198:201], v[124:127]
	v_mfma_f32_16x16x32_bf16 v[120:123], v[168:171], v[198:201], v[120:123]
	v_mfma_f32_16x16x32_bf16 v[108:111], v[132:135], v[206:209], v[108:111]
	v_mfma_f32_16x16x32_bf16 v[104:107], v[168:171], v[206:209], v[104:107]
	v_mfma_f32_16x16x32_bf16 v[92:95], v[132:135], v[214:217], v[92:95]
	v_mfma_f32_16x16x32_bf16 v[88:91], v[168:171], v[214:217], v[88:91]
	v_mfma_f32_16x16x32_bf16 v[76:79], v[132:135], v[222:225], v[76:79]
	v_mfma_f32_16x16x32_bf16 v[72:75], v[168:171], v[222:225], v[72:75]
	s_setprio 0
	s_setprio 1
	v_mfma_f32_16x16x32_bf16 v[116:119], v[172:175], v[194:197], v[116:119]
	v_mfma_f32_16x16x32_bf16 v[112:115], v[180:183], v[194:197], v[112:115]
	v_mfma_f32_16x16x32_bf16 v[100:103], v[172:175], v[202:205], v[100:103]
	v_mfma_f32_16x16x32_bf16 v[96:99], v[180:183], v[202:205], v[96:99]
	v_mfma_f32_16x16x32_bf16 v[84:87], v[172:175], v[210:213], v[84:87]
	v_mfma_f32_16x16x32_bf16 v[80:83], v[180:183], v[210:213], v[80:83]
	v_mfma_f32_16x16x32_bf16 v[68:71], v[172:175], v[218:221], v[68:71]
	v_mfma_f32_16x16x32_bf16 v[64:67], v[180:183], v[218:221], v[64:67]
	v_mfma_f32_16x16x32_bf16 v[116:119], v[176:179], v[198:201], v[116:119]
	v_mfma_f32_16x16x32_bf16 v[112:115], v[190:193], v[198:201], v[112:115]
	v_mfma_f32_16x16x32_bf16 v[100:103], v[176:179], v[206:209], v[100:103]
	v_mfma_f32_16x16x32_bf16 v[96:99], v[190:193], v[206:209], v[96:99]
	v_mfma_f32_16x16x32_bf16 v[84:87], v[176:179], v[214:217], v[84:87]
	v_mfma_f32_16x16x32_bf16 v[80:83], v[190:193], v[214:217], v[80:83]
	v_mfma_f32_16x16x32_bf16 v[68:71], v[176:179], v[222:225], v[68:71]
	v_mfma_f32_16x16x32_bf16 v[64:67], v[190:193], v[222:225], v[64:67]
	s_barrier
; #define PG8_STAGE(bufoff, gbase, voff) do { _Pragma("unroll") for (int _i = 0; _i < 2; ++_i) \
;         __builtin_amdgcn_global_load_lds((const unsigned*)((const char*)(gbase) + (voff)[_i]), (PG8_LAS unsigned*)(lds + (bufoff) + ldsw + _i * 8192), 16, 0, 0); } while (0)
; #define PG8_LDA(dst, b, h) do { _Pragma("unroll") for (int m = 0; m < 4; ++m) _Pragma("unroll") for (int k = 0; k < 2; ++k) dst[m][k] = *(const PG8_LAS bf16x8*)(lds + PG8_SA(b, h) + aoff + m * 2048 + k * 1024); } while (0)
; #define PG8_MMA(ai, bj, At, Bt) do { __builtin_amdgcn_s_setprio(1); _Pragma("unroll") for (int m = 0; m < 4; ++m) _Pragma("unroll") for (int n = 0; n < 2; ++n) _Pragma("unroll") for (int k = 0; k < 2; ++k) \
;         acc[ai][bj][m][n] = __builtin_amdgcn_mfma_f32_16x16x32_bf16(Bt[n][k], At[m][k], acc[ai][bj][m][n], 0, 0, 0); __builtin_amdgcn_s_setprio(0); } while (0)
; #define PG8_WAIT_V(n) asm volatile("s_waitcnt vmcnt(" #n ")" ::: "memory")
; #define PG8_WAIT_L(n) asm volatile("s_waitcnt lgkmcnt(" #n ")" ::: "memory")
; #define PG8_BAR __builtin_amdgcn_s_barrier()
; #define PG8_SCHED __builtin_amdgcn_sched_barrier(0)
; template <class Epi, class Sched, bool ALIGN_EPI = false, bool SP2 = false>
; __device__ __forceinline__ void gemm_phase(PG8_LAS unsigned char* lds, const Gemm g, const Sched& S, const Epi& E) {
;     ...
;             PG8_LDA(At, 1, 1); PG8_STAGE(PG8_SB(1, 0), b3, voffB); PG8_STAGE(PG8_SB(1, 1), b3 + hstepB, voffB); PG8_STAGE(PG8_SA(1, 0), a3, voffA);
;             PG8_WAIT_V(8); PG8_WAIT_L(0); PG8_BAR; PG8_MMA(1, 0, At, B0); PG8_MMA(1, 1, At, B1); PG8_BAR; PG8_SCHED;
;     ...
;         if constexpr (ALIGN_EPI) { if (wr == 0) PG8_BAR; }
	s_setprio 0
	s_add_i32 s13, s13, s6
	v_lshl_add_u64 v[226:227], v[226:227], 0, s[54:55]
	s_mov_b32 m0, s13
	ds_read_b128 v[194:197], v161 offset:49152
	ds_read_b128 v[198:201], v161 offset:50176
	ds_read_b128 v[202:205], v161 offset:51200
	ds_read_b128 v[206:209], v161 offset:52224
	ds_read_b128 v[210:213], v161 offset:53248
	ds_read_b128 v[214:217], v161 offset:54272
	ds_read_b128 v[218:221], v161 offset:55296
	ds_read_b128 v[222:225], v161 offset:56320
	global_load_lds_dwordx4 v[226:227], off
	s_add_i32 m0, s13, 0x2000
	s_add_u32 s38, s38, 0x80080
	v_lshl_add_u64 v[226:227], v[228:229], 0, s[54:55]
	s_addc_u32 s39, s39, 0
	s_add_i32 s13, s33, s6
	global_load_lds_dwordx4 v[226:227], off
	v_lshl_add_u64 v[226:227], s[38:39], 0, v[138:139]
	s_mov_b32 m0, s13
	s_nop 0
	global_load_lds_dwordx4 v[226:227], off
	v_lshl_add_u64 v[226:227], s[38:39], 0, v[142:143]
	s_add_i32 m0, s13, 0x2000
	s_nop 0
	global_load_lds_dwordx4 v[226:227], off
	v_lshl_add_u64 v[226:227], v[230:231], 0, s[54:55]
	s_mov_b32 m0, s51
	s_nop 0
	global_load_lds_dwordx4 v[226:227], off
	v_lshl_add_u64 v[226:227], v[232:233], 0, s[54:55]
	s_mov_b32 m0, s68
	s_nop 0
	global_load_lds_dwordx4 v[226:227], off
	s_waitcnt vmcnt(8)
	s_waitcnt lgkmcnt(0)
	s_setprio 1
	s_barrier
	v_mfma_f32_16x16x32_bf16 v[60:63], v[128:131], v[194:197], v[60:63]
	v_mfma_f32_16x16x32_bf16 v[56:59], v[164:167], v[194:197], v[56:59]
	v_mfma_f32_16x16x32_bf16 v[44:47], v[128:131], v[202:205], v[44:47]
	v_mfma_f32_16x16x32_bf16 v[40:43], v[164:167], v[202:205], v[40:43]
	v_mfma_f32_16x16x32_bf16 v[28:31], v[128:131], v[210:213], v[28:31]
	v_mfma_f32_16x16x32_bf16 v[24:27], v[164:167], v[210:213], v[24:27]
	v_mfma_f32_16x16x32_bf16 v[12:15], v[128:131], v[218:221], v[12:15]
	v_mfma_f32_16x16x32_bf16 v[8:11], v[164:167], v[218:221], v[8:11]
	v_mfma_f32_16x16x32_bf16 v[60:63], v[132:135], v[198:201], v[60:63]
	v_mfma_f32_16x16x32_bf16 v[56:59], v[168:171], v[198:201], v[56:59]
	v_mfma_f32_16x16x32_bf16 v[44:47], v[132:135], v[206:209], v[44:47]
	v_mfma_f32_16x16x32_bf16 v[40:43], v[168:171], v[206:209], v[40:43]
	v_mfma_f32_16x16x32_bf16 v[28:31], v[132:135], v[214:217], v[28:31]
	v_mfma_f32_16x16x32_bf16 v[24:27], v[168:171], v[214:217], v[24:27]
	v_mfma_f32_16x16x32_bf16 v[12:15], v[132:135], v[222:225], v[12:15]
	v_mfma_f32_16x16x32_bf16 v[8:11], v[168:171], v[222:225], v[8:11]
	s_setprio 0
	s_setprio 1
	v_mfma_f32_16x16x32_bf16 v[52:55], v[172:175], v[194:197], v[52:55]
	v_mfma_f32_16x16x32_bf16 v[48:51], v[180:183], v[194:197], v[48:51]
	v_mfma_f32_16x16x32_bf16 v[36:39], v[172:175], v[202:205], v[36:39]
	v_mfma_f32_16x16x32_bf16 v[32:35], v[180:183], v[202:205], v[32:35]
	v_mfma_f32_16x16x32_bf16 v[20:23], v[172:175], v[210:213], v[20:23]
	v_mfma_f32_16x16x32_bf16 v[16:19], v[180:183], v[210:213], v[16:19]
	v_mfma_f32_16x16x32_bf16 v[4:7], v[172:175], v[218:221], v[4:7]
	v_mfma_f32_16x16x32_bf16 v[0:3], v[180:183], v[218:221], v[0:3]
	v_mfma_f32_16x16x32_bf16 v[52:55], v[176:179], v[198:201], v[52:55]
	v_mfma_f32_16x16x32_bf16 v[48:51], v[190:193], v[198:201], v[48:51]
	v_mfma_f32_16x16x32_bf16 v[36:39], v[176:179], v[206:209], v[36:39]
	v_mfma_f32_16x16x32_bf16 v[32:35], v[190:193], v[206:209], v[32:35]
	v_mfma_f32_16x16x32_bf16 v[20:23], v[176:179], v[214:217], v[20:23]
	v_mfma_f32_16x16x32_bf16 v[16:19], v[190:193], v[214:217], v[16:19]
	v_mfma_f32_16x16x32_bf16 v[4:7], v[176:179], v[222:225], v[4:7]
	v_mfma_f32_16x16x32_bf16 v[0:3], v[190:193], v[222:225], v[0:3]
	s_barrier
	s_setprio 0
	s_add_i32 s12, s12, 2
	s_add_u32 s20, s20, 0x100
	s_addc_u32 s21, s21, 0
	s_add_u32 s10, s10, 0x100
	s_addc_u32 s11, s11, 0
	s_cmp_gt_u32 s12, 29
	s_cbranch_scc0 .LBB0_2050
	s_and_b64 vcc, exec, s[56:57]
	s_cbranch_vccz .LBB0_2053
	s_barrier

; #define PG8_STAGE(bufoff, gbase, voff) do { _Pragma("unroll") for (int _i = 0; _i < 2; ++_i) \
;         __builtin_amdgcn_global_load_lds((const unsigned*)((const char*)(gbase) + (voff)[_i]), (PG8_LAS unsigned*)(lds + (bufoff) + ldsw + _i * 8192), 16, 0, 0); } while (0)
; #define PG8_LDA(dst, b, h) do { _Pragma("unroll") for (int m = 0; m < 4; ++m) _Pragma("unroll") for (int k = 0; k < 2; ++k) dst[m][k] = *(const PG8_LAS bf16x8*)(lds + PG8_SA(b, h) + aoff + m * 2048 + k * 1024); } while (0)
; #define PG8_LDB(dst, b, h) do { _Pragma("unroll") for (int n = 0; n < 2; ++n) _Pragma("unroll") for (int k = 0; k < 2; ++k) dst[n][k] = *(const PG8_LAS bf16x8*)(lds + PG8_SB(b, h) + boff + n * 2048 + k * 1024); } while (0)
; #define PG8_MMA(ai, bj, At, Bt) do { __builtin_amdgcn_s_setprio(1); _Pragma("unroll") for (int m = 0; m < 4; ++m) _Pragma("unroll") for (int n = 0; n < 2; ++n) _Pragma("unroll") for (int k = 0; k < 2; ++k) \
;         acc[ai][bj][m][n] = __builtin_amdgcn_mfma_f32_16x16x32_bf16(Bt[n][k], At[m][k], acc[ai][bj][m][n], 0, 0, 0); __builtin_amdgcn_s_setprio(0); } while (0)
; #define PG8_WAIT_V(n) asm volatile("s_waitcnt vmcnt(" #n ")" ::: "memory")
; #define PG8_WAIT_L(n) asm volatile("s_waitcnt lgkmcnt(" #n ")" ::: "memory")
; #define PG8_BAR __builtin_amdgcn_s_barrier()
; template <class Epi, class Sched, bool ALIGN_EPI = false, bool SP2 = false>
; __device__ __forceinline__ void gemm_phase(PG8_LAS unsigned char* lds, const Gemm g, const Sched& S, const Epi& E) {
;     ...
;             const char* a1 = cA + (size_t)(t + 1) * kstA;
;             const char* a2 = last ? nA : cA + (size_t)(t + 2) * kstA; const char* b2 = last ? nB : cB + (size_t)(t + 2) * kstep;
;             const char* a3 = a2 + kstA; const char* b3 = b2 + kstep;
;             if (last && has_next) S.a_ready(nxt);
;             if constexpr (SP2) {
;             PG8_LDB(B0, 0, 0); PG8_LDB(B1, 0, 1); PG8_SCHED; PG8_LDA(At, 0, 0); PG8_STAGE(PG8_SA(1, 1), a1 + hstepA, voffA);
;             PG8_WAIT_V(8); PG8_WAIT_L(0); PG8_BAR; PG8_MMA(0, 0, At, B0); PG8_MMA(0, 1, At, B1); PG8_BAR; PG8_SCHED;
;             PG8_LDA(At, 0, 1); PG8_STAGE(PG8_SB(0, 0), b2, voffB); PG8_STAGE(PG8_SB(0, 1), b2 + hstepB, voffB); PG8_STAGE(PG8_SA(0, 0), a2, voffA);
;             PG8_WAIT_V(8); PG8_WAIT_L(0); PG8_BAR; PG8_MMA(1, 0, At, B0); PG8_MMA(1, 1, At, B1); PG8_BAR; PG8_SCHED;
.LBB0_2749:
	v_add_u32_e32 v176, s77, v180
	v_add_u32_e32 v183, s84, v180
	ds_read_b128 v[132:135], v176
	ds_read_b128 v[136:139], v176 offset:1024
	ds_read_b128 v[140:143], v176 offset:2048
	ds_read_b128 v[176:179], v176 offset:3072
	ds_read_b128 v[190:193], v183
	ds_read_b128 v[194:197], v183 offset:1024
	ds_read_b128 v[198:201], v183 offset:2048
	ds_read_b128 v[202:205], v183 offset:3072
	s_add_u32 s4, s46, s62
	s_addc_u32 s5, s47, s63
	s_add_u32 s12, s48, s62
	s_addc_u32 s13, s49, s63
	s_cmp_eq_u32 s7, s1
	s_cselect_b32 s67, s59, s5
	s_cselect_b32 s66, s58, s4
	s_cselect_b32 s65, s61, s13
	s_cselect_b32 s64, s60, s12
	v_lshl_add_u64 v[238:239], s[46:47], 0, v[130:131]
	s_add_i32 m0, s9, 0xc000
	ds_read_b128 v[206:209], v182
	ds_read_b128 v[210:213], v182 offset:1024
	ds_read_b128 v[214:217], v182 offset:2048
	ds_read_b128 v[218:221], v182 offset:3072
	ds_read_b128 v[222:225], v182 offset:4096
	ds_read_b128 v[226:229], v182 offset:5120
	ds_read_b128 v[230:233], v182 offset:6144
	ds_read_b128 v[234:237], v182 offset:7168
	global_load_lds_dwordx4 v[238:239], off
	v_lshl_add_u64 v[238:239], s[46:47], 0, v[128:129]
	s_add_i32 m0, s9, 0xe000
	s_nop 0
	global_load_lds_dwordx4 v[238:239], off
	s_waitcnt vmcnt(8)
	s_waitcnt lgkmcnt(0)
	s_setprio 1
	s_barrier
	v_mfma_f32_16x16x32_bf16 v[124:127], v[132:135], v[206:209], v[124:127]
	v_mfma_f32_16x16x32_bf16 v[120:123], v[140:143], v[206:209], v[120:123]
	v_mfma_f32_16x16x32_bf16 v[116:119], v[132:135], v[214:217], v[116:119]
	v_mfma_f32_16x16x32_bf16 v[112:115], v[140:143], v[214:217], v[112:115]
	v_mfma_f32_16x16x32_bf16 v[108:111], v[132:135], v[222:225], v[108:111]
	v_mfma_f32_16x16x32_bf16 v[104:107], v[140:143], v[222:225], v[104:107]
	v_mfma_f32_16x16x32_bf16 v[100:103], v[132:135], v[230:233], v[100:103]
	v_mfma_f32_16x16x32_bf16 v[96:99], v[140:143], v[230:233], v[96:99]
	v_mfma_f32_16x16x32_bf16 v[124:127], v[136:139], v[210:213], v[124:127]
	v_mfma_f32_16x16x32_bf16 v[120:123], v[176:179], v[210:213], v[120:123]
	v_mfma_f32_16x16x32_bf16 v[116:119], v[136:139], v[218:221], v[116:119]
	v_mfma_f32_16x16x32_bf16 v[112:115], v[176:179], v[218:221], v[112:115]
	v_mfma_f32_16x16x32_bf16 v[108:111], v[136:139], v[226:229], v[108:111]
	v_mfma_f32_16x16x32_bf16 v[104:107], v[176:179], v[226:229], v[104:107]
	v_mfma_f32_16x16x32_bf16 v[100:103], v[136:139], v[234:237], v[100:103]
	v_mfma_f32_16x16x32_bf16 v[96:99], v[176:179], v[234:237], v[96:99]
	s_setprio 0
	s_setprio 1
	v_mfma_f32_16x16x32_bf16 v[92:95], v[190:193], v[206:209], v[92:95]
	v_mfma_f32_16x16x32_bf16 v[88:91], v[198:201], v[206:209], v[88:91]
	v_mfma_f32_16x16x32_bf16 v[84:87], v[190:193], v[214:217], v[84:87]
	v_mfma_f32_16x16x32_bf16 v[80:83], v[198:201], v[214:217], v[80:83]
	v_mfma_f32_16x16x32_bf16 v[76:79], v[190:193], v[222:225], v[76:79]
	v_mfma_f32_16x16x32_bf16 v[72:75], v[198:201], v[222:225], v[72:75]
	v_mfma_f32_16x16x32_bf16 v[68:71], v[190:193], v[230:233], v[68:71]
	v_mfma_f32_16x16x32_bf16 v[64:67], v[198:201], v[230:233], v[64:67]
	v_mfma_f32_16x16x32_bf16 v[92:95], v[194:197], v[210:213], v[92:95]
	v_mfma_f32_16x16x32_bf16 v[88:91], v[202:205], v[210:213], v[88:91]
	v_mfma_f32_16x16x32_bf16 v[84:87], v[194:197], v[218:221], v[84:87]
	v_mfma_f32_16x16x32_bf16 v[80:83], v[202:205], v[218:221], v[80:83]
	v_mfma_f32_16x16x32_bf16 v[76:79], v[194:197], v[226:229], v[76:79]
	v_mfma_f32_16x16x32_bf16 v[72:75], v[202:205], v[226:229], v[72:75]
	v_mfma_f32_16x16x32_bf16 v[68:71], v[194:197], v[234:237], v[68:71]
	v_mfma_f32_16x16x32_bf16 v[64:67], v[202:205], v[234:237], v[64:67]
	s_barrier
	s_setprio 0
	s_add_i32 s4, s77, s8
	v_lshl_add_u64 v[238:239], s[64:65], 0, v[146:147]
	s_mov_b32 m0, s4
	ds_read_b128 v[206:209], v182 offset:16384
	ds_read_b128 v[210:213], v182 offset:17408
	ds_read_b128 v[214:217], v182 offset:18432
	ds_read_b128 v[218:221], v182 offset:19456
	ds_read_b128 v[222:225], v182 offset:20480
	ds_read_b128 v[226:229], v182 offset:21504
	ds_read_b128 v[230:233], v182 offset:22528
	ds_read_b128 v[234:237], v182 offset:23552
	global_load_lds_dwordx4 v[238:239], off
	s_add_i32 m0, s4, 0x2000
	s_add_u32 s4, s64, 0x80000
	v_lshl_add_u64 v[240:241], s[64:65], 0, v[150:151]
	s_addc_u32 s5, s65, 0
	s_add_i32 s12, s84, s8
	global_load_lds_dwordx4 v[240:241], off
	v_lshl_add_u64 v[242:243], s[4:5], 0, v[146:147]
	s_mov_b32 m0, s12
	v_lshl_add_u64 v[244:245], s[66:67], 0, v[148:149]
	global_load_lds_dwordx4 v[242:243], off
	v_lshl_add_u64 v[242:243], s[4:5], 0, v[150:151]
	s_add_i32 m0, s12, 0x2000
	s_nop 0
	global_load_lds_dwordx4 v[242:243], off
	v_lshl_add_u64 v[242:243], s[66:67], 0, v[144:145]
	s_mov_b32 m0, s9
	s_nop 0
	global_load_lds_dwordx4 v[242:243], off
	s_mov_b32 m0, s37
	s_nop 0
	global_load_lds_dwordx4 v[244:245], off
	s_waitcnt vmcnt(8)
	s_waitcnt lgkmcnt(0)
	s_setprio 1
	s_barrier
; #define PG8_STAGE(bufoff, gbase, voff) do { _Pragma("unroll") for (int _i = 0; _i < 2; ++_i) \
;         __builtin_amdgcn_global_load_lds((const unsigned*)((const char*)(gbase) + (voff)[_i]), (PG8_LAS unsigned*)(lds + (bufoff) + ldsw + _i * 8192), 16, 0, 0); } while (0)
; #define PG8_LDA(dst, b, h) do { _Pragma("unroll") for (int m = 0; m < 4; ++m) _Pragma("unroll") for (int k = 0; k < 2; ++k) dst[m][k] = *(const PG8_LAS bf16x8*)(lds + PG8_SA(b, h) + aoff + m * 2048 + k * 1024); } while (0)
; #define PG8_LDB(dst, b, h) do { _Pragma("unroll") for (int n = 0; n < 2; ++n) _Pragma("unroll") for (int k = 0; k < 2; ++k) dst[n][k] = *(const PG8_LAS bf16x8*)(lds + PG8_SB(b, h) + boff + n * 2048 + k * 1024); } while (0)
; #define PG8_MMA(ai, bj, At, Bt) do { __builtin_amdgcn_s_setprio(1); _Pragma("unroll") for (int m = 0; m < 4; ++m) _Pragma("unroll") for (int n = 0; n < 2; ++n) _Pragma("unroll") for (int k = 0; k < 2; ++k) \
;         acc[ai][bj][m][n] = __builtin_amdgcn_mfma_f32_16x16x32_bf16(Bt[n][k], At[m][k], acc[ai][bj][m][n], 0, 0, 0); __builtin_amdgcn_s_setprio(0); } while (0)
; #define PG8_WAIT_V(n) asm volatile("s_waitcnt vmcnt(" #n ")" ::: "memory")
; #define PG8_WAIT_L(n) asm volatile("s_waitcnt lgkmcnt(" #n ")" ::: "memory")
; #define PG8_BAR __builtin_amdgcn_s_barrier()
; #define PG8_SCHED __builtin_amdgcn_sched_barrier(0)
; template <class Epi, class Sched, bool ALIGN_EPI = false, bool SP2 = false>
; __device__ __forceinline__ void gemm_phase(PG8_LAS unsigned char* lds, const Gemm g, const Sched& S, const Epi& E) {
;     ...
;             PG8_WAIT_V(8); PG8_WAIT_L(0); PG8_BAR; PG8_MMA(1, 0, At, B0); PG8_MMA(1, 1, At, B1); PG8_BAR; PG8_SCHED;
;             PG8_LDB(B0, 1, 0); PG8_LDB(B1, 1, 1); PG8_SCHED; PG8_LDA(At, 1, 0); PG8_STAGE(PG8_SA(0, 1), a2 + hstepA, voffA);
;             PG8_WAIT_V(8); PG8_WAIT_L(0); PG8_BAR; PG8_MMA(0, 0, At, B0); PG8_MMA(0, 1, At, B1); PG8_BAR; PG8_SCHED;
	v_mfma_f32_16x16x32_bf16 v[60:63], v[132:135], v[206:209], v[60:63]
	v_mfma_f32_16x16x32_bf16 v[56:59], v[140:143], v[206:209], v[56:59]
	v_mfma_f32_16x16x32_bf16 v[52:55], v[132:135], v[214:217], v[52:55]
	v_mfma_f32_16x16x32_bf16 v[48:51], v[140:143], v[214:217], v[48:51]
	v_mfma_f32_16x16x32_bf16 v[44:47], v[132:135], v[222:225], v[44:47]
	v_mfma_f32_16x16x32_bf16 v[40:43], v[140:143], v[222:225], v[40:43]
	v_mfma_f32_16x16x32_bf16 v[36:39], v[132:135], v[230:233], v[36:39]
	v_mfma_f32_16x16x32_bf16 v[32:35], v[140:143], v[230:233], v[32:35]
	v_mfma_f32_16x16x32_bf16 v[60:63], v[136:139], v[210:213], v[60:63]
	v_mfma_f32_16x16x32_bf16 v[56:59], v[176:179], v[210:213], v[56:59]
	v_mfma_f32_16x16x32_bf16 v[52:55], v[136:139], v[218:221], v[52:55]
	v_mfma_f32_16x16x32_bf16 v[48:51], v[176:179], v[218:221], v[48:51]
	v_mfma_f32_16x16x32_bf16 v[44:47], v[136:139], v[226:229], v[44:47]
	v_mfma_f32_16x16x32_bf16 v[40:43], v[176:179], v[226:229], v[40:43]
	v_mfma_f32_16x16x32_bf16 v[36:39], v[136:139], v[234:237], v[36:39]
	v_mfma_f32_16x16x32_bf16 v[32:35], v[176:179], v[234:237], v[32:35]
	s_setprio 0
	s_setprio 1
	v_mfma_f32_16x16x32_bf16 v[28:31], v[190:193], v[206:209], v[28:31]
	v_mfma_f32_16x16x32_bf16 v[24:27], v[198:201], v[206:209], v[24:27]
	v_mfma_f32_16x16x32_bf16 v[20:23], v[190:193], v[214:217], v[20:23]
	v_mfma_f32_16x16x32_bf16 v[16:19], v[198:201], v[214:217], v[16:19]
	v_mfma_f32_16x16x32_bf16 v[12:15], v[190:193], v[222:225], v[12:15]
	v_mfma_f32_16x16x32_bf16 v[8:11], v[198:201], v[222:225], v[8:11]
	v_mfma_f32_16x16x32_bf16 v[4:7], v[190:193], v[230:233], v[4:7]
	v_mfma_f32_16x16x32_bf16 v[0:3], v[198:201], v[230:233], v[0:3]
	v_mfma_f32_16x16x32_bf16 v[28:31], v[194:197], v[210:213], v[28:31]
	v_mfma_f32_16x16x32_bf16 v[24:27], v[202:205], v[210:213], v[24:27]
	v_mfma_f32_16x16x32_bf16 v[20:23], v[194:197], v[218:221], v[20:23]
	v_mfma_f32_16x16x32_bf16 v[16:19], v[202:205], v[218:221], v[16:19]
	v_mfma_f32_16x16x32_bf16 v[12:15], v[194:197], v[226:229], v[12:15]
	v_mfma_f32_16x16x32_bf16 v[8:11], v[202:205], v[226:229], v[8:11]
	v_mfma_f32_16x16x32_bf16 v[4:7], v[194:197], v[234:237], v[4:7]
	v_mfma_f32_16x16x32_bf16 v[0:3], v[202:205], v[234:237], v[0:3]
	s_barrier
	s_setprio 0
	s_add_i32 s12, 0, 0x18000
	s_add_i32 s13, 0, 0x1c000
	v_add_u32_e32 v176, s12, v180
	v_add_u32_e32 v183, s13, v180
	ds_read_b128 v[132:135], v176
	ds_read_b128 v[136:139], v176 offset:1024
	ds_read_b128 v[140:143], v176 offset:2048
	ds_read_b128 v[176:179], v176 offset:3072
	ds_read_b128 v[190:193], v183
	ds_read_b128 v[194:197], v183 offset:1024
	ds_read_b128 v[198:201], v183 offset:2048
	ds_read_b128 v[202:205], v183 offset:3072
	s_add_u32 s4, s66, 0x80000
	s_addc_u32 s5, s67, 0
	s_mov_b32 m0, s70
	v_lshl_add_u64 v[246:247], s[4:5], 0, v[144:145]
	ds_read_b128 v[206:209], v182 offset:32768
	ds_read_b128 v[210:213], v182 offset:33792
	ds_read_b128 v[214:217], v182 offset:34816
	ds_read_b128 v[218:221], v182 offset:35840
	ds_read_b128 v[222:225], v182 offset:36864
	ds_read_b128 v[226:229], v182 offset:37888
	ds_read_b128 v[230:233], v182 offset:38912
	ds_read_b128 v[234:237], v182 offset:39936
	global_load_lds_dwordx4 v[246:247], off
	v_lshl_add_u64 v[246:247], s[4:5], 0, v[148:149]
	s_mov_b32 m0, s71
	s_nop 0
	global_load_lds_dwordx4 v[246:247], off
	s_waitcnt vmcnt(8)
	s_waitcnt lgkmcnt(0)
	s_setprio 1
	s_barrier
	v_mfma_f32_16x16x32_bf16 v[124:127], v[132:135], v[206:209], v[124:127]
	v_mfma_f32_16x16x32_bf16 v[120:123], v[140:143], v[206:209], v[120:123]
	v_mfma_f32_16x16x32_bf16 v[116:119], v[132:135], v[214:217], v[116:119]
	v_mfma_f32_16x16x32_bf16 v[112:115], v[140:143], v[214:217], v[112:115]
	v_mfma_f32_16x16x32_bf16 v[108:111], v[132:135], v[222:225], v[108:111]
	v_mfma_f32_16x16x32_bf16 v[104:107], v[140:143], v[222:225], v[104:107]
	v_mfma_f32_16x16x32_bf16 v[100:103], v[132:135], v[230:233], v[100:103]
	v_mfma_f32_16x16x32_bf16 v[96:99], v[140:143], v[230:233], v[96:99]
	v_mfma_f32_16x16x32_bf16 v[124:127], v[136:139], v[210:213], v[124:127]
	v_mfma_f32_16x16x32_bf16 v[120:123], v[176:179], v[210:213], v[120:123]
	v_mfma_f32_16x16x32_bf16 v[116:119], v[136:139], v[218:221], v[116:119]
	v_mfma_f32_16x16x32_bf16 v[112:115], v[176:179], v[218:221], v[112:115]
	v_mfma_f32_16x16x32_bf16 v[108:111], v[136:139], v[226:229], v[108:111]
	v_mfma_f32_16x16x32_bf16 v[104:107], v[176:179], v[226:229], v[104:107]
	v_mfma_f32_16x16x32_bf16 v[100:103], v[136:139], v[234:237], v[100:103]
	v_mfma_f32_16x16x32_bf16 v[96:99], v[176:179], v[234:237], v[96:99]
	s_setprio 0
	s_setprio 1
	v_mfma_f32_16x16x32_bf16 v[92:95], v[190:193], v[206:209], v[92:95]
	v_mfma_f32_16x16x32_bf16 v[88:91], v[198:201], v[206:209], v[88:91]
	v_mfma_f32_16x16x32_bf16 v[84:87], v[190:193], v[214:217], v[84:87]
	v_mfma_f32_16x16x32_bf16 v[80:83], v[198:201], v[214:217], v[80:83]
	v_mfma_f32_16x16x32_bf16 v[76:79], v[190:193], v[222:225], v[76:79]
	v_mfma_f32_16x16x32_bf16 v[72:75], v[198:201], v[222:225], v[72:75]
	v_mfma_f32_16x16x32_bf16 v[68:71], v[190:193], v[230:233], v[68:71]
	v_mfma_f32_16x16x32_bf16 v[64:67], v[198:201], v[230:233], v[64:67]
	v_mfma_f32_16x16x32_bf16 v[92:95], v[194:197], v[210:213], v[92:95]
	v_mfma_f32_16x16x32_bf16 v[88:91], v[202:205], v[210:213], v[88:91]
	v_mfma_f32_16x16x32_bf16 v[84:87], v[194:197], v[218:221], v[84:87]
	v_mfma_f32_16x16x32_bf16 v[80:83], v[202:205], v[218:221], v[80:83]
	v_mfma_f32_16x16x32_bf16 v[76:79], v[194:197], v[226:229], v[76:79]
	v_mfma_f32_16x16x32_bf16 v[72:75], v[202:205], v[226:229], v[72:75]
	v_mfma_f32_16x16x32_bf16 v[68:71], v[194:197], v[234:237], v[68:71]
	v_mfma_f32_16x16x32_bf16 v[64:67], v[202:205], v[234:237], v[64:67]
	s_barrier
; #define PG8_STAGE(bufoff, gbase, voff) do { _Pragma("unroll") for (int _i = 0; _i < 2; ++_i) \
;         __builtin_amdgcn_global_load_lds((const unsigned*)((const char*)(gbase) + (voff)[_i]), (PG8_LAS unsigned*)(lds + (bufoff) + ldsw + _i * 8192), 16, 0, 0); } while (0)
; #define PG8_LDA(dst, b, h) do { _Pragma("unroll") for (int m = 0; m < 4; ++m) _Pragma("unroll") for (int k = 0; k < 2; ++k) dst[m][k] = *(const PG8_LAS bf16x8*)(lds + PG8_SA(b, h) + aoff + m * 2048 + k * 1024); } while (0)
; #define PG8_MMA(ai, bj, At, Bt) do { __builtin_amdgcn_s_setprio(1); _Pragma("unroll") for (int m = 0; m < 4; ++m) _Pragma("unroll") for (int n = 0; n < 2; ++n) _Pragma("unroll") for (int k = 0; k < 2; ++k) \
;         acc[ai][bj][m][n] = __builtin_amdgcn_mfma_f32_16x16x32_bf16(Bt[n][k], At[m][k], acc[ai][bj][m][n], 0, 0, 0); __builtin_amdgcn_s_setprio(0); } while (0)
; #define PG8_WAIT_V(n) asm volatile("s_waitcnt vmcnt(" #n ")" ::: "memory")
; #define PG8_WAIT_L(n) asm volatile("s_waitcnt lgkmcnt(" #n ")" ::: "memory")
; #define PG8_BAR __builtin_amdgcn_s_barrier()
; #define PG8_SCHED __builtin_amdgcn_sched_barrier(0)
; template <class Epi, class Sched, bool ALIGN_EPI = false, bool SP2 = false>
; __device__ __forceinline__ void gemm_phase(PG8_LAS unsigned char* lds, const Gemm g, const Sched& S, const Epi& E) {
;     ...
;             PG8_LDA(At, 1, 1); PG8_STAGE(PG8_SB(1, 0), b3, voffB); PG8_STAGE(PG8_SB(1, 1), b3 + hstepB, voffB); PG8_STAGE(PG8_SA(1, 0), a3, voffA);
;             PG8_WAIT_V(8); PG8_WAIT_L(0); PG8_BAR; PG8_MMA(1, 0, At, B0); PG8_MMA(1, 1, At, B1); PG8_BAR; PG8_SCHED;
;     ...
;         if constexpr (ALIGN_EPI) { if (wr == 0) PG8_BAR; }
	s_setprio 0
	s_add_i32 s4, s12, s8
	v_lshl_add_u64 v[238:239], v[238:239], 0, s[52:53]
	s_mov_b32 m0, s4
	ds_read_b128 v[206:209], v182 offset:49152
	ds_read_b128 v[210:213], v182 offset:50176
	ds_read_b128 v[214:217], v182 offset:51200
	ds_read_b128 v[218:221], v182 offset:52224
	ds_read_b128 v[222:225], v182 offset:53248
	ds_read_b128 v[226:229], v182 offset:54272
	ds_read_b128 v[230:233], v182 offset:55296
	ds_read_b128 v[234:237], v182 offset:56320
	global_load_lds_dwordx4 v[238:239], off
	s_add_i32 m0, s4, 0x2000
	s_add_u32 s4, s64, 0x80080
	v_lshl_add_u64 v[238:239], v[240:241], 0, s[52:53]
	s_addc_u32 s5, s65, 0
	s_add_i32 s12, s13, s8
	global_load_lds_dwordx4 v[238:239], off
	v_lshl_add_u64 v[238:239], s[4:5], 0, v[146:147]
	s_mov_b32 m0, s12
	s_nop 0
	global_load_lds_dwordx4 v[238:239], off
	v_lshl_add_u64 v[238:239], s[4:5], 0, v[150:151]
	s_add_i32 m0, s12, 0x2000
	s_nop 0
	global_load_lds_dwordx4 v[238:239], off
	v_lshl_add_u64 v[238:239], v[242:243], 0, s[52:53]
	s_mov_b32 m0, s74
	s_nop 0
	global_load_lds_dwordx4 v[238:239], off
	v_lshl_add_u64 v[238:239], v[244:245], 0, s[52:53]
	s_mov_b32 m0, s75
	s_nop 0
	global_load_lds_dwordx4 v[238:239], off
	s_waitcnt vmcnt(8)
	s_waitcnt lgkmcnt(0)
	s_setprio 1
	s_barrier
	v_mfma_f32_16x16x32_bf16 v[60:63], v[132:135], v[206:209], v[60:63]
	v_mfma_f32_16x16x32_bf16 v[56:59], v[140:143], v[206:209], v[56:59]
	v_mfma_f32_16x16x32_bf16 v[52:55], v[132:135], v[214:217], v[52:55]
	v_mfma_f32_16x16x32_bf16 v[48:51], v[140:143], v[214:217], v[48:51]
	v_mfma_f32_16x16x32_bf16 v[44:47], v[132:135], v[222:225], v[44:47]
	v_mfma_f32_16x16x32_bf16 v[40:43], v[140:143], v[222:225], v[40:43]
	v_mfma_f32_16x16x32_bf16 v[36:39], v[132:135], v[230:233], v[36:39]
	v_mfma_f32_16x16x32_bf16 v[32:35], v[140:143], v[230:233], v[32:35]
	v_mfma_f32_16x16x32_bf16 v[60:63], v[136:139], v[210:213], v[60:63]
	v_mfma_f32_16x16x32_bf16 v[56:59], v[176:179], v[210:213], v[56:59]
	v_mfma_f32_16x16x32_bf16 v[52:55], v[136:139], v[218:221], v[52:55]
	v_mfma_f32_16x16x32_bf16 v[48:51], v[176:179], v[218:221], v[48:51]
	v_mfma_f32_16x16x32_bf16 v[44:47], v[136:139], v[226:229], v[44:47]
	v_mfma_f32_16x16x32_bf16 v[40:43], v[176:179], v[226:229], v[40:43]
	v_mfma_f32_16x16x32_bf16 v[36:39], v[136:139], v[234:237], v[36:39]
	v_mfma_f32_16x16x32_bf16 v[32:35], v[176:179], v[234:237], v[32:35]
	s_setprio 0
	s_setprio 1
	v_mfma_f32_16x16x32_bf16 v[28:31], v[190:193], v[206:209], v[28:31]
	v_mfma_f32_16x16x32_bf16 v[24:27], v[198:201], v[206:209], v[24:27]
	v_mfma_f32_16x16x32_bf16 v[20:23], v[190:193], v[214:217], v[20:23]
	v_mfma_f32_16x16x32_bf16 v[16:19], v[198:201], v[214:217], v[16:19]
	v_mfma_f32_16x16x32_bf16 v[12:15], v[190:193], v[222:225], v[12:15]
	v_mfma_f32_16x16x32_bf16 v[8:11], v[198:201], v[222:225], v[8:11]
	v_mfma_f32_16x16x32_bf16 v[4:7], v[190:193], v[230:233], v[4:7]
	v_mfma_f32_16x16x32_bf16 v[0:3], v[198:201], v[230:233], v[0:3]
	v_mfma_f32_16x16x32_bf16 v[28:31], v[194:197], v[210:213], v[28:31]
	v_mfma_f32_16x16x32_bf16 v[24:27], v[202:205], v[210:213], v[24:27]
	v_mfma_f32_16x16x32_bf16 v[20:23], v[194:197], v[218:221], v[20:23]
	v_mfma_f32_16x16x32_bf16 v[16:19], v[202:205], v[218:221], v[16:19]
	v_mfma_f32_16x16x32_bf16 v[12:15], v[194:197], v[226:229], v[12:15]
	v_mfma_f32_16x16x32_bf16 v[8:11], v[202:205], v[226:229], v[8:11]
	v_mfma_f32_16x16x32_bf16 v[4:7], v[194:197], v[234:237], v[4:7]
	v_mfma_f32_16x16x32_bf16 v[0:3], v[202:205], v[234:237], v[0:3]
	s_barrier
	s_setprio 0
	s_add_i32 s4, s1, 2
	s_add_u32 s62, s62, 0x100
	s_addc_u32 s63, s63, 0
	v_lshl_add_u64 v[130:131], v[130:131], 0, s[34:35]
	v_lshl_add_u64 v[128:129], v[128:129], 0, s[34:35]
	s_cmp_ge_i32 s1, s7
	s_mov_b32 s1, s4
	s_cbranch_scc0 .LBB0_2749
	s_and_b64 vcc, exec, s[54:55]
	s_cbranch_vccz .LBB0_2752
	s_barrier

; #define PG8_STAGE(bufoff, gbase, voff) do { _Pragma("unroll") for (int _i = 0; _i < 2; ++_i) \
;         __builtin_amdgcn_global_load_lds((const unsigned*)((const char*)(gbase) + (voff)[_i]), (PG8_LAS unsigned*)(lds + (bufoff) + ldsw + _i * 8192), 16, 0, 0); } while (0)
; #define PG8_LDA(dst, b, h) do { _Pragma("unroll") for (int m = 0; m < 4; ++m) _Pragma("unroll") for (int k = 0; k < 2; ++k) dst[m][k] = *(const PG8_LAS bf16x8*)(lds + PG8_SA(b, h) + aoff + m * 2048 + k * 1024); } while (0)
; #define PG8_LDB(dst, b, h) do { _Pragma("unroll") for (int n = 0; n < 2; ++n) _Pragma("unroll") for (int k = 0; k < 2; ++k) dst[n][k] = *(const PG8_LAS bf16x8*)(lds + PG8_SB(b, h) + boff + n * 2048 + k * 1024); } while (0)
; #define PG8_MMA(ai, bj, At, Bt) do { __builtin_amdgcn_s_setprio(1); _Pragma("unroll") for (int m = 0; m < 4; ++m) _Pragma("unroll") for (int n = 0; n < 2; ++n) _Pragma("unroll") for (int k = 0; k < 2; ++k) \
;         acc[ai][bj][m][n] = __builtin_amdgcn_mfma_f32_16x16x32_bf16(Bt[n][k], At[m][k], acc[ai][bj][m][n], 0, 0, 0); __builtin_amdgcn_s_setprio(0); } while (0)
; #define PG8_WAIT_V(n) asm volatile("s_waitcnt vmcnt(" #n ")" ::: "memory")
; #define PG8_WAIT_L(n) asm volatile("s_waitcnt lgkmcnt(" #n ")" ::: "memory")
; #define PG8_BAR __builtin_amdgcn_s_barrier()
; template <class Epi, class Sched, bool ALIGN_EPI = false, bool SP2 = false>
; __device__ __forceinline__ void gemm_phase(PG8_LAS unsigned char* lds, const Gemm g, const Sched& S, const Epi& E) {
;     ...
;             const char* a1 = cA + (size_t)(t + 1) * kstA;
;             const char* a2 = last ? nA : cA + (size_t)(t + 2) * kstA; const char* b2 = last ? nB : cB + (size_t)(t + 2) * kstep;
;             const char* a3 = a2 + kstA; const char* b3 = b2 + kstep;
;             if (last && has_next) S.a_ready(nxt);
;             if constexpr (SP2) {
;             PG8_LDB(B0, 0, 0); PG8_LDB(B1, 0, 1); PG8_SCHED; PG8_LDA(At, 0, 0); PG8_STAGE(PG8_SA(1, 1), a1 + hstepA, voffA);
;             PG8_WAIT_V(8); PG8_WAIT_L(0); PG8_BAR; PG8_MMA(0, 0, At, B0); PG8_MMA(0, 1, At, B1); PG8_BAR; PG8_SCHED;
;             PG8_LDA(At, 0, 1); PG8_STAGE(PG8_SB(0, 0), b2, voffB); PG8_STAGE(PG8_SB(0, 1), b2 + hstepB, voffB); PG8_STAGE(PG8_SA(0, 0), a2, voffA);
;             PG8_WAIT_V(8); PG8_WAIT_L(0); PG8_BAR; PG8_MMA(1, 0, At, B0); PG8_MMA(1, 1, At, B1); PG8_BAR; PG8_SCHED;
.LBB0_3058:
	ds_read_b128 v[156:159], v152
	ds_read_b128 v[160:163], v152 offset:1024
	ds_read_b128 v[164:167], v152 offset:2048
	ds_read_b128 v[168:171], v152 offset:3072
	ds_read_b128 v[172:175], v153
	ds_read_b128 v[176:179], v153 offset:1024
	ds_read_b128 v[180:183], v153 offset:2048
	ds_read_b128 v[190:193], v153 offset:3072
	s_add_u32 s42, s40, 0xfff80080
	s_addc_u32 s43, s41, -1
	s_cmp_eq_u32 s35, 28
	s_cselect_b32 s45, s4, s43
	s_cselect_b32 s44, s5, s42
	s_cselect_b32 s43, s12, s23
	s_cselect_b32 s42, s13, s21
	v_lshl_add_u64 v[226:227], s[40:41], 0, v[142:143]
	s_add_i32 m0, s8, 0xc000
	ds_read_b128 v[194:197], v154
	ds_read_b128 v[198:201], v154 offset:1024
	ds_read_b128 v[202:205], v154 offset:2048
	ds_read_b128 v[206:209], v154 offset:3072
	ds_read_b128 v[210:213], v154 offset:4096
	ds_read_b128 v[214:217], v154 offset:5120
	ds_read_b128 v[218:221], v154 offset:6144
	ds_read_b128 v[222:225], v154 offset:7168
	global_load_lds_dwordx4 v[226:227], off
	v_lshl_add_u64 v[226:227], s[40:41], 0, v[144:145]
	s_add_i32 m0, s8, 0xe000
	s_nop 0
	global_load_lds_dwordx4 v[226:227], off
	s_waitcnt vmcnt(8)
	s_waitcnt lgkmcnt(0)
	s_setprio 1
	s_barrier
	v_mfma_f32_16x16x32_bf16 v[124:127], v[156:159], v[194:197], v[124:127]
	v_mfma_f32_16x16x32_bf16 v[120:123], v[164:167], v[194:197], v[120:123]
	v_mfma_f32_16x16x32_bf16 v[108:111], v[156:159], v[202:205], v[108:111]
	v_mfma_f32_16x16x32_bf16 v[104:107], v[164:167], v[202:205], v[104:107]
	v_mfma_f32_16x16x32_bf16 v[92:95], v[156:159], v[210:213], v[92:95]
	v_mfma_f32_16x16x32_bf16 v[88:91], v[164:167], v[210:213], v[88:91]
	v_mfma_f32_16x16x32_bf16 v[76:79], v[156:159], v[218:221], v[76:79]
	v_mfma_f32_16x16x32_bf16 v[72:75], v[164:167], v[218:221], v[72:75]
	v_mfma_f32_16x16x32_bf16 v[124:127], v[160:163], v[198:201], v[124:127]
	v_mfma_f32_16x16x32_bf16 v[120:123], v[168:171], v[198:201], v[120:123]
	v_mfma_f32_16x16x32_bf16 v[108:111], v[160:163], v[206:209], v[108:111]
	v_mfma_f32_16x16x32_bf16 v[104:107], v[168:171], v[206:209], v[104:107]
	v_mfma_f32_16x16x32_bf16 v[92:95], v[160:163], v[214:217], v[92:95]
	v_mfma_f32_16x16x32_bf16 v[88:91], v[168:171], v[214:217], v[88:91]
	v_mfma_f32_16x16x32_bf16 v[76:79], v[160:163], v[222:225], v[76:79]
	v_mfma_f32_16x16x32_bf16 v[72:75], v[168:171], v[222:225], v[72:75]
	s_setprio 0
	s_setprio 1
	v_mfma_f32_16x16x32_bf16 v[116:119], v[172:175], v[194:197], v[116:119]
	v_mfma_f32_16x16x32_bf16 v[112:115], v[180:183], v[194:197], v[112:115]
	v_mfma_f32_16x16x32_bf16 v[100:103], v[172:175], v[202:205], v[100:103]
	v_mfma_f32_16x16x32_bf16 v[96:99], v[180:183], v[202:205], v[96:99]
	v_mfma_f32_16x16x32_bf16 v[84:87], v[172:175], v[210:213], v[84:87]
	v_mfma_f32_16x16x32_bf16 v[80:83], v[180:183], v[210:213], v[80:83]
	v_mfma_f32_16x16x32_bf16 v[68:71], v[172:175], v[218:221], v[68:71]
	v_mfma_f32_16x16x32_bf16 v[64:67], v[180:183], v[218:221], v[64:67]
	v_mfma_f32_16x16x32_bf16 v[116:119], v[176:179], v[198:201], v[116:119]
	v_mfma_f32_16x16x32_bf16 v[112:115], v[190:193], v[198:201], v[112:115]
	v_mfma_f32_16x16x32_bf16 v[100:103], v[176:179], v[206:209], v[100:103]
	v_mfma_f32_16x16x32_bf16 v[96:99], v[190:193], v[206:209], v[96:99]
	v_mfma_f32_16x16x32_bf16 v[84:87], v[176:179], v[214:217], v[84:87]
	v_mfma_f32_16x16x32_bf16 v[80:83], v[190:193], v[214:217], v[80:83]
	v_mfma_f32_16x16x32_bf16 v[68:71], v[176:179], v[222:225], v[68:71]
	v_mfma_f32_16x16x32_bf16 v[64:67], v[190:193], v[222:225], v[64:67]
	s_barrier
	s_setprio 0
	s_add_i32 s53, s50, s7
	v_lshl_add_u64 v[226:227], s[42:43], 0, v[130:131]
	s_mov_b32 m0, s53
	ds_read_b128 v[194:197], v154 offset:16384
	ds_read_b128 v[198:201], v154 offset:17408
	ds_read_b128 v[202:205], v154 offset:18432
	ds_read_b128 v[206:209], v154 offset:19456
	ds_read_b128 v[210:213], v154 offset:20480
	ds_read_b128 v[214:217], v154 offset:21504
	ds_read_b128 v[218:221], v154 offset:22528
	ds_read_b128 v[222:225], v154 offset:23552
	global_load_lds_dwordx4 v[226:227], off
	s_add_i32 m0, s53, 0x2000
	s_add_u32 s54, s42, 0x80000
	v_lshl_add_u64 v[228:229], s[42:43], 0, v[134:135]
	s_addc_u32 s55, s43, 0
	s_add_i32 s53, s51, s7
	global_load_lds_dwordx4 v[228:229], off
	v_lshl_add_u64 v[230:231], s[54:55], 0, v[130:131]
	s_mov_b32 m0, s53
	v_lshl_add_u64 v[232:233], s[44:45], 0, v[132:133]
	global_load_lds_dwordx4 v[230:231], off
	v_lshl_add_u64 v[230:231], s[54:55], 0, v[134:135]
	s_add_i32 m0, s53, 0x2000
	s_nop 0
	global_load_lds_dwordx4 v[230:231], off
	v_lshl_add_u64 v[230:231], s[44:45], 0, v[128:129]
	s_mov_b32 m0, s8
	s_nop 0
	global_load_lds_dwordx4 v[230:231], off
	s_mov_b32 m0, s9
	s_nop 0
	global_load_lds_dwordx4 v[232:233], off
	s_waitcnt vmcnt(8)
	s_waitcnt lgkmcnt(0)
	s_setprio 1
	s_barrier
; #define PG8_STAGE(bufoff, gbase, voff) do { _Pragma("unroll") for (int _i = 0; _i < 2; ++_i) \
;         __builtin_amdgcn_global_load_lds((const unsigned*)((const char*)(gbase) + (voff)[_i]), (PG8_LAS unsigned*)(lds + (bufoff) + ldsw + _i * 8192), 16, 0, 0); } while (0)
; #define PG8_LDA(dst, b, h) do { _Pragma("unroll") for (int m = 0; m < 4; ++m) _Pragma("unroll") for (int k = 0; k < 2; ++k) dst[m][k] = *(const PG8_LAS bf16x8*)(lds + PG8_SA(b, h) + aoff + m * 2048 + k * 1024); } while (0)
; #define PG8_LDB(dst, b, h) do { _Pragma("unroll") for (int n = 0; n < 2; ++n) _Pragma("unroll") for (int k = 0; k < 2; ++k) dst[n][k] = *(const PG8_LAS bf16x8*)(lds + PG8_SB(b, h) + boff + n * 2048 + k * 1024); } while (0)
; #define PG8_MMA(ai, bj, At, Bt) do { __builtin_amdgcn_s_setprio(1); _Pragma("unroll") for (int m = 0; m < 4; ++m) _Pragma("unroll") for (int n = 0; n < 2; ++n) _Pragma("unroll") for (int k = 0; k < 2; ++k) \
;         acc[ai][bj][m][n] = __builtin_amdgcn_mfma_f32_16x16x32_bf16(Bt[n][k], At[m][k], acc[ai][bj][m][n], 0, 0, 0); __builtin_amdgcn_s_setprio(0); } while (0)
; #define PG8_WAIT_V(n) asm volatile("s_waitcnt vmcnt(" #n ")" ::: "memory")
; #define PG8_WAIT_L(n) asm volatile("s_waitcnt lgkmcnt(" #n ")" ::: "memory")
; #define PG8_BAR __builtin_amdgcn_s_barrier()
; #define PG8_SCHED __builtin_amdgcn_sched_barrier(0)
; template <class Epi, class Sched, bool ALIGN_EPI = false, bool SP2 = false>
; __device__ __forceinline__ void gemm_phase(PG8_LAS unsigned char* lds, const Gemm g, const Sched& S, const Epi& E) {
;     ...
;             PG8_WAIT_V(8); PG8_WAIT_L(0); PG8_BAR; PG8_MMA(1, 0, At, B0); PG8_MMA(1, 1, At, B1); PG8_BAR; PG8_SCHED;
;             PG8_LDB(B0, 1, 0); PG8_LDB(B1, 1, 1); PG8_SCHED; PG8_LDA(At, 1, 0); PG8_STAGE(PG8_SA(0, 1), a2 + hstepA, voffA);
;             PG8_WAIT_V(8); PG8_WAIT_L(0); PG8_BAR; PG8_MMA(0, 0, At, B0); PG8_MMA(0, 1, At, B1); PG8_BAR; PG8_SCHED;
	v_mfma_f32_16x16x32_bf16 v[60:63], v[156:159], v[194:197], v[60:63]
	v_mfma_f32_16x16x32_bf16 v[56:59], v[164:167], v[194:197], v[56:59]
	v_mfma_f32_16x16x32_bf16 v[44:47], v[156:159], v[202:205], v[44:47]
	v_mfma_f32_16x16x32_bf16 v[40:43], v[164:167], v[202:205], v[40:43]
	v_mfma_f32_16x16x32_bf16 v[28:31], v[156:159], v[210:213], v[28:31]
	v_mfma_f32_16x16x32_bf16 v[24:27], v[164:167], v[210:213], v[24:27]
	v_mfma_f32_16x16x32_bf16 v[12:15], v[156:159], v[218:221], v[12:15]
	v_mfma_f32_16x16x32_bf16 v[8:11], v[164:167], v[218:221], v[8:11]
	v_mfma_f32_16x16x32_bf16 v[60:63], v[160:163], v[198:201], v[60:63]
	v_mfma_f32_16x16x32_bf16 v[56:59], v[168:171], v[198:201], v[56:59]
	v_mfma_f32_16x16x32_bf16 v[44:47], v[160:163], v[206:209], v[44:47]
	v_mfma_f32_16x16x32_bf16 v[40:43], v[168:171], v[206:209], v[40:43]
	v_mfma_f32_16x16x32_bf16 v[28:31], v[160:163], v[214:217], v[28:31]
	v_mfma_f32_16x16x32_bf16 v[24:27], v[168:171], v[214:217], v[24:27]
	v_mfma_f32_16x16x32_bf16 v[12:15], v[160:163], v[222:225], v[12:15]
	v_mfma_f32_16x16x32_bf16 v[8:11], v[168:171], v[222:225], v[8:11]
	s_setprio 0
	s_setprio 1
	v_mfma_f32_16x16x32_bf16 v[52:55], v[172:175], v[194:197], v[52:55]
	v_mfma_f32_16x16x32_bf16 v[48:51], v[180:183], v[194:197], v[48:51]
	v_mfma_f32_16x16x32_bf16 v[36:39], v[172:175], v[202:205], v[36:39]
	v_mfma_f32_16x16x32_bf16 v[32:35], v[180:183], v[202:205], v[32:35]
	v_mfma_f32_16x16x32_bf16 v[20:23], v[172:175], v[210:213], v[20:23]
	v_mfma_f32_16x16x32_bf16 v[16:19], v[180:183], v[210:213], v[16:19]
	v_mfma_f32_16x16x32_bf16 v[4:7], v[172:175], v[218:221], v[4:7]
	v_mfma_f32_16x16x32_bf16 v[0:3], v[180:183], v[218:221], v[0:3]
	v_mfma_f32_16x16x32_bf16 v[52:55], v[176:179], v[198:201], v[52:55]
	v_mfma_f32_16x16x32_bf16 v[48:51], v[190:193], v[198:201], v[48:51]
	v_mfma_f32_16x16x32_bf16 v[36:39], v[176:179], v[206:209], v[36:39]
	v_mfma_f32_16x16x32_bf16 v[32:35], v[190:193], v[206:209], v[32:35]
	v_mfma_f32_16x16x32_bf16 v[20:23], v[176:179], v[214:217], v[20:23]
	v_mfma_f32_16x16x32_bf16 v[16:19], v[190:193], v[214:217], v[16:19]
	v_mfma_f32_16x16x32_bf16 v[4:7], v[176:179], v[222:225], v[4:7]
	v_mfma_f32_16x16x32_bf16 v[0:3], v[190:193], v[222:225], v[0:3]
	s_barrier
	s_setprio 0
	s_add_i32 s53, 0, 0x18000
	v_add_u32_e32 v155, s53, v150
	s_add_i32 s54, 0, 0x1c000
	ds_read_b128 v[156:159], v155
	ds_read_b128 v[160:163], v155 offset:1024
	ds_read_b128 v[164:167], v155 offset:2048
	ds_read_b128 v[168:171], v155 offset:3072
	v_add_u32_e32 v155, s54, v150
	ds_read_b128 v[172:175], v155
	ds_read_b128 v[176:179], v155 offset:1024
	ds_read_b128 v[180:183], v155 offset:2048
	ds_read_b128 v[190:193], v155 offset:3072
	s_add_u32 s44, s44, 0x80000
	s_addc_u32 s45, s45, 0
	s_mov_b32 m0, s10
	v_lshl_add_u64 v[234:235], s[44:45], 0, v[128:129]
	ds_read_b128 v[194:197], v154 offset:32768
	ds_read_b128 v[198:201], v154 offset:33792
	ds_read_b128 v[202:205], v154 offset:34816
	ds_read_b128 v[206:209], v154 offset:35840
	ds_read_b128 v[210:213], v154 offset:36864
	ds_read_b128 v[214:217], v154 offset:37888
	ds_read_b128 v[218:221], v154 offset:38912
	ds_read_b128 v[222:225], v154 offset:39936
	global_load_lds_dwordx4 v[234:235], off
	v_lshl_add_u64 v[234:235], s[44:45], 0, v[132:133]
	s_mov_b32 m0, s11
	s_nop 0
	global_load_lds_dwordx4 v[234:235], off
	s_waitcnt vmcnt(8)
	s_waitcnt lgkmcnt(0)
	s_setprio 1
	s_barrier
	v_mfma_f32_16x16x32_bf16 v[124:127], v[156:159], v[194:197], v[124:127]
	v_mfma_f32_16x16x32_bf16 v[120:123], v[164:167], v[194:197], v[120:123]
	v_mfma_f32_16x16x32_bf16 v[108:111], v[156:159], v[202:205], v[108:111]
	v_mfma_f32_16x16x32_bf16 v[104:107], v[164:167], v[202:205], v[104:107]
	v_mfma_f32_16x16x32_bf16 v[92:95], v[156:159], v[210:213], v[92:95]
	v_mfma_f32_16x16x32_bf16 v[88:91], v[164:167], v[210:213], v[88:91]
	v_mfma_f32_16x16x32_bf16 v[76:79], v[156:159], v[218:221], v[76:79]
	v_mfma_f32_16x16x32_bf16 v[72:75], v[164:167], v[218:221], v[72:75]
	v_mfma_f32_16x16x32_bf16 v[124:127], v[160:163], v[198:201], v[124:127]
	v_mfma_f32_16x16x32_bf16 v[120:123], v[168:171], v[198:201], v[120:123]
	v_mfma_f32_16x16x32_bf16 v[108:111], v[160:163], v[206:209], v[108:111]
	v_mfma_f32_16x16x32_bf16 v[104:107], v[168:171], v[206:209], v[104:107]
	v_mfma_f32_16x16x32_bf16 v[92:95], v[160:163], v[214:217], v[92:95]
	v_mfma_f32_16x16x32_bf16 v[88:91], v[168:171], v[214:217], v[88:91]
	v_mfma_f32_16x16x32_bf16 v[76:79], v[160:163], v[222:225], v[76:79]
	v_mfma_f32_16x16x32_bf16 v[72:75], v[168:171], v[222:225], v[72:75]
	s_setprio 0
	s_setprio 1
	v_mfma_f32_16x16x32_bf16 v[116:119], v[172:175], v[194:197], v[116:119]
	v_mfma_f32_16x16x32_bf16 v[112:115], v[180:183], v[194:197], v[112:115]
	v_mfma_f32_16x16x32_bf16 v[100:103], v[172:175], v[202:205], v[100:103]
	v_mfma_f32_16x16x32_bf16 v[96:99], v[180:183], v[202:205], v[96:99]
	v_mfma_f32_16x16x32_bf16 v[84:87], v[172:175], v[210:213], v[84:87]
	v_mfma_f32_16x16x32_bf16 v[80:83], v[180:183], v[210:213], v[80:83]
	v_mfma_f32_16x16x32_bf16 v[68:71], v[172:175], v[218:221], v[68:71]
	v_mfma_f32_16x16x32_bf16 v[64:67], v[180:183], v[218:221], v[64:67]
	v_mfma_f32_16x16x32_bf16 v[116:119], v[176:179], v[198:201], v[116:119]
	v_mfma_f32_16x16x32_bf16 v[112:115], v[190:193], v[198:201], v[112:115]
	v_mfma_f32_16x16x32_bf16 v[100:103], v[176:179], v[206:209], v[100:103]
	v_mfma_f32_16x16x32_bf16 v[96:99], v[190:193], v[206:209], v[96:99]
	v_mfma_f32_16x16x32_bf16 v[84:87], v[176:179], v[214:217], v[84:87]
	v_mfma_f32_16x16x32_bf16 v[80:83], v[190:193], v[214:217], v[80:83]
	v_mfma_f32_16x16x32_bf16 v[68:71], v[176:179], v[222:225], v[68:71]
	v_mfma_f32_16x16x32_bf16 v[64:67], v[190:193], v[222:225], v[64:67]
	s_barrier
; #define PG8_STAGE(bufoff, gbase, voff) do { _Pragma("unroll") for (int _i = 0; _i < 2; ++_i) \
;         __builtin_amdgcn_global_load_lds((const unsigned*)((const char*)(gbase) + (voff)[_i]), (PG8_LAS unsigned*)(lds + (bufoff) + ldsw + _i * 8192), 16, 0, 0); } while (0)
; #define PG8_LDA(dst, b, h) do { _Pragma("unroll") for (int m = 0; m < 4; ++m) _Pragma("unroll") for (int k = 0; k < 2; ++k) dst[m][k] = *(const PG8_LAS bf16x8*)(lds + PG8_SA(b, h) + aoff + m * 2048 + k * 1024); } while (0)
; #define PG8_MMA(ai, bj, At, Bt) do { __builtin_amdgcn_s_setprio(1); _Pragma("unroll") for (int m = 0; m < 4; ++m) _Pragma("unroll") for (int n = 0; n < 2; ++n) _Pragma("unroll") for (int k = 0; k < 2; ++k) \
;         acc[ai][bj][m][n] = __builtin_amdgcn_mfma_f32_16x16x32_bf16(Bt[n][k], At[m][k], acc[ai][bj][m][n], 0, 0, 0); __builtin_amdgcn_s_setprio(0); } while (0)
; #define PG8_WAIT_V(n) asm volatile("s_waitcnt vmcnt(" #n ")" ::: "memory")
; #define PG8_WAIT_L(n) asm volatile("s_waitcnt lgkmcnt(" #n ")" ::: "memory")
; #define PG8_BAR __builtin_amdgcn_s_barrier()
; #define PG8_SCHED __builtin_amdgcn_sched_barrier(0)
; template <class Epi, class Sched, bool ALIGN_EPI = false, bool SP2 = false>
; __device__ __forceinline__ void gemm_phase(PG8_LAS unsigned char* lds, const Gemm g, const Sched& S, const Epi& E) {
;     ...
;             PG8_LDA(At, 1, 1); PG8_STAGE(PG8_SB(1, 0), b3, voffB); PG8_STAGE(PG8_SB(1, 1), b3 + hstepB, voffB); PG8_STAGE(PG8_SA(1, 0), a3, voffA);
;             PG8_WAIT_V(8); PG8_WAIT_L(0); PG8_BAR; PG8_MMA(1, 0, At, B0); PG8_MMA(1, 1, At, B1); PG8_BAR; PG8_SCHED;
;     ...
;         if constexpr (ALIGN_EPI) { if (wr == 0) PG8_BAR; }
	s_setprio 0
	s_add_i32 s44, s53, s7
	v_lshl_add_u64 v[226:227], v[226:227], 0, s[16:17]
	s_mov_b32 m0, s44
	ds_read_b128 v[194:197], v154 offset:49152
	ds_read_b128 v[198:201], v154 offset:50176
	ds_read_b128 v[202:205], v154 offset:51200
	ds_read_b128 v[206:209], v154 offset:52224
	ds_read_b128 v[210:213], v154 offset:53248
	ds_read_b128 v[214:217], v154 offset:54272
	ds_read_b128 v[218:221], v154 offset:55296
	ds_read_b128 v[222:225], v154 offset:56320
	global_load_lds_dwordx4 v[226:227], off
	s_add_i32 m0, s44, 0x2000
	s_add_u32 s42, s42, 0x80080
	v_lshl_add_u64 v[226:227], v[228:229], 0, s[16:17]
	s_addc_u32 s43, s43, 0
	s_add_i32 s44, s54, s7
	global_load_lds_dwordx4 v[226:227], off
	v_lshl_add_u64 v[226:227], s[42:43], 0, v[130:131]
	s_mov_b32 m0, s44
	s_nop 0
	global_load_lds_dwordx4 v[226:227], off
	v_lshl_add_u64 v[226:227], s[42:43], 0, v[134:135]
	s_add_i32 m0, s44, 0x2000
	s_nop 0
	global_load_lds_dwordx4 v[226:227], off
	v_lshl_add_u64 v[226:227], v[230:231], 0, s[16:17]
	s_mov_b32 m0, s48
	s_nop 0
	global_load_lds_dwordx4 v[226:227], off
	v_lshl_add_u64 v[226:227], v[232:233], 0, s[16:17]
	s_mov_b32 m0, s49
	s_nop 0
	global_load_lds_dwordx4 v[226:227], off
	s_waitcnt vmcnt(8)
	s_waitcnt lgkmcnt(0)
	s_setprio 1
	s_barrier
	v_mfma_f32_16x16x32_bf16 v[60:63], v[156:159], v[194:197], v[60:63]
	v_mfma_f32_16x16x32_bf16 v[56:59], v[164:167], v[194:197], v[56:59]
	v_mfma_f32_16x16x32_bf16 v[44:47], v[156:159], v[202:205], v[44:47]
	v_mfma_f32_16x16x32_bf16 v[40:43], v[164:167], v[202:205], v[40:43]
	v_mfma_f32_16x16x32_bf16 v[28:31], v[156:159], v[210:213], v[28:31]
	v_mfma_f32_16x16x32_bf16 v[24:27], v[164:167], v[210:213], v[24:27]
	v_mfma_f32_16x16x32_bf16 v[12:15], v[156:159], v[218:221], v[12:15]
	v_mfma_f32_16x16x32_bf16 v[8:11], v[164:167], v[218:221], v[8:11]
	v_mfma_f32_16x16x32_bf16 v[60:63], v[160:163], v[198:201], v[60:63]
	v_mfma_f32_16x16x32_bf16 v[56:59], v[168:171], v[198:201], v[56:59]
	v_mfma_f32_16x16x32_bf16 v[44:47], v[160:163], v[206:209], v[44:47]
	v_mfma_f32_16x16x32_bf16 v[40:43], v[168:171], v[206:209], v[40:43]
	v_mfma_f32_16x16x32_bf16 v[28:31], v[160:163], v[214:217], v[28:31]
	v_mfma_f32_16x16x32_bf16 v[24:27], v[168:171], v[214:217], v[24:27]
	v_mfma_f32_16x16x32_bf16 v[12:15], v[160:163], v[222:225], v[12:15]
	v_mfma_f32_16x16x32_bf16 v[8:11], v[168:171], v[222:225], v[8:11]
	s_setprio 0
	s_setprio 1
	v_mfma_f32_16x16x32_bf16 v[52:55], v[172:175], v[194:197], v[52:55]
	v_mfma_f32_16x16x32_bf16 v[48:51], v[180:183], v[194:197], v[48:51]
	v_mfma_f32_16x16x32_bf16 v[36:39], v[172:175], v[202:205], v[36:39]
	v_mfma_f32_16x16x32_bf16 v[32:35], v[180:183], v[202:205], v[32:35]
	v_mfma_f32_16x16x32_bf16 v[20:23], v[172:175], v[210:213], v[20:23]
	v_mfma_f32_16x16x32_bf16 v[16:19], v[180:183], v[210:213], v[16:19]
	v_mfma_f32_16x16x32_bf16 v[4:7], v[172:175], v[218:221], v[4:7]
	v_mfma_f32_16x16x32_bf16 v[0:3], v[180:183], v[218:221], v[0:3]
	v_mfma_f32_16x16x32_bf16 v[52:55], v[176:179], v[198:201], v[52:55]
	v_mfma_f32_16x16x32_bf16 v[48:51], v[190:193], v[198:201], v[48:51]
	v_mfma_f32_16x16x32_bf16 v[36:39], v[176:179], v[206:209], v[36:39]
	v_mfma_f32_16x16x32_bf16 v[32:35], v[190:193], v[206:209], v[32:35]
	v_mfma_f32_16x16x32_bf16 v[20:23], v[176:179], v[214:217], v[20:23]
	v_mfma_f32_16x16x32_bf16 v[16:19], v[190:193], v[214:217], v[16:19]
	v_mfma_f32_16x16x32_bf16 v[4:7], v[176:179], v[222:225], v[4:7]
	v_mfma_f32_16x16x32_bf16 v[0:3], v[190:193], v[222:225], v[0:3]
	s_barrier
	s_setprio 0
	s_add_i32 s35, s35, 2
	s_add_u32 s40, s40, 0x100
	s_addc_u32 s41, s41, 0
	s_add_u32 s21, s21, 0x100
	s_addc_u32 s23, s23, 0
	s_cmp_gt_u32 s35, 29
	s_cbranch_scc0 .LBB0_3058
	s_and_b64 vcc, exec, s[18:19]
	s_cbranch_vccz .LBB0_3061
	s_barrier

; #define PG8_STAGE(bufoff, gbase, voff) do { _Pragma("unroll") for (int _i = 0; _i < 2; ++_i) \
;         __builtin_amdgcn_global_load_lds((const unsigned*)((const char*)(gbase) + (voff)[_i]), (PG8_LAS unsigned*)(lds + (bufoff) + ldsw + _i * 8192), 16, 0, 0); } while (0)
; #define PG8_LDA(dst, b, h) do { _Pragma("unroll") for (int m = 0; m < 4; ++m) _Pragma("unroll") for (int k = 0; k < 2; ++k) dst[m][k] = *(const PG8_LAS bf16x8*)(lds + PG8_SA(b, h) + aoff + m * 2048 + k * 1024); } while (0)
; #define PG8_LDB(dst, b, h) do { _Pragma("unroll") for (int n = 0; n < 2; ++n) _Pragma("unroll") for (int k = 0; k < 2; ++k) dst[n][k] = *(const PG8_LAS bf16x8*)(lds + PG8_SB(b, h) + boff + n * 2048 + k * 1024); } while (0)
; #define PG8_MMA(ai, bj, At, Bt) do { __builtin_amdgcn_s_setprio(1); _Pragma("unroll") for (int m = 0; m < 4; ++m) _Pragma("unroll") for (int n = 0; n < 2; ++n) _Pragma("unroll") for (int k = 0; k < 2; ++k) \
;         acc[ai][bj][m][n] = __builtin_amdgcn_mfma_f32_16x16x32_bf16(Bt[n][k], At[m][k], acc[ai][bj][m][n], 0, 0, 0); __builtin_amdgcn_s_setprio(0); } while (0)
; #define PG8_WAIT_V(n) asm volatile("s_waitcnt vmcnt(" #n ")" ::: "memory")
; #define PG8_BAR __builtin_amdgcn_s_barrier()
; template <class Epi, class Sched, bool ALIGN_EPI = false, bool SP2 = false>
; __device__ __forceinline__ void gemm_phase(PG8_LAS unsigned char* lds, const Gemm g, const Sched& S, const Epi& E) {
;     ...
;         for (int t = 0; t < nt; t += 2) {
;             const bool last = (t == nt - 2);
;             const char* a1 = cA + (size_t)(t + 1) * kstA;
;             const char* a2 = last ? nA : cA + (size_t)(t + 2) * kstA; const char* b2 = last ? nB : cB + (size_t)(t + 2) * kstep;
;             const char* a3 = a2 + kstA; const char* b3 = b2 + kstep;
;             if (last && has_next) S.a_ready(nxt);
;             if constexpr (SP2) {
;             PG8_LDB(B0, 0, 0); PG8_LDB(B1, 0, 1); PG8_SCHED; PG8_LDA(At, 0, 0); PG8_STAGE(PG8_SA(1, 1), a1 + hstepA, voffA);
;             PG8_WAIT_V(8); PG8_WAIT_L(0); PG8_BAR; PG8_MMA(0, 0, At, B0); PG8_MMA(0, 1, At, B1); PG8_BAR; PG8_SCHED;
;             PG8_LDA(At, 0, 1); PG8_STAGE(PG8_SB(0, 0), b2, voffB); PG8_STAGE(PG8_SB(0, 1), b2 + hstepB, voffB); PG8_STAGE(PG8_SA(0, 0), a2, voffA);
;             PG8_WAIT_V(8); PG8_WAIT_L(0); PG8_BAR; PG8_MMA(1, 0, At, B0); PG8_MMA(1, 1, At, B1); PG8_BAR; PG8_SCHED;
.LBB0_3147:
	v_add_u32_e32 v176, s64, v178
	ds_read_b128 v[164:167], v176
	ds_read_b128 v[168:171], v176 offset:1024
	ds_read_b128 v[172:175], v176 offset:2048
	ds_read_b128 v[190:193], v176 offset:3072
	v_add_u32_e32 v176, s65, v178
	ds_read_b128 v[194:197], v176
	ds_read_b128 v[198:201], v176 offset:1024
	ds_read_b128 v[202:205], v176 offset:2048
	ds_read_b128 v[206:209], v176 offset:3072
	s_add_u32 s12, s20, s46
	s_addc_u32 s13, s21, s47
	s_cmp_eq_u32 s7, s5
	s_cselect_b32 s52, s42, s12
	s_cselect_b32 s53, s43, s13
	s_cselect_b32 s51, s45, s4
	s_cselect_b32 s50, s44, s1
	s_add_u32 s48, s52, 0x8000
	s_addc_u32 s49, s53, 0
	v_lshl_add_u64 v[176:177], s[20:21], 0, v[162:163]
	s_add_i32 m0, s55, 0xc000
	ds_read_b128 v[210:213], v180
	ds_read_b128 v[214:217], v180 offset:1024
	ds_read_b128 v[218:221], v180 offset:2048
	ds_read_b128 v[222:225], v180 offset:3072
	ds_read_b128 v[226:229], v180 offset:4096
	ds_read_b128 v[230:233], v180 offset:5120
	ds_read_b128 v[234:237], v180 offset:6144
	ds_read_b128 v[238:241], v180 offset:7168
	global_load_lds_dwordx4 v[176:177], off
	v_lshl_add_u64 v[176:177], s[20:21], 0, v[160:161]
	s_add_i32 m0, s55, 0xe000
	s_nop 0
	global_load_lds_dwordx4 v[176:177], off
	s_waitcnt vmcnt(8)
	s_waitcnt lgkmcnt(0)
	s_setprio 1
	s_barrier
	v_mfma_f32_16x16x32_bf16 v[124:127], v[164:167], v[210:213], v[124:127]
	v_mfma_f32_16x16x32_bf16 v[120:123], v[172:175], v[210:213], v[120:123]
	v_mfma_f32_16x16x32_bf16 v[116:119], v[164:167], v[218:221], v[116:119]
	v_mfma_f32_16x16x32_bf16 v[112:115], v[172:175], v[218:221], v[112:115]
	v_mfma_f32_16x16x32_bf16 v[108:111], v[164:167], v[226:229], v[108:111]
	v_mfma_f32_16x16x32_bf16 v[104:107], v[172:175], v[226:229], v[104:107]
	v_mfma_f32_16x16x32_bf16 v[100:103], v[164:167], v[234:237], v[100:103]
	v_mfma_f32_16x16x32_bf16 v[96:99], v[172:175], v[234:237], v[96:99]
	v_mfma_f32_16x16x32_bf16 v[124:127], v[168:171], v[214:217], v[124:127]
	v_mfma_f32_16x16x32_bf16 v[120:123], v[190:193], v[214:217], v[120:123]
	v_mfma_f32_16x16x32_bf16 v[116:119], v[168:171], v[222:225], v[116:119]
	v_mfma_f32_16x16x32_bf16 v[112:115], v[190:193], v[222:225], v[112:115]
	v_mfma_f32_16x16x32_bf16 v[108:111], v[168:171], v[230:233], v[108:111]
	v_mfma_f32_16x16x32_bf16 v[104:107], v[190:193], v[230:233], v[104:107]
	v_mfma_f32_16x16x32_bf16 v[100:103], v[168:171], v[238:241], v[100:103]
	v_mfma_f32_16x16x32_bf16 v[96:99], v[190:193], v[238:241], v[96:99]
	s_setprio 0
	s_setprio 1
	v_mfma_f32_16x16x32_bf16 v[92:95], v[194:197], v[210:213], v[92:95]
	v_mfma_f32_16x16x32_bf16 v[88:91], v[202:205], v[210:213], v[88:91]
	v_mfma_f32_16x16x32_bf16 v[84:87], v[194:197], v[218:221], v[84:87]
	v_mfma_f32_16x16x32_bf16 v[80:83], v[202:205], v[218:221], v[80:83]
	v_mfma_f32_16x16x32_bf16 v[76:79], v[194:197], v[226:229], v[76:79]
	v_mfma_f32_16x16x32_bf16 v[72:75], v[202:205], v[226:229], v[72:75]
	v_mfma_f32_16x16x32_bf16 v[68:71], v[194:197], v[234:237], v[68:71]
	v_mfma_f32_16x16x32_bf16 v[64:67], v[202:205], v[234:237], v[64:67]
	v_mfma_f32_16x16x32_bf16 v[92:95], v[198:201], v[214:217], v[92:95]
	v_mfma_f32_16x16x32_bf16 v[88:91], v[206:209], v[214:217], v[88:91]
	v_mfma_f32_16x16x32_bf16 v[84:87], v[198:201], v[222:225], v[84:87]
	v_mfma_f32_16x16x32_bf16 v[80:83], v[206:209], v[222:225], v[80:83]
	v_mfma_f32_16x16x32_bf16 v[76:79], v[198:201], v[230:233], v[76:79]
	v_mfma_f32_16x16x32_bf16 v[72:75], v[206:209], v[230:233], v[72:75]
	v_mfma_f32_16x16x32_bf16 v[68:71], v[198:201], v[238:241], v[68:71]
	v_mfma_f32_16x16x32_bf16 v[64:67], v[206:209], v[238:241], v[64:67]
	s_barrier
	s_setprio 0
	s_add_i32 s12, s64, s54
	v_lshl_add_u64 v[176:177], s[50:51], 0, v[130:131]
	s_mov_b32 m0, s12
	ds_read_b128 v[210:213], v180 offset:16384
	ds_read_b128 v[214:217], v180 offset:17408
	ds_read_b128 v[218:221], v180 offset:18432
	ds_read_b128 v[222:225], v180 offset:19456
	ds_read_b128 v[226:229], v180 offset:20480
	ds_read_b128 v[230:233], v180 offset:21504
	ds_read_b128 v[234:237], v180 offset:22528
	ds_read_b128 v[238:241], v180 offset:23552
	global_load_lds_dwordx4 v[176:177], off
	s_add_i32 m0, s12, 0x2000
	s_add_u32 s12, s50, 0x160000
	v_lshl_add_u64 v[182:183], s[50:51], 0, v[134:135]
	s_addc_u32 s13, s51, 0
	s_add_i32 s17, s65, s54
	global_load_lds_dwordx4 v[182:183], off
	v_lshl_add_u64 v[242:243], s[12:13], 0, v[130:131]
	s_mov_b32 m0, s17
	s_nop 0
	global_load_lds_dwordx4 v[242:243], off
	v_lshl_add_u64 v[242:243], s[12:13], 0, v[134:135]
	s_add_i32 m0, s17, 0x2000
	s_nop 0
	global_load_lds_dwordx4 v[242:243], off
	v_lshl_add_u64 v[242:243], s[52:53], 0, v[128:129]
	s_mov_b32 m0, s55
	s_nop 0
	global_load_lds_dwordx4 v[242:243], off
	v_lshl_add_u64 v[242:243], s[52:53], 0, v[132:133]
	s_mov_b32 m0, s56
	s_nop 0
	global_load_lds_dwordx4 v[242:243], off
	s_waitcnt vmcnt(8)
	s_waitcnt lgkmcnt(0)
	s_setprio 1
	s_barrier
; #define PG8_STAGE(bufoff, gbase, voff) do { _Pragma("unroll") for (int _i = 0; _i < 2; ++_i) \
;         __builtin_amdgcn_global_load_lds((const unsigned*)((const char*)(gbase) + (voff)[_i]), (PG8_LAS unsigned*)(lds + (bufoff) + ldsw + _i * 8192), 16, 0, 0); } while (0)
; #define PG8_LDA(dst, b, h) do { _Pragma("unroll") for (int m = 0; m < 4; ++m) _Pragma("unroll") for (int k = 0; k < 2; ++k) dst[m][k] = *(const PG8_LAS bf16x8*)(lds + PG8_SA(b, h) + aoff + m * 2048 + k * 1024); } while (0)
; #define PG8_LDB(dst, b, h) do { _Pragma("unroll") for (int n = 0; n < 2; ++n) _Pragma("unroll") for (int k = 0; k < 2; ++k) dst[n][k] = *(const PG8_LAS bf16x8*)(lds + PG8_SB(b, h) + boff + n * 2048 + k * 1024); } while (0)
; #define PG8_MMA(ai, bj, At, Bt) do { __builtin_amdgcn_s_setprio(1); _Pragma("unroll") for (int m = 0; m < 4; ++m) _Pragma("unroll") for (int n = 0; n < 2; ++n) _Pragma("unroll") for (int k = 0; k < 2; ++k) \
;         acc[ai][bj][m][n] = __builtin_amdgcn_mfma_f32_16x16x32_bf16(Bt[n][k], At[m][k], acc[ai][bj][m][n], 0, 0, 0); __builtin_amdgcn_s_setprio(0); } while (0)
; #define PG8_WAIT_V(n) asm volatile("s_waitcnt vmcnt(" #n ")" ::: "memory")
; #define PG8_WAIT_L(n) asm volatile("s_waitcnt lgkmcnt(" #n ")" ::: "memory")
; #define PG8_BAR __builtin_amdgcn_s_barrier()
; #define PG8_SCHED __builtin_amdgcn_sched_barrier(0)
; template <class Epi, class Sched, bool ALIGN_EPI = false, bool SP2 = false>
; __device__ __forceinline__ void gemm_phase(PG8_LAS unsigned char* lds, const Gemm g, const Sched& S, const Epi& E) {
;     ...
;             PG8_WAIT_V(8); PG8_WAIT_L(0); PG8_BAR; PG8_MMA(1, 0, At, B0); PG8_MMA(1, 1, At, B1); PG8_BAR; PG8_SCHED;
;             PG8_LDB(B0, 1, 0); PG8_LDB(B1, 1, 1); PG8_SCHED; PG8_LDA(At, 1, 0); PG8_STAGE(PG8_SA(0, 1), a2 + hstepA, voffA);
;             PG8_WAIT_V(8); PG8_WAIT_L(0); PG8_BAR; PG8_MMA(0, 0, At, B0); PG8_MMA(0, 1, At, B1); PG8_BAR; PG8_SCHED;
	v_mfma_f32_16x16x32_bf16 v[60:63], v[164:167], v[210:213], v[60:63]
	v_mfma_f32_16x16x32_bf16 v[56:59], v[172:175], v[210:213], v[56:59]
	v_mfma_f32_16x16x32_bf16 v[52:55], v[164:167], v[218:221], v[52:55]
	v_mfma_f32_16x16x32_bf16 v[48:51], v[172:175], v[218:221], v[48:51]
	v_mfma_f32_16x16x32_bf16 v[44:47], v[164:167], v[226:229], v[44:47]
	v_mfma_f32_16x16x32_bf16 v[40:43], v[172:175], v[226:229], v[40:43]
	v_mfma_f32_16x16x32_bf16 v[36:39], v[164:167], v[234:237], v[36:39]
	v_mfma_f32_16x16x32_bf16 v[32:35], v[172:175], v[234:237], v[32:35]
	v_mfma_f32_16x16x32_bf16 v[60:63], v[168:171], v[214:217], v[60:63]
	v_mfma_f32_16x16x32_bf16 v[56:59], v[190:193], v[214:217], v[56:59]
	v_mfma_f32_16x16x32_bf16 v[52:55], v[168:171], v[222:225], v[52:55]
	v_mfma_f32_16x16x32_bf16 v[48:51], v[190:193], v[222:225], v[48:51]
	v_mfma_f32_16x16x32_bf16 v[44:47], v[168:171], v[230:233], v[44:47]
	v_mfma_f32_16x16x32_bf16 v[40:43], v[190:193], v[230:233], v[40:43]
	v_mfma_f32_16x16x32_bf16 v[36:39], v[168:171], v[238:241], v[36:39]
	v_mfma_f32_16x16x32_bf16 v[32:35], v[190:193], v[238:241], v[32:35]
	s_setprio 0
	s_setprio 1
	v_mfma_f32_16x16x32_bf16 v[28:31], v[194:197], v[210:213], v[28:31]
	v_mfma_f32_16x16x32_bf16 v[24:27], v[202:205], v[210:213], v[24:27]
	v_mfma_f32_16x16x32_bf16 v[20:23], v[194:197], v[218:221], v[20:23]
	v_mfma_f32_16x16x32_bf16 v[16:19], v[202:205], v[218:221], v[16:19]
	v_mfma_f32_16x16x32_bf16 v[12:15], v[194:197], v[226:229], v[12:15]
	v_mfma_f32_16x16x32_bf16 v[8:11], v[202:205], v[226:229], v[8:11]
	v_mfma_f32_16x16x32_bf16 v[4:7], v[194:197], v[234:237], v[4:7]
	v_mfma_f32_16x16x32_bf16 v[0:3], v[202:205], v[234:237], v[0:3]
	v_mfma_f32_16x16x32_bf16 v[28:31], v[198:201], v[214:217], v[28:31]
	v_mfma_f32_16x16x32_bf16 v[24:27], v[206:209], v[214:217], v[24:27]
	v_mfma_f32_16x16x32_bf16 v[20:23], v[198:201], v[222:225], v[20:23]
	v_mfma_f32_16x16x32_bf16 v[16:19], v[206:209], v[222:225], v[16:19]
	v_mfma_f32_16x16x32_bf16 v[12:15], v[198:201], v[230:233], v[12:15]
	v_mfma_f32_16x16x32_bf16 v[8:11], v[206:209], v[230:233], v[8:11]
	v_mfma_f32_16x16x32_bf16 v[4:7], v[198:201], v[238:241], v[4:7]
	v_mfma_f32_16x16x32_bf16 v[0:3], v[206:209], v[238:241], v[0:3]
	s_barrier
	s_setprio 0
	s_add_i32 s17, 0, 0x18000
	v_add_u32_e32 v181, s17, v178
	s_add_i32 s19, 0, 0x1c000
	ds_read_b128 v[164:167], v181
	ds_read_b128 v[168:171], v181 offset:1024
	ds_read_b128 v[172:175], v181 offset:2048
	ds_read_b128 v[190:193], v181 offset:3072
	v_add_u32_e32 v181, s19, v178
	ds_read_b128 v[194:197], v181
	ds_read_b128 v[198:201], v181 offset:1024
	ds_read_b128 v[202:205], v181 offset:2048
	ds_read_b128 v[206:209], v181 offset:3072
	s_add_u32 s12, s52, 0x4000
	s_addc_u32 s13, s53, 0
	s_mov_b32 m0, s57
	v_lshl_add_u64 v[242:243], s[12:13], 0, v[128:129]
	ds_read_b128 v[210:213], v180 offset:32768
	ds_read_b128 v[214:217], v180 offset:33792
	ds_read_b128 v[218:221], v180 offset:34816
	ds_read_b128 v[222:225], v180 offset:35840
	ds_read_b128 v[226:229], v180 offset:36864
	ds_read_b128 v[230:233], v180 offset:37888
	ds_read_b128 v[234:237], v180 offset:38912
	ds_read_b128 v[238:241], v180 offset:39936
	global_load_lds_dwordx4 v[242:243], off
	v_lshl_add_u64 v[242:243], s[12:13], 0, v[132:133]
	s_mov_b32 m0, s58
	s_nop 0
	global_load_lds_dwordx4 v[242:243], off
	s_waitcnt vmcnt(8)
	s_waitcnt lgkmcnt(0)
	s_setprio 1
	s_barrier
	v_mfma_f32_16x16x32_bf16 v[124:127], v[164:167], v[210:213], v[124:127]
	v_mfma_f32_16x16x32_bf16 v[120:123], v[172:175], v[210:213], v[120:123]
	v_mfma_f32_16x16x32_bf16 v[116:119], v[164:167], v[218:221], v[116:119]
	v_mfma_f32_16x16x32_bf16 v[112:115], v[172:175], v[218:221], v[112:115]
	v_mfma_f32_16x16x32_bf16 v[108:111], v[164:167], v[226:229], v[108:111]
	v_mfma_f32_16x16x32_bf16 v[104:107], v[172:175], v[226:229], v[104:107]
	v_mfma_f32_16x16x32_bf16 v[100:103], v[164:167], v[234:237], v[100:103]
	v_mfma_f32_16x16x32_bf16 v[96:99], v[172:175], v[234:237], v[96:99]
	v_mfma_f32_16x16x32_bf16 v[124:127], v[168:171], v[214:217], v[124:127]
	v_mfma_f32_16x16x32_bf16 v[120:123], v[190:193], v[214:217], v[120:123]
	v_mfma_f32_16x16x32_bf16 v[116:119], v[168:171], v[222:225], v[116:119]
	v_mfma_f32_16x16x32_bf16 v[112:115], v[190:193], v[222:225], v[112:115]
	v_mfma_f32_16x16x32_bf16 v[108:111], v[168:171], v[230:233], v[108:111]
	v_mfma_f32_16x16x32_bf16 v[104:107], v[190:193], v[230:233], v[104:107]
	v_mfma_f32_16x16x32_bf16 v[100:103], v[168:171], v[238:241], v[100:103]
	v_mfma_f32_16x16x32_bf16 v[96:99], v[190:193], v[238:241], v[96:99]
	s_setprio 0
	s_setprio 1
	v_mfma_f32_16x16x32_bf16 v[92:95], v[194:197], v[210:213], v[92:95]
	v_mfma_f32_16x16x32_bf16 v[88:91], v[202:205], v[210:213], v[88:91]
	v_mfma_f32_16x16x32_bf16 v[84:87], v[194:197], v[218:221], v[84:87]
	v_mfma_f32_16x16x32_bf16 v[80:83], v[202:205], v[218:221], v[80:83]
	v_mfma_f32_16x16x32_bf16 v[76:79], v[194:197], v[226:229], v[76:79]
	v_mfma_f32_16x16x32_bf16 v[72:75], v[202:205], v[226:229], v[72:75]
	v_mfma_f32_16x16x32_bf16 v[68:71], v[194:197], v[234:237], v[68:71]
	v_mfma_f32_16x16x32_bf16 v[64:67], v[202:205], v[234:237], v[64:67]
	v_mfma_f32_16x16x32_bf16 v[92:95], v[198:201], v[214:217], v[92:95]
	v_mfma_f32_16x16x32_bf16 v[88:91], v[206:209], v[214:217], v[88:91]
	v_mfma_f32_16x16x32_bf16 v[84:87], v[198:201], v[222:225], v[84:87]
	v_mfma_f32_16x16x32_bf16 v[80:83], v[206:209], v[222:225], v[80:83]
	v_mfma_f32_16x16x32_bf16 v[76:79], v[198:201], v[230:233], v[76:79]
	v_mfma_f32_16x16x32_bf16 v[72:75], v[206:209], v[230:233], v[72:75]
	v_mfma_f32_16x16x32_bf16 v[68:71], v[198:201], v[238:241], v[68:71]
	v_mfma_f32_16x16x32_bf16 v[64:67], v[206:209], v[238:241], v[64:67]
	s_barrier
; #define PG8_STAGE(bufoff, gbase, voff) do { _Pragma("unroll") for (int _i = 0; _i < 2; ++_i) \
;         __builtin_amdgcn_global_load_lds((const unsigned*)((const char*)(gbase) + (voff)[_i]), (PG8_LAS unsigned*)(lds + (bufoff) + ldsw + _i * 8192), 16, 0, 0); } while (0)
; #define PG8_LDA(dst, b, h) do { _Pragma("unroll") for (int m = 0; m < 4; ++m) _Pragma("unroll") for (int k = 0; k < 2; ++k) dst[m][k] = *(const PG8_LAS bf16x8*)(lds + PG8_SA(b, h) + aoff + m * 2048 + k * 1024); } while (0)
; #define PG8_MMA(ai, bj, At, Bt) do { __builtin_amdgcn_s_setprio(1); _Pragma("unroll") for (int m = 0; m < 4; ++m) _Pragma("unroll") for (int n = 0; n < 2; ++n) _Pragma("unroll") for (int k = 0; k < 2; ++k) \
;         acc[ai][bj][m][n] = __builtin_amdgcn_mfma_f32_16x16x32_bf16(Bt[n][k], At[m][k], acc[ai][bj][m][n], 0, 0, 0); __builtin_amdgcn_s_setprio(0); } while (0)
; #define PG8_WAIT_V(n) asm volatile("s_waitcnt vmcnt(" #n ")" ::: "memory")
; #define PG8_WAIT_L(n) asm volatile("s_waitcnt lgkmcnt(" #n ")" ::: "memory")
; #define PG8_BAR __builtin_amdgcn_s_barrier()
; #define PG8_SCHED __builtin_amdgcn_sched_barrier(0)
; template <class Epi, class Sched, bool ALIGN_EPI = false, bool SP2 = false>
; __device__ __forceinline__ void gemm_phase(PG8_LAS unsigned char* lds, const Gemm g, const Sched& S, const Epi& E) {
;     ...
;             PG8_LDA(At, 1, 1); PG8_STAGE(PG8_SB(1, 0), b3, voffB); PG8_STAGE(PG8_SB(1, 1), b3 + hstepB, voffB); PG8_STAGE(PG8_SA(1, 0), a3, voffA);
;             PG8_WAIT_V(8); PG8_WAIT_L(0); PG8_BAR; PG8_MMA(1, 0, At, B0); PG8_MMA(1, 1, At, B1); PG8_BAR; PG8_SCHED;
;     ...
;         if constexpr (ALIGN_EPI) { if (wr == 0) PG8_BAR; }
	s_setprio 0
	s_add_i32 s12, s17, s54
	v_lshl_add_u64 v[176:177], v[176:177], 0, s[30:31]
	s_mov_b32 m0, s12
	ds_read_b128 v[210:213], v180 offset:49152
	ds_read_b128 v[214:217], v180 offset:50176
	ds_read_b128 v[218:221], v180 offset:51200
	ds_read_b128 v[222:225], v180 offset:52224
	ds_read_b128 v[226:229], v180 offset:53248
	ds_read_b128 v[230:233], v180 offset:54272
	ds_read_b128 v[234:237], v180 offset:55296
	ds_read_b128 v[238:241], v180 offset:56320
	global_load_lds_dwordx4 v[176:177], off
	s_add_i32 m0, s12, 0x2000
	s_add_u32 s12, s50, 0x160080
	v_lshl_add_u64 v[176:177], v[182:183], 0, s[30:31]
	s_addc_u32 s13, s51, 0
	s_add_i32 s17, s19, s54
	global_load_lds_dwordx4 v[176:177], off
	v_lshl_add_u64 v[176:177], s[12:13], 0, v[130:131]
	s_mov_b32 m0, s17
	s_nop 0
	global_load_lds_dwordx4 v[176:177], off
	v_lshl_add_u64 v[176:177], s[12:13], 0, v[134:135]
	s_add_i32 m0, s17, 0x2000
	s_nop 0
	global_load_lds_dwordx4 v[176:177], off
	v_lshl_add_u64 v[176:177], s[48:49], 0, v[128:129]
	s_mov_b32 m0, s62
	s_nop 0
	global_load_lds_dwordx4 v[176:177], off
	v_lshl_add_u64 v[176:177], s[48:49], 0, v[132:133]
	s_mov_b32 m0, s63
	s_nop 0
	global_load_lds_dwordx4 v[176:177], off
	s_waitcnt vmcnt(8)
	s_waitcnt lgkmcnt(0)
	s_setprio 1
	s_barrier
	v_mfma_f32_16x16x32_bf16 v[60:63], v[164:167], v[210:213], v[60:63]
	v_mfma_f32_16x16x32_bf16 v[56:59], v[172:175], v[210:213], v[56:59]
	v_mfma_f32_16x16x32_bf16 v[52:55], v[164:167], v[218:221], v[52:55]
	v_mfma_f32_16x16x32_bf16 v[48:51], v[172:175], v[218:221], v[48:51]
	v_mfma_f32_16x16x32_bf16 v[44:47], v[164:167], v[226:229], v[44:47]
	v_mfma_f32_16x16x32_bf16 v[40:43], v[172:175], v[226:229], v[40:43]
	v_mfma_f32_16x16x32_bf16 v[36:39], v[164:167], v[234:237], v[36:39]
	v_mfma_f32_16x16x32_bf16 v[32:35], v[172:175], v[234:237], v[32:35]
	v_mfma_f32_16x16x32_bf16 v[60:63], v[168:171], v[214:217], v[60:63]
	v_mfma_f32_16x16x32_bf16 v[56:59], v[190:193], v[214:217], v[56:59]
	v_mfma_f32_16x16x32_bf16 v[52:55], v[168:171], v[222:225], v[52:55]
	v_mfma_f32_16x16x32_bf16 v[48:51], v[190:193], v[222:225], v[48:51]
	v_mfma_f32_16x16x32_bf16 v[44:47], v[168:171], v[230:233], v[44:47]
	v_mfma_f32_16x16x32_bf16 v[40:43], v[190:193], v[230:233], v[40:43]
	v_mfma_f32_16x16x32_bf16 v[36:39], v[168:171], v[238:241], v[36:39]
	v_mfma_f32_16x16x32_bf16 v[32:35], v[190:193], v[238:241], v[32:35]
	s_setprio 0
	s_setprio 1
	v_mfma_f32_16x16x32_bf16 v[28:31], v[194:197], v[210:213], v[28:31]
	v_mfma_f32_16x16x32_bf16 v[24:27], v[202:205], v[210:213], v[24:27]
	v_mfma_f32_16x16x32_bf16 v[20:23], v[194:197], v[218:221], v[20:23]
	v_mfma_f32_16x16x32_bf16 v[16:19], v[202:205], v[218:221], v[16:19]
	v_mfma_f32_16x16x32_bf16 v[12:15], v[194:197], v[226:229], v[12:15]
	v_mfma_f32_16x16x32_bf16 v[8:11], v[202:205], v[226:229], v[8:11]
	v_mfma_f32_16x16x32_bf16 v[4:7], v[194:197], v[234:237], v[4:7]
	v_mfma_f32_16x16x32_bf16 v[0:3], v[202:205], v[234:237], v[0:3]
	v_mfma_f32_16x16x32_bf16 v[28:31], v[198:201], v[214:217], v[28:31]
	v_mfma_f32_16x16x32_bf16 v[24:27], v[206:209], v[214:217], v[24:27]
	v_mfma_f32_16x16x32_bf16 v[20:23], v[198:201], v[222:225], v[20:23]
	v_mfma_f32_16x16x32_bf16 v[16:19], v[206:209], v[222:225], v[16:19]
	v_mfma_f32_16x16x32_bf16 v[12:15], v[198:201], v[230:233], v[12:15]
	v_mfma_f32_16x16x32_bf16 v[8:11], v[206:209], v[230:233], v[8:11]
	v_mfma_f32_16x16x32_bf16 v[4:7], v[198:201], v[238:241], v[4:7]
	v_mfma_f32_16x16x32_bf16 v[0:3], v[206:209], v[238:241], v[0:3]
	s_barrier
	s_setprio 0
	s_add_i32 s12, s5, 2
	s_add_u32 s46, s46, 0x10000
	s_addc_u32 s47, s47, 0
	s_add_u32 s1, s1, 0x100
	s_addc_u32 s4, s4, 0
	v_lshl_add_u64 v[162:163], v[162:163], 0, s[38:39]
	v_lshl_add_u64 v[160:161], v[160:161], 0, s[38:39]
	s_cmp_ge_i32 s5, s7
	s_mov_b32 s5, s12
	s_cbranch_scc0 .LBB0_3147
	s_and_b64 vcc, exec, s[36:37]
	s_cbranch_vccz .LBB0_3150
	s_barrier
